# UP phases: cross-tile prefetch of next tile prologue loads from inside the epilogue
# speedup vs baseline: 1.0227x; 1.0193x over previous
.LBB0_336:
	s_cmpk_gt_u32 s2, 0x1fff
	v_readfirstlane_b32 s8, v2
	s_cbranch_scc1 .LBB0_339
	v_lshrrev_b32_e32 v3, 3, v2
	v_lshlrev_b32_e32 v5, 3, v2
	v_lshlrev_b32_e32 v4, 4, v2
	v_mov_b32_e32 v67, 0
	v_lshlrev_b32_e32 v66, 11, v3
	v_readlane_b32 s14, v252, 2
	s_add_u32 s6, s82, 0xae60000
	v_and_b32_e32 v4, 0x70, v4
	v_and_b32_e32 v6, 0x78, v5
	v_lshl_add_u64 v[8:9], s[92:93], 0, v[66:67]
	v_mov_b32_e32 v5, v67
	v_readlane_b32 s15, v252, 3
	s_load_dword s10, s[0:1], 0x1b8
	s_addc_u32 s7, s83, 0
	v_lshl_add_u64 v[68:69], v[8:9], 0, v[4:5]
	v_lshl_add_u64 v[8:9], s[14:15], 0, v[66:67]
	s_bfe_u32 s14, s8, 0x10006
	s_lshr_b32 s8, s8, 1
	v_mul_u32_u24_e32 v1, 0x48, v3
	v_lshrrev_b32_e32 v93, 4, v2
	v_bfe_u32 v3, v2, 5, 1
	v_and_b32_e32 v2, 31, v2
	s_and_b32 s15, s8, 0x7fffffc0
	v_lshl_add_u32 v1, v1, 1, v4
	v_lshl_add_u64 v[70:71], v[8:9], 0, v[4:5]
	v_lshlrev_b32_e32 v4, 4, v3
	v_or_b32_e32 v5, s15, v2
	s_movk_i32 s16, 0x90
	s_movk_i32 s11, 0x204
	v_mad_u64_u32 v[72:73], s[8:9], v5, s16, v[4:5]
	v_lshl_or_b32 v3, v3, 2, s15
	v_lshlrev_b32_e32 v7, 2, v6
	v_mul_u32_u24_e32 v10, 0x204, v93
	v_lshl_or_b32 v5, s14, 6, v2
	v_mul_lo_u32 v3, v3, s11
	s_lshl_b32 s8, s14, 8
	v_lshlrev_b32_e32 v2, 2, v2
	s_waitcnt lgkmcnt(0)
	s_lshr_b32 s12, s10, 3
	s_lshr_b32 s13, s2, 3
	v_add3_u32 v101, s8, v3, v2
	v_add_u32_e32 v103, v7, v10
	s_and_b32 s3, s2, 7
	v_add_u32_e32 v92, 0x9000, v1
	v_add_u32_e32 v94, 16, v93
	v_add_u32_e32 v95, 32, v93
	v_add_u32_e32 v96, 48, v93
	v_or_b32_e32 v97, 64, v93
	v_add_u32_e32 v98, 0x50, v93
	v_add_u32_e32 v99, 0x60, v93
	v_add_u32_e32 v100, 0x70, v93
	v_mad_u32_u24 v73, v5, s16, v4
	s_lshl_b32 s14, s13, 4
	s_lshl_b32 s15, s12, 4
	s_and_b32 s16, s2, -8
	s_and_b32 s17, s10, -8
	s_mov_b32 s9, 0
	s_mov_b32 s18, 0x10000
	s_mov_b32 s19, 0x20000
	s_mov_b32 s20, 0x30000
	v_mov_b32_e32 v102, 0x358637bd
	s_mov_b32 s21, 0x800000
	v_lshlrev_b32_e32 v74, 1, v6
	v_mov_b32_e32 v75, v67
	s_movk_i32 s22, 0x7fff
	v_add_u32_e32 v104, 0x2040, v103
	v_add_u32_e32 v105, 0x2048, v103
	v_add_u32_e32 v106, 0x2050, v103
	v_add_u32_e32 v107, 0x2058, v103
	v_add_u32_e32 v108, 0x4080, v103
	v_add_u32_e32 v109, 0x4088, v103
	v_add_u32_e32 v110, 0x4090, v103
	v_add_u32_e32 v111, 0x4098, v103
	v_add_u32_e32 v112, 0x60c0, v103
	v_add_u32_e32 v113, 0x60c8, v103
	v_add_u32_e32 v114, 0x60d0, v103
	v_add_u32_e32 v115, 0x60d8, v103
	v_add_u32_e32 v116, 0x8100, v103
	v_add_u32_e32 v117, 0x8108, v103
	v_add_u32_e32 v118, 0x8110, v103
	v_add_u32_e32 v119, 0x8118, v103
	v_add_u32_e32 v120, 0xa140, v103
	v_add_u32_e32 v121, 0xa148, v103
	v_add_u32_e32 v122, 0xa150, v103
	v_add_u32_e32 v123, 0xa158, v103
	v_add_u32_e32 v124, 0xc180, v103
	v_add_u32_e32 v125, 0xc188, v103
	v_add_u32_e32 v126, 0xc190, v103
	v_add_u32_e32 v127, 0xc198, v103
	v_add_u32_e32 v128, 0xe1c0, v103
	v_add_u32_e32 v129, 0xe1c8, v103
	v_add_u32_e32 v130, 0xe1d0, v103
	v_add_u32_e32 v131, 0xe1d8, v103
	v_add_u32_e32 v132, 0x4000, v101
	v_add_u32_e32 v133, 0x400, v101
	v_add_u32_e32 v134, 0x4400, v101
	v_add_u32_e32 v135, 0x1000, v101
	v_add_u32_e32 v136, 0x5000, v101
	v_add_u32_e32 v137, 0x1400, v101
	v_add_u32_e32 v138, 0x5400, v101
	v_add_u32_e32 v139, 0x2000, v101
	v_add_u32_e32 v140, 0x6000, v101
	v_add_u32_e32 v141, 0x2400, v101
	v_add_u32_e32 v142, 0x6400, v101
	v_add_u32_e32 v143, 0x3000, v101
	v_add_u32_e32 v144, 0x7000, v101
	v_add_u32_e32 v145, 0x3400, v101
	v_add_u32_e32 v146, 0x7400, v101
	v_mov_b32_e32 v147, 1
	s_lshr_b32 s8, s13, 2
	s_and_b32 s10, s16, 56
	s_and_b32 s8, s8, 0x1ffffc0
	s_or_b32 s10, s10, s3
	s_or_b32 s8, s10, s8
	s_lshl_b32 s8, s8, 7
	s_lshl_b64 s[24:25], s[8:9], 11
	v_lshl_add_u64 v[78:79], v[68:69], 0, s[24:25]
	v_add_co_u32_e32 v80, vcc, s18, v78
	s_and_b32 s10, s14, 0xf80
	s_nop 0
	v_addc_co_u32_e32 v81, vcc, 0, v79, vcc
	s_lshl_b32 s26, s10, 11
	s_mov_b32 s27, s9
	v_add_co_u32_e32 v82, vcc, s19, v78
	v_lshl_add_u64 v[76:77], v[70:71], 0, s[26:27]
	s_nop 0
	v_addc_co_u32_e32 v83, vcc, 0, v79, vcc
	v_add_co_u32_e32 v84, vcc, s18, v76
	global_load_dwordx4 v[2:5], v[78:79], off
	global_load_dwordx4 v[6:9], v[80:81], off
	v_addc_co_u32_e32 v85, vcc, 0, v77, vcc
	v_add_co_u32_e32 v86, vcc, s19, v76
	global_load_dwordx4 v[10:13], v[82:83], off
	global_load_dwordx4 v[14:17], v[76:77], off
	v_addc_co_u32_e32 v87, vcc, 0, v77, vcc
	global_load_dwordx4 v[18:21], v[84:85], off
	global_load_dwordx4 v[22:25], v[86:87], off
	v_add_co_u32_e32 v88, vcc, s20, v76
	s_nop 1
	v_addc_co_u32_e32 v89, vcc, 0, v77, vcc
	global_load_dwordx4 v[26:29], v[88:89], off
	v_add_co_u32_e32 v90, vcc, s20, v78
	s_nop 1
	v_addc_co_u32_e32 v91, vcc, 0, v79, vcc
	global_load_dwordx4 v[30:33], v[90:91], off
	global_load_dwordx4 v[148:151], v[76:77], off offset:128
	global_load_dwordx4 v[152:155], v[84:85], off offset:128
	global_load_dwordx4 v[156:159], v[86:87], off offset:128
	global_load_dwordx4 v[160:163], v[88:89], off offset:128
	global_load_dwordx4 v[164:167], v[78:79], off offset:128
	global_load_dwordx4 v[168:171], v[80:81], off offset:128
	global_load_dwordx4 v[172:175], v[82:83], off offset:128
	global_load_dwordx4 v[176:179], v[90:91], off offset:128
.LBB0_338:
	s_waitcnt vmcnt(12)
	ds_write_b128 v1, v[14:17] offset:36864
	s_waitcnt vmcnt(11)
	ds_write_b128 v1, v[18:21] offset:41472
	s_waitcnt vmcnt(10)
	ds_write_b128 v1, v[22:25] offset:46080
	s_waitcnt vmcnt(9)
	ds_write_b128 v1, v[26:29] offset:50688
	ds_write_b128 v1, v[2:5]
	ds_write_b128 v1, v[6:9] offset:4608
	ds_write_b128 v1, v[10:13] offset:9216
	s_waitcnt vmcnt(8)
	ds_write_b128 v1, v[30:33] offset:13824
	s_waitcnt lgkmcnt(0)
	s_barrier
	global_load_dwordx4 v[180:183], v[80:81], off offset:256
	global_load_dwordx4 v[184:187], v[82:83], off offset:256
	global_load_dwordx4 v[188:191], v[78:79], off offset:256
	global_load_dwordx4 v[192:195], v[76:77], off offset:256
	global_load_dwordx4 v[196:199], v[90:91], off offset:256
	global_load_dwordx4 v[200:203], v[84:85], off offset:256
	global_load_dwordx4 v[204:207], v[86:87], off offset:256
	global_load_dwordx4 v[208:211], v[88:89], off offset:256
	ds_read_b128 v[18:21], v72
	ds_read_b128 v[34:37], v73 offset:36864
	ds_read_b128 v[212:215], v72 offset:32
	ds_read_b128 v[216:219], v73 offset:36896
	ds_read_b128 v[50:53], v73 offset:41472
	ds_read_b128 v[220:223], v73 offset:41504
	ds_read_b128 v[54:57], v72 offset:4608
	ds_read_b128 v[224:227], v72 offset:4640
	s_waitcnt lgkmcnt(6)
	v_mfma_f32_32x32x16_bf16 v[2:17], v[18:21], v[34:37], 0
	s_waitcnt lgkmcnt(3)
	v_mfma_f32_32x32x16_bf16 v[18:33], v[18:21], v[50:53], 0
	s_waitcnt lgkmcnt(1)
	v_mfma_f32_32x32x16_bf16 v[34:49], v[54:57], v[34:37], 0
	v_mfma_f32_32x32x16_bf16 v[50:65], v[54:57], v[50:53], 0
	v_mfma_f32_32x32x16_bf16 v[2:17], v[212:215], v[216:219], v[2:17]
	v_mfma_f32_32x32x16_bf16 v[18:33], v[212:215], v[220:223], v[18:33]
	s_waitcnt lgkmcnt(0)
	v_mfma_f32_32x32x16_bf16 v[34:49], v[224:227], v[216:219], v[34:49]
	v_mfma_f32_32x32x16_bf16 v[50:65], v[224:227], v[220:223], v[50:65]
	ds_read_b128 v[212:215], v72 offset:64
	ds_read_b128 v[216:219], v73 offset:36928
	ds_read_b128 v[220:223], v72 offset:96
	ds_read_b128 v[224:227], v73 offset:36960
	ds_read_b128 v[228:231], v73 offset:41536
	ds_read_b128 v[232:235], v73 offset:41568
	s_waitcnt lgkmcnt(4)
	v_mfma_f32_32x32x16_bf16 v[2:17], v[212:215], v[216:219], v[2:17]
	s_waitcnt lgkmcnt(1)
	v_mfma_f32_32x32x16_bf16 v[18:33], v[212:215], v[228:231], v[18:33]
	ds_read_b128 v[212:215], v72 offset:4672
	ds_read_b128 v[236:239], v72 offset:4704
	s_waitcnt vmcnt(11)
	ds_write_b128 v1, v[164:167] offset:18432
	s_waitcnt vmcnt(10)
	ds_write_b128 v1, v[168:171] offset:23040
	s_waitcnt vmcnt(9)
	ds_write_b128 v1, v[172:175] offset:27648
	s_waitcnt vmcnt(8)
	ds_write_b128 v1, v[176:179] offset:32256
	ds_write_b128 v1, v[148:151] offset:55296
	ds_write_b128 v1, v[152:155] offset:59904
	ds_write_b128 v1, v[156:159] offset:64512
	ds_write_b128 v92, v[160:163] offset:32256
	global_load_dwordx4 v[148:151], v[80:81], off offset:384
	global_load_dwordx4 v[152:155], v[82:83], off offset:384
	global_load_dwordx4 v[156:159], v[78:79], off offset:384
	global_load_dwordx4 v[160:163], v[76:77], off offset:384
	global_load_dwordx4 v[164:167], v[90:91], off offset:384
	global_load_dwordx4 v[168:171], v[84:85], off offset:384
	global_load_dwordx4 v[172:175], v[86:87], off offset:384
	global_load_dwordx4 v[176:179], v[88:89], off offset:384
	s_waitcnt lgkmcnt(0)
	s_barrier
	v_mfma_f32_32x32x16_bf16 v[34:49], v[212:215], v[216:219], v[34:49]
	v_mfma_f32_32x32x16_bf16 v[50:65], v[212:215], v[228:231], v[50:65]
	v_mfma_f32_32x32x16_bf16 v[2:17], v[220:223], v[224:227], v[2:17]
	v_mfma_f32_32x32x16_bf16 v[18:33], v[220:223], v[232:235], v[18:33]
	v_mfma_f32_32x32x16_bf16 v[34:49], v[236:239], v[224:227], v[34:49]
	v_mfma_f32_32x32x16_bf16 v[50:65], v[236:239], v[232:235], v[50:65]
	ds_read_b128 v[212:215], v72 offset:18432
	ds_read_b128 v[216:219], v73 offset:55296
	ds_read_b128 v[220:223], v72 offset:18464
	ds_read_b128 v[224:227], v73 offset:55328
	ds_read_b128 v[228:231], v73 offset:59904
	ds_read_b128 v[232:235], v73 offset:59936
	s_waitcnt lgkmcnt(4)
	v_mfma_f32_32x32x16_bf16 v[2:17], v[212:215], v[216:219], v[2:17]
	s_waitcnt lgkmcnt(1)
	v_mfma_f32_32x32x16_bf16 v[18:33], v[212:215], v[228:231], v[18:33]
	ds_read_b128 v[212:215], v72 offset:23040
	ds_read_b128 v[236:239], v72 offset:23072
	s_waitcnt lgkmcnt(1)
	v_mfma_f32_32x32x16_bf16 v[34:49], v[212:215], v[216:219], v[34:49]
	v_mfma_f32_32x32x16_bf16 v[50:65], v[212:215], v[228:231], v[50:65]
	v_mfma_f32_32x32x16_bf16 v[2:17], v[220:223], v[224:227], v[2:17]
	v_mfma_f32_32x32x16_bf16 v[18:33], v[220:223], v[232:235], v[18:33]
	s_waitcnt lgkmcnt(0)
	v_mfma_f32_32x32x16_bf16 v[34:49], v[236:239], v[224:227], v[34:49]
	ds_read_b128 v[212:215], v72 offset:18496
	ds_read_b128 v[216:219], v73 offset:55360
	ds_read_b128 v[220:223], v72 offset:18528
	ds_read_b128 v[224:227], v73 offset:55392
	v_mfma_f32_32x32x16_bf16 v[50:65], v[236:239], v[232:235], v[50:65]
	ds_read_b128 v[228:231], v73 offset:59968
	ds_read_b128 v[232:235], v73 offset:60000
	s_waitcnt lgkmcnt(4)
	v_mfma_f32_32x32x16_bf16 v[2:17], v[212:215], v[216:219], v[2:17]
	s_waitcnt lgkmcnt(1)
	v_mfma_f32_32x32x16_bf16 v[18:33], v[212:215], v[228:231], v[18:33]
	ds_read_b128 v[212:215], v72 offset:23104
	ds_read_b128 v[236:239], v72 offset:23136
	s_waitcnt vmcnt(13)
	ds_write_b128 v1, v[188:191]
	ds_write_b128 v1, v[180:183] offset:4608
	ds_write_b128 v1, v[184:187] offset:9216
	s_waitcnt vmcnt(11)
	ds_write_b128 v1, v[196:199] offset:13824
	ds_write_b128 v1, v[192:195] offset:36864
	s_waitcnt vmcnt(10)
	ds_write_b128 v1, v[200:203] offset:41472
	s_waitcnt vmcnt(9)
	ds_write_b128 v1, v[204:207] offset:46080
	s_waitcnt vmcnt(8)
	ds_write_b128 v1, v[208:211] offset:50688
	global_load_dwordx4 v[180:183], v[80:81], off offset:512
	global_load_dwordx4 v[184:187], v[82:83], off offset:512
	global_load_dwordx4 v[188:191], v[78:79], off offset:512
	global_load_dwordx4 v[192:195], v[76:77], off offset:512
	global_load_dwordx4 v[196:199], v[90:91], off offset:512
	global_load_dwordx4 v[200:203], v[84:85], off offset:512
	global_load_dwordx4 v[204:207], v[86:87], off offset:512
	global_load_dwordx4 v[208:211], v[88:89], off offset:512
	s_waitcnt lgkmcnt(0)
	s_barrier
	v_mfma_f32_32x32x16_bf16 v[34:49], v[212:215], v[216:219], v[34:49]
	v_mfma_f32_32x32x16_bf16 v[50:65], v[212:215], v[228:231], v[50:65]
	v_mfma_f32_32x32x16_bf16 v[2:17], v[220:223], v[224:227], v[2:17]
	v_mfma_f32_32x32x16_bf16 v[18:33], v[220:223], v[232:235], v[18:33]
	v_mfma_f32_32x32x16_bf16 v[34:49], v[236:239], v[224:227], v[34:49]
	v_mfma_f32_32x32x16_bf16 v[50:65], v[236:239], v[232:235], v[50:65]
	ds_read_b128 v[212:215], v72
	ds_read_b128 v[216:219], v73 offset:36864
	ds_read_b128 v[220:223], v72 offset:32
	ds_read_b128 v[224:227], v73 offset:36896
	ds_read_b128 v[228:231], v73 offset:41472
	ds_read_b128 v[232:235], v73 offset:41504
	s_waitcnt lgkmcnt(4)
	v_mfma_f32_32x32x16_bf16 v[2:17], v[212:215], v[216:219], v[2:17]
	s_waitcnt lgkmcnt(1)
	v_mfma_f32_32x32x16_bf16 v[18:33], v[212:215], v[228:231], v[18:33]
	ds_read_b128 v[212:215], v72 offset:4608
	ds_read_b128 v[236:239], v72 offset:4640
	s_waitcnt lgkmcnt(1)
	v_mfma_f32_32x32x16_bf16 v[34:49], v[212:215], v[216:219], v[34:49]
	v_mfma_f32_32x32x16_bf16 v[50:65], v[212:215], v[228:231], v[50:65]
	v_mfma_f32_32x32x16_bf16 v[2:17], v[220:223], v[224:227], v[2:17]
	v_mfma_f32_32x32x16_bf16 v[18:33], v[220:223], v[232:235], v[18:33]
	s_waitcnt lgkmcnt(0)
	v_mfma_f32_32x32x16_bf16 v[34:49], v[236:239], v[224:227], v[34:49]
	ds_read_b128 v[212:215], v72 offset:64
	ds_read_b128 v[216:219], v73 offset:36928
	ds_read_b128 v[220:223], v72 offset:96
	ds_read_b128 v[224:227], v73 offset:36960
	v_mfma_f32_32x32x16_bf16 v[50:65], v[236:239], v[232:235], v[50:65]
	ds_read_b128 v[228:231], v73 offset:41536
	ds_read_b128 v[232:235], v73 offset:41568
	s_waitcnt lgkmcnt(4)
	v_mfma_f32_32x32x16_bf16 v[2:17], v[212:215], v[216:219], v[2:17]
	s_waitcnt lgkmcnt(1)
	v_mfma_f32_32x32x16_bf16 v[18:33], v[212:215], v[228:231], v[18:33]
	ds_read_b128 v[212:215], v72 offset:4672
	ds_read_b128 v[236:239], v72 offset:4704
	s_waitcnt vmcnt(13)
	ds_write_b128 v1, v[156:159] offset:18432
	ds_write_b128 v1, v[148:151] offset:23040
	ds_write_b128 v1, v[152:155] offset:27648
	s_waitcnt vmcnt(11)
	ds_write_b128 v1, v[164:167] offset:32256
	ds_write_b128 v1, v[160:163] offset:55296
	s_waitcnt vmcnt(10)
	ds_write_b128 v1, v[168:171] offset:59904
	s_waitcnt vmcnt(9)
	ds_write_b128 v1, v[172:175] offset:64512
	s_waitcnt vmcnt(8)
	ds_write_b128 v92, v[176:179] offset:32256
	global_load_dwordx4 v[148:151], v[80:81], off offset:640
	global_load_dwordx4 v[152:155], v[82:83], off offset:640
	global_load_dwordx4 v[156:159], v[78:79], off offset:640
	global_load_dwordx4 v[160:163], v[76:77], off offset:640
	global_load_dwordx4 v[164:167], v[90:91], off offset:640
	global_load_dwordx4 v[168:171], v[84:85], off offset:640
	global_load_dwordx4 v[172:175], v[86:87], off offset:640
	global_load_dwordx4 v[176:179], v[88:89], off offset:640
	s_waitcnt lgkmcnt(0)
	s_barrier
	v_mfma_f32_32x32x16_bf16 v[34:49], v[212:215], v[216:219], v[34:49]
	v_mfma_f32_32x32x16_bf16 v[50:65], v[212:215], v[228:231], v[50:65]
	v_mfma_f32_32x32x16_bf16 v[2:17], v[220:223], v[224:227], v[2:17]
	v_mfma_f32_32x32x16_bf16 v[18:33], v[220:223], v[232:235], v[18:33]
	v_mfma_f32_32x32x16_bf16 v[34:49], v[236:239], v[224:227], v[34:49]
	v_mfma_f32_32x32x16_bf16 v[50:65], v[236:239], v[232:235], v[50:65]
	ds_read_b128 v[212:215], v72 offset:18432
	ds_read_b128 v[216:219], v73 offset:55296
	ds_read_b128 v[220:223], v72 offset:18464
	ds_read_b128 v[224:227], v73 offset:55328
	ds_read_b128 v[228:231], v73 offset:59904
	ds_read_b128 v[232:235], v73 offset:59936
	s_waitcnt lgkmcnt(4)
	v_mfma_f32_32x32x16_bf16 v[2:17], v[212:215], v[216:219], v[2:17]
	s_waitcnt lgkmcnt(1)
	v_mfma_f32_32x32x16_bf16 v[18:33], v[212:215], v[228:231], v[18:33]
	ds_read_b128 v[212:215], v72 offset:23040
	ds_read_b128 v[236:239], v72 offset:23072
	s_waitcnt lgkmcnt(1)
	v_mfma_f32_32x32x16_bf16 v[34:49], v[212:215], v[216:219], v[34:49]
	v_mfma_f32_32x32x16_bf16 v[50:65], v[212:215], v[228:231], v[50:65]
	v_mfma_f32_32x32x16_bf16 v[2:17], v[220:223], v[224:227], v[2:17]
	v_mfma_f32_32x32x16_bf16 v[18:33], v[220:223], v[232:235], v[18:33]
	s_waitcnt lgkmcnt(0)
	v_mfma_f32_32x32x16_bf16 v[34:49], v[236:239], v[224:227], v[34:49]
	ds_read_b128 v[212:215], v72 offset:18496
	ds_read_b128 v[216:219], v73 offset:55360
	ds_read_b128 v[220:223], v72 offset:18528
	ds_read_b128 v[224:227], v73 offset:55392
	v_mfma_f32_32x32x16_bf16 v[50:65], v[236:239], v[232:235], v[50:65]
	ds_read_b128 v[228:231], v73 offset:59968
	ds_read_b128 v[232:235], v73 offset:60000
	s_waitcnt lgkmcnt(4)
	v_mfma_f32_32x32x16_bf16 v[2:17], v[212:215], v[216:219], v[2:17]
	s_waitcnt lgkmcnt(1)
	v_mfma_f32_32x32x16_bf16 v[18:33], v[212:215], v[228:231], v[18:33]
	ds_read_b128 v[212:215], v72 offset:23104
	ds_read_b128 v[236:239], v72 offset:23136
	s_waitcnt vmcnt(13)
	ds_write_b128 v1, v[188:191]
	ds_write_b128 v1, v[180:183] offset:4608
	ds_write_b128 v1, v[184:187] offset:9216
	s_waitcnt vmcnt(11)
	ds_write_b128 v1, v[196:199] offset:13824
	ds_write_b128 v1, v[192:195] offset:36864
	s_waitcnt vmcnt(10)
	ds_write_b128 v1, v[200:203] offset:41472
	s_waitcnt vmcnt(9)
	ds_write_b128 v1, v[204:207] offset:46080
	s_waitcnt vmcnt(8)
	ds_write_b128 v1, v[208:211] offset:50688
	global_load_dwordx4 v[180:183], v[80:81], off offset:768
	global_load_dwordx4 v[184:187], v[82:83], off offset:768
	global_load_dwordx4 v[188:191], v[78:79], off offset:768
	global_load_dwordx4 v[192:195], v[76:77], off offset:768
	global_load_dwordx4 v[196:199], v[90:91], off offset:768
	global_load_dwordx4 v[200:203], v[84:85], off offset:768
	global_load_dwordx4 v[204:207], v[86:87], off offset:768
	global_load_dwordx4 v[208:211], v[88:89], off offset:768
	s_waitcnt lgkmcnt(0)
	s_barrier
	v_mfma_f32_32x32x16_bf16 v[34:49], v[212:215], v[216:219], v[34:49]
	v_mfma_f32_32x32x16_bf16 v[50:65], v[212:215], v[228:231], v[50:65]
	v_mfma_f32_32x32x16_bf16 v[2:17], v[220:223], v[224:227], v[2:17]
	v_mfma_f32_32x32x16_bf16 v[18:33], v[220:223], v[232:235], v[18:33]
	v_mfma_f32_32x32x16_bf16 v[34:49], v[236:239], v[224:227], v[34:49]
	v_mfma_f32_32x32x16_bf16 v[50:65], v[236:239], v[232:235], v[50:65]
	ds_read_b128 v[212:215], v72
	ds_read_b128 v[216:219], v73 offset:36864
	ds_read_b128 v[220:223], v72 offset:32
	ds_read_b128 v[224:227], v73 offset:36896
	ds_read_b128 v[228:231], v73 offset:41472
	ds_read_b128 v[232:235], v73 offset:41504
	s_waitcnt lgkmcnt(4)
	v_mfma_f32_32x32x16_bf16 v[2:17], v[212:215], v[216:219], v[2:17]
	s_waitcnt lgkmcnt(1)
	v_mfma_f32_32x32x16_bf16 v[18:33], v[212:215], v[228:231], v[18:33]
	ds_read_b128 v[212:215], v72 offset:4608
	ds_read_b128 v[236:239], v72 offset:4640
	s_waitcnt lgkmcnt(1)
	v_mfma_f32_32x32x16_bf16 v[34:49], v[212:215], v[216:219], v[34:49]
	v_mfma_f32_32x32x16_bf16 v[50:65], v[212:215], v[228:231], v[50:65]
	v_mfma_f32_32x32x16_bf16 v[2:17], v[220:223], v[224:227], v[2:17]
	v_mfma_f32_32x32x16_bf16 v[18:33], v[220:223], v[232:235], v[18:33]
	s_waitcnt lgkmcnt(0)
	v_mfma_f32_32x32x16_bf16 v[34:49], v[236:239], v[224:227], v[34:49]
	ds_read_b128 v[212:215], v72 offset:64
	ds_read_b128 v[216:219], v73 offset:36928
	ds_read_b128 v[220:223], v72 offset:96
	ds_read_b128 v[224:227], v73 offset:36960
	v_mfma_f32_32x32x16_bf16 v[50:65], v[236:239], v[232:235], v[50:65]
	ds_read_b128 v[228:231], v73 offset:41536
	ds_read_b128 v[232:235], v73 offset:41568
	s_waitcnt lgkmcnt(4)
	v_mfma_f32_32x32x16_bf16 v[2:17], v[212:215], v[216:219], v[2:17]
	s_waitcnt lgkmcnt(1)
	v_mfma_f32_32x32x16_bf16 v[18:33], v[212:215], v[228:231], v[18:33]
	ds_read_b128 v[212:215], v72 offset:4672
	ds_read_b128 v[236:239], v72 offset:4704
	s_waitcnt vmcnt(13)
	ds_write_b128 v1, v[156:159] offset:18432
	ds_write_b128 v1, v[148:151] offset:23040
	ds_write_b128 v1, v[152:155] offset:27648
	s_waitcnt vmcnt(11)
	ds_write_b128 v1, v[164:167] offset:32256
	ds_write_b128 v1, v[160:163] offset:55296
	s_waitcnt vmcnt(10)
	ds_write_b128 v1, v[168:171] offset:59904
	s_waitcnt vmcnt(9)
	ds_write_b128 v1, v[172:175] offset:64512
	s_waitcnt vmcnt(8)
	ds_write_b128 v92, v[176:179] offset:32256
	global_load_dwordx4 v[148:151], v[80:81], off offset:896
	global_load_dwordx4 v[152:155], v[82:83], off offset:896
	global_load_dwordx4 v[156:159], v[78:79], off offset:896
	global_load_dwordx4 v[160:163], v[76:77], off offset:896
	global_load_dwordx4 v[164:167], v[90:91], off offset:896
	global_load_dwordx4 v[168:171], v[84:85], off offset:896
	global_load_dwordx4 v[172:175], v[86:87], off offset:896
	global_load_dwordx4 v[176:179], v[88:89], off offset:896
	s_waitcnt lgkmcnt(0)
	s_barrier
	v_mfma_f32_32x32x16_bf16 v[34:49], v[212:215], v[216:219], v[34:49]
	v_mfma_f32_32x32x16_bf16 v[50:65], v[212:215], v[228:231], v[50:65]
	v_mfma_f32_32x32x16_bf16 v[2:17], v[220:223], v[224:227], v[2:17]
	v_mfma_f32_32x32x16_bf16 v[18:33], v[220:223], v[232:235], v[18:33]
	v_mfma_f32_32x32x16_bf16 v[34:49], v[236:239], v[224:227], v[34:49]
	v_mfma_f32_32x32x16_bf16 v[50:65], v[236:239], v[232:235], v[50:65]
	ds_read_b128 v[212:215], v72 offset:18432
	ds_read_b128 v[216:219], v73 offset:55296
	ds_read_b128 v[220:223], v72 offset:18464
	ds_read_b128 v[224:227], v73 offset:55328
	ds_read_b128 v[228:231], v73 offset:59904
	ds_read_b128 v[232:235], v73 offset:59936
	s_waitcnt lgkmcnt(4)
	v_mfma_f32_32x32x16_bf16 v[2:17], v[212:215], v[216:219], v[2:17]
	s_waitcnt lgkmcnt(1)
	v_mfma_f32_32x32x16_bf16 v[18:33], v[212:215], v[228:231], v[18:33]
	ds_read_b128 v[212:215], v72 offset:23040
	ds_read_b128 v[236:239], v72 offset:23072
	s_waitcnt lgkmcnt(1)
	v_mfma_f32_32x32x16_bf16 v[34:49], v[212:215], v[216:219], v[34:49]
	v_mfma_f32_32x32x16_bf16 v[50:65], v[212:215], v[228:231], v[50:65]
	v_mfma_f32_32x32x16_bf16 v[2:17], v[220:223], v[224:227], v[2:17]
	v_mfma_f32_32x32x16_bf16 v[18:33], v[220:223], v[232:235], v[18:33]
	s_waitcnt lgkmcnt(0)
	v_mfma_f32_32x32x16_bf16 v[34:49], v[236:239], v[224:227], v[34:49]
	ds_read_b128 v[212:215], v72 offset:18496
	ds_read_b128 v[216:219], v73 offset:55360
	ds_read_b128 v[220:223], v72 offset:18528
	ds_read_b128 v[224:227], v73 offset:55392
	v_mfma_f32_32x32x16_bf16 v[50:65], v[236:239], v[232:235], v[50:65]
	ds_read_b128 v[228:231], v73 offset:59968
	ds_read_b128 v[232:235], v73 offset:60000
	s_waitcnt lgkmcnt(4)
	v_mfma_f32_32x32x16_bf16 v[2:17], v[212:215], v[216:219], v[2:17]
	s_waitcnt lgkmcnt(1)
	v_mfma_f32_32x32x16_bf16 v[18:33], v[212:215], v[228:231], v[18:33]
	ds_read_b128 v[212:215], v72 offset:23104
	ds_read_b128 v[236:239], v72 offset:23136
	s_waitcnt vmcnt(13)
	ds_write_b128 v1, v[188:191]
	ds_write_b128 v1, v[180:183] offset:4608
	ds_write_b128 v1, v[184:187] offset:9216
	s_waitcnt vmcnt(11)
	ds_write_b128 v1, v[196:199] offset:13824
	ds_write_b128 v1, v[192:195] offset:36864
	s_waitcnt vmcnt(10)
	ds_write_b128 v1, v[200:203] offset:41472
	s_waitcnt vmcnt(9)
	ds_write_b128 v1, v[204:207] offset:46080
	s_waitcnt vmcnt(8)
	ds_write_b128 v1, v[208:211] offset:50688
	global_load_dwordx4 v[180:183], v[80:81], off offset:1024
	global_load_dwordx4 v[184:187], v[82:83], off offset:1024
	global_load_dwordx4 v[188:191], v[78:79], off offset:1024
	global_load_dwordx4 v[192:195], v[76:77], off offset:1024
	global_load_dwordx4 v[196:199], v[90:91], off offset:1024
	global_load_dwordx4 v[200:203], v[84:85], off offset:1024
	global_load_dwordx4 v[204:207], v[86:87], off offset:1024
	global_load_dwordx4 v[208:211], v[88:89], off offset:1024
	s_waitcnt lgkmcnt(0)
	s_barrier
	v_mfma_f32_32x32x16_bf16 v[34:49], v[212:215], v[216:219], v[34:49]
	v_mfma_f32_32x32x16_bf16 v[50:65], v[212:215], v[228:231], v[50:65]
	v_mfma_f32_32x32x16_bf16 v[2:17], v[220:223], v[224:227], v[2:17]
	v_mfma_f32_32x32x16_bf16 v[18:33], v[220:223], v[232:235], v[18:33]
	v_mfma_f32_32x32x16_bf16 v[34:49], v[236:239], v[224:227], v[34:49]
	v_mfma_f32_32x32x16_bf16 v[50:65], v[236:239], v[232:235], v[50:65]
	ds_read_b128 v[212:215], v72
	ds_read_b128 v[216:219], v73 offset:36864
	ds_read_b128 v[220:223], v72 offset:32
	ds_read_b128 v[224:227], v73 offset:36896
	ds_read_b128 v[228:231], v73 offset:41472
	ds_read_b128 v[232:235], v73 offset:41504
	s_waitcnt lgkmcnt(4)
	v_mfma_f32_32x32x16_bf16 v[2:17], v[212:215], v[216:219], v[2:17]
	s_waitcnt lgkmcnt(1)
	v_mfma_f32_32x32x16_bf16 v[18:33], v[212:215], v[228:231], v[18:33]
	ds_read_b128 v[212:215], v72 offset:4608
	ds_read_b128 v[236:239], v72 offset:4640
	s_waitcnt lgkmcnt(1)
	v_mfma_f32_32x32x16_bf16 v[34:49], v[212:215], v[216:219], v[34:49]
	v_mfma_f32_32x32x16_bf16 v[50:65], v[212:215], v[228:231], v[50:65]
	v_mfma_f32_32x32x16_bf16 v[2:17], v[220:223], v[224:227], v[2:17]
	v_mfma_f32_32x32x16_bf16 v[18:33], v[220:223], v[232:235], v[18:33]
	s_waitcnt lgkmcnt(0)
	v_mfma_f32_32x32x16_bf16 v[34:49], v[236:239], v[224:227], v[34:49]
	ds_read_b128 v[212:215], v72 offset:64
	ds_read_b128 v[216:219], v73 offset:36928
	ds_read_b128 v[220:223], v72 offset:96
	ds_read_b128 v[224:227], v73 offset:36960
	v_mfma_f32_32x32x16_bf16 v[50:65], v[236:239], v[232:235], v[50:65]
	ds_read_b128 v[228:231], v73 offset:41536
	ds_read_b128 v[232:235], v73 offset:41568
	s_waitcnt lgkmcnt(4)
	v_mfma_f32_32x32x16_bf16 v[2:17], v[212:215], v[216:219], v[2:17]
	s_waitcnt lgkmcnt(1)
	v_mfma_f32_32x32x16_bf16 v[18:33], v[212:215], v[228:231], v[18:33]
	ds_read_b128 v[212:215], v72 offset:4672
	ds_read_b128 v[236:239], v72 offset:4704
	s_waitcnt vmcnt(13)
	ds_write_b128 v1, v[156:159] offset:18432
	ds_write_b128 v1, v[148:151] offset:23040
	ds_write_b128 v1, v[152:155] offset:27648
	s_waitcnt vmcnt(11)
	ds_write_b128 v1, v[164:167] offset:32256
	ds_write_b128 v1, v[160:163] offset:55296
	s_waitcnt vmcnt(10)
	ds_write_b128 v1, v[168:171] offset:59904
	s_waitcnt vmcnt(9)
	ds_write_b128 v1, v[172:175] offset:64512
	s_waitcnt vmcnt(8)
	ds_write_b128 v92, v[176:179] offset:32256
	global_load_dwordx4 v[148:151], v[80:81], off offset:1152
	global_load_dwordx4 v[152:155], v[82:83], off offset:1152
	global_load_dwordx4 v[156:159], v[78:79], off offset:1152
	global_load_dwordx4 v[160:163], v[76:77], off offset:1152
	global_load_dwordx4 v[164:167], v[90:91], off offset:1152
	global_load_dwordx4 v[168:171], v[84:85], off offset:1152
	global_load_dwordx4 v[172:175], v[86:87], off offset:1152
	global_load_dwordx4 v[176:179], v[88:89], off offset:1152
	s_waitcnt lgkmcnt(0)
	s_barrier
	v_mfma_f32_32x32x16_bf16 v[34:49], v[212:215], v[216:219], v[34:49]
	v_mfma_f32_32x32x16_bf16 v[50:65], v[212:215], v[228:231], v[50:65]
	v_mfma_f32_32x32x16_bf16 v[2:17], v[220:223], v[224:227], v[2:17]
	v_mfma_f32_32x32x16_bf16 v[18:33], v[220:223], v[232:235], v[18:33]
	v_mfma_f32_32x32x16_bf16 v[34:49], v[236:239], v[224:227], v[34:49]
	v_mfma_f32_32x32x16_bf16 v[50:65], v[236:239], v[232:235], v[50:65]
	ds_read_b128 v[212:215], v72 offset:18432
	ds_read_b128 v[216:219], v73 offset:55296
	ds_read_b128 v[220:223], v72 offset:18464
	ds_read_b128 v[224:227], v73 offset:55328
	ds_read_b128 v[228:231], v73 offset:59904
	ds_read_b128 v[232:235], v73 offset:59936
	s_waitcnt lgkmcnt(4)
	v_mfma_f32_32x32x16_bf16 v[2:17], v[212:215], v[216:219], v[2:17]
	s_waitcnt lgkmcnt(1)
	v_mfma_f32_32x32x16_bf16 v[18:33], v[212:215], v[228:231], v[18:33]
	ds_read_b128 v[212:215], v72 offset:23040
	ds_read_b128 v[236:239], v72 offset:23072
	s_waitcnt lgkmcnt(1)
	v_mfma_f32_32x32x16_bf16 v[34:49], v[212:215], v[216:219], v[34:49]
	v_mfma_f32_32x32x16_bf16 v[50:65], v[212:215], v[228:231], v[50:65]
	v_mfma_f32_32x32x16_bf16 v[2:17], v[220:223], v[224:227], v[2:17]
	v_mfma_f32_32x32x16_bf16 v[18:33], v[220:223], v[232:235], v[18:33]
	s_waitcnt lgkmcnt(0)
	v_mfma_f32_32x32x16_bf16 v[34:49], v[236:239], v[224:227], v[34:49]
	ds_read_b128 v[212:215], v72 offset:18496
	ds_read_b128 v[216:219], v73 offset:55360
	ds_read_b128 v[220:223], v72 offset:18528
	ds_read_b128 v[224:227], v73 offset:55392
	v_mfma_f32_32x32x16_bf16 v[50:65], v[236:239], v[232:235], v[50:65]
	ds_read_b128 v[228:231], v73 offset:59968
	ds_read_b128 v[232:235], v73 offset:60000
	s_waitcnt lgkmcnt(4)
	v_mfma_f32_32x32x16_bf16 v[2:17], v[212:215], v[216:219], v[2:17]
	s_waitcnt lgkmcnt(1)
	v_mfma_f32_32x32x16_bf16 v[18:33], v[212:215], v[228:231], v[18:33]
	ds_read_b128 v[212:215], v72 offset:23104
	ds_read_b128 v[236:239], v72 offset:23136
	s_waitcnt vmcnt(13)
	ds_write_b128 v1, v[188:191]
	ds_write_b128 v1, v[180:183] offset:4608
	ds_write_b128 v1, v[184:187] offset:9216
	s_waitcnt vmcnt(11)
	ds_write_b128 v1, v[196:199] offset:13824
	ds_write_b128 v1, v[192:195] offset:36864
	s_waitcnt vmcnt(10)
	ds_write_b128 v1, v[200:203] offset:41472
	s_waitcnt vmcnt(9)
	ds_write_b128 v1, v[204:207] offset:46080
	s_waitcnt vmcnt(8)
	ds_write_b128 v1, v[208:211] offset:50688
	global_load_dwordx4 v[180:183], v[80:81], off offset:1280
	global_load_dwordx4 v[184:187], v[82:83], off offset:1280
	global_load_dwordx4 v[188:191], v[78:79], off offset:1280
	global_load_dwordx4 v[192:195], v[76:77], off offset:1280
	global_load_dwordx4 v[196:199], v[90:91], off offset:1280
	global_load_dwordx4 v[200:203], v[84:85], off offset:1280
	global_load_dwordx4 v[204:207], v[86:87], off offset:1280
	global_load_dwordx4 v[208:211], v[88:89], off offset:1280
	s_waitcnt lgkmcnt(0)
	s_barrier
	v_mfma_f32_32x32x16_bf16 v[34:49], v[212:215], v[216:219], v[34:49]
	v_mfma_f32_32x32x16_bf16 v[50:65], v[212:215], v[228:231], v[50:65]
	v_mfma_f32_32x32x16_bf16 v[2:17], v[220:223], v[224:227], v[2:17]
	v_mfma_f32_32x32x16_bf16 v[18:33], v[220:223], v[232:235], v[18:33]
	v_mfma_f32_32x32x16_bf16 v[34:49], v[236:239], v[224:227], v[34:49]
	v_mfma_f32_32x32x16_bf16 v[50:65], v[236:239], v[232:235], v[50:65]
	ds_read_b128 v[212:215], v72
	ds_read_b128 v[216:219], v73 offset:36864
	ds_read_b128 v[220:223], v72 offset:32
	ds_read_b128 v[224:227], v73 offset:36896
	ds_read_b128 v[228:231], v73 offset:41472
	ds_read_b128 v[232:235], v73 offset:41504
	s_waitcnt lgkmcnt(4)
	v_mfma_f32_32x32x16_bf16 v[2:17], v[212:215], v[216:219], v[2:17]
	s_waitcnt lgkmcnt(1)
	v_mfma_f32_32x32x16_bf16 v[18:33], v[212:215], v[228:231], v[18:33]
	ds_read_b128 v[212:215], v72 offset:4608
	ds_read_b128 v[236:239], v72 offset:4640
	s_waitcnt lgkmcnt(1)
	v_mfma_f32_32x32x16_bf16 v[34:49], v[212:215], v[216:219], v[34:49]
	v_mfma_f32_32x32x16_bf16 v[50:65], v[212:215], v[228:231], v[50:65]
	v_mfma_f32_32x32x16_bf16 v[2:17], v[220:223], v[224:227], v[2:17]
	v_mfma_f32_32x32x16_bf16 v[18:33], v[220:223], v[232:235], v[18:33]
	s_waitcnt lgkmcnt(0)
	v_mfma_f32_32x32x16_bf16 v[34:49], v[236:239], v[224:227], v[34:49]
	ds_read_b128 v[212:215], v72 offset:64
	ds_read_b128 v[216:219], v73 offset:36928
	ds_read_b128 v[220:223], v72 offset:96
	ds_read_b128 v[224:227], v73 offset:36960
	v_mfma_f32_32x32x16_bf16 v[50:65], v[236:239], v[232:235], v[50:65]
	ds_read_b128 v[228:231], v73 offset:41536
	ds_read_b128 v[232:235], v73 offset:41568
	s_waitcnt lgkmcnt(4)
	v_mfma_f32_32x32x16_bf16 v[2:17], v[212:215], v[216:219], v[2:17]
	s_waitcnt lgkmcnt(1)
	v_mfma_f32_32x32x16_bf16 v[18:33], v[212:215], v[228:231], v[18:33]
	ds_read_b128 v[212:215], v72 offset:4672
	ds_read_b128 v[236:239], v72 offset:4704
	s_waitcnt vmcnt(13)
	ds_write_b128 v1, v[156:159] offset:18432
	ds_write_b128 v1, v[148:151] offset:23040
	ds_write_b128 v1, v[152:155] offset:27648
	s_waitcnt vmcnt(11)
	ds_write_b128 v1, v[164:167] offset:32256
	ds_write_b128 v1, v[160:163] offset:55296
	s_waitcnt vmcnt(10)
	ds_write_b128 v1, v[168:171] offset:59904
	s_waitcnt vmcnt(9)
	ds_write_b128 v1, v[172:175] offset:64512
	s_waitcnt vmcnt(8)
	ds_write_b128 v92, v[176:179] offset:32256
	global_load_dwordx4 v[148:151], v[80:81], off offset:1408
	global_load_dwordx4 v[152:155], v[82:83], off offset:1408
	global_load_dwordx4 v[156:159], v[78:79], off offset:1408
	global_load_dwordx4 v[160:163], v[76:77], off offset:1408
	global_load_dwordx4 v[164:167], v[90:91], off offset:1408
	global_load_dwordx4 v[168:171], v[84:85], off offset:1408
	global_load_dwordx4 v[172:175], v[86:87], off offset:1408
	global_load_dwordx4 v[176:179], v[88:89], off offset:1408
	s_waitcnt lgkmcnt(0)
	s_barrier
	v_mfma_f32_32x32x16_bf16 v[34:49], v[212:215], v[216:219], v[34:49]
	v_mfma_f32_32x32x16_bf16 v[50:65], v[212:215], v[228:231], v[50:65]
	v_mfma_f32_32x32x16_bf16 v[2:17], v[220:223], v[224:227], v[2:17]
	v_mfma_f32_32x32x16_bf16 v[18:33], v[220:223], v[232:235], v[18:33]
	v_mfma_f32_32x32x16_bf16 v[34:49], v[236:239], v[224:227], v[34:49]
	v_mfma_f32_32x32x16_bf16 v[50:65], v[236:239], v[232:235], v[50:65]
	ds_read_b128 v[212:215], v72 offset:18432
	ds_read_b128 v[216:219], v73 offset:55296
	ds_read_b128 v[220:223], v72 offset:18464
	ds_read_b128 v[224:227], v73 offset:55328
	ds_read_b128 v[228:231], v73 offset:59904
	ds_read_b128 v[232:235], v73 offset:59936
	s_waitcnt lgkmcnt(4)
	v_mfma_f32_32x32x16_bf16 v[2:17], v[212:215], v[216:219], v[2:17]
	s_waitcnt lgkmcnt(1)
	v_mfma_f32_32x32x16_bf16 v[18:33], v[212:215], v[228:231], v[18:33]
	ds_read_b128 v[212:215], v72 offset:23040
	ds_read_b128 v[236:239], v72 offset:23072
	s_waitcnt lgkmcnt(1)
	v_mfma_f32_32x32x16_bf16 v[34:49], v[212:215], v[216:219], v[34:49]
	v_mfma_f32_32x32x16_bf16 v[50:65], v[212:215], v[228:231], v[50:65]
	v_mfma_f32_32x32x16_bf16 v[2:17], v[220:223], v[224:227], v[2:17]
	v_mfma_f32_32x32x16_bf16 v[18:33], v[220:223], v[232:235], v[18:33]
	s_waitcnt lgkmcnt(0)
	v_mfma_f32_32x32x16_bf16 v[34:49], v[236:239], v[224:227], v[34:49]
	ds_read_b128 v[212:215], v72 offset:18496
	ds_read_b128 v[216:219], v73 offset:55360
	ds_read_b128 v[220:223], v72 offset:18528
	ds_read_b128 v[224:227], v73 offset:55392
	v_mfma_f32_32x32x16_bf16 v[50:65], v[236:239], v[232:235], v[50:65]
	ds_read_b128 v[228:231], v73 offset:59968
	ds_read_b128 v[232:235], v73 offset:60000
	s_waitcnt lgkmcnt(4)
	v_mfma_f32_32x32x16_bf16 v[2:17], v[212:215], v[216:219], v[2:17]
	s_waitcnt lgkmcnt(1)
	v_mfma_f32_32x32x16_bf16 v[18:33], v[212:215], v[228:231], v[18:33]
	ds_read_b128 v[212:215], v72 offset:23104
	ds_read_b128 v[236:239], v72 offset:23136
	s_waitcnt vmcnt(13)
	ds_write_b128 v1, v[188:191]
	ds_write_b128 v1, v[180:183] offset:4608
	ds_write_b128 v1, v[184:187] offset:9216
	s_waitcnt vmcnt(11)
	ds_write_b128 v1, v[196:199] offset:13824
	ds_write_b128 v1, v[192:195] offset:36864
	s_waitcnt vmcnt(10)
	ds_write_b128 v1, v[200:203] offset:41472
	s_waitcnt vmcnt(9)
	ds_write_b128 v1, v[204:207] offset:46080
	s_waitcnt vmcnt(8)
	ds_write_b128 v1, v[208:211] offset:50688
	global_load_dwordx4 v[180:183], v[80:81], off offset:1536
	global_load_dwordx4 v[184:187], v[82:83], off offset:1536
	global_load_dwordx4 v[188:191], v[78:79], off offset:1536
	global_load_dwordx4 v[192:195], v[76:77], off offset:1536
	global_load_dwordx4 v[196:199], v[90:91], off offset:1536
	global_load_dwordx4 v[200:203], v[84:85], off offset:1536
	global_load_dwordx4 v[204:207], v[86:87], off offset:1536
	global_load_dwordx4 v[208:211], v[88:89], off offset:1536
	s_waitcnt lgkmcnt(0)
	s_barrier
	v_mfma_f32_32x32x16_bf16 v[34:49], v[212:215], v[216:219], v[34:49]
	v_mfma_f32_32x32x16_bf16 v[50:65], v[212:215], v[228:231], v[50:65]
	v_mfma_f32_32x32x16_bf16 v[2:17], v[220:223], v[224:227], v[2:17]
	v_mfma_f32_32x32x16_bf16 v[18:33], v[220:223], v[232:235], v[18:33]
	v_mfma_f32_32x32x16_bf16 v[34:49], v[236:239], v[224:227], v[34:49]
	v_mfma_f32_32x32x16_bf16 v[50:65], v[236:239], v[232:235], v[50:65]
	ds_read_b128 v[212:215], v72
	ds_read_b128 v[216:219], v73 offset:36864
	ds_read_b128 v[220:223], v72 offset:32
	ds_read_b128 v[224:227], v73 offset:36896
	ds_read_b128 v[228:231], v73 offset:41472
	ds_read_b128 v[232:235], v73 offset:41504
	s_waitcnt lgkmcnt(4)
	v_mfma_f32_32x32x16_bf16 v[2:17], v[212:215], v[216:219], v[2:17]
	s_waitcnt lgkmcnt(1)
	v_mfma_f32_32x32x16_bf16 v[18:33], v[212:215], v[228:231], v[18:33]
	ds_read_b128 v[212:215], v72 offset:4608
	ds_read_b128 v[236:239], v72 offset:4640
	s_waitcnt lgkmcnt(1)
	v_mfma_f32_32x32x16_bf16 v[34:49], v[212:215], v[216:219], v[34:49]
	v_mfma_f32_32x32x16_bf16 v[50:65], v[212:215], v[228:231], v[50:65]
	v_mfma_f32_32x32x16_bf16 v[2:17], v[220:223], v[224:227], v[2:17]
	v_mfma_f32_32x32x16_bf16 v[18:33], v[220:223], v[232:235], v[18:33]
	s_waitcnt lgkmcnt(0)
	v_mfma_f32_32x32x16_bf16 v[34:49], v[236:239], v[224:227], v[34:49]
	ds_read_b128 v[212:215], v72 offset:64
	ds_read_b128 v[216:219], v73 offset:36928
	ds_read_b128 v[220:223], v72 offset:96
	ds_read_b128 v[224:227], v73 offset:36960
	v_mfma_f32_32x32x16_bf16 v[50:65], v[236:239], v[232:235], v[50:65]
	ds_read_b128 v[228:231], v73 offset:41536
	ds_read_b128 v[232:235], v73 offset:41568
	s_waitcnt lgkmcnt(4)
	v_mfma_f32_32x32x16_bf16 v[2:17], v[212:215], v[216:219], v[2:17]
	s_waitcnt lgkmcnt(1)
	v_mfma_f32_32x32x16_bf16 v[18:33], v[212:215], v[228:231], v[18:33]
	ds_read_b128 v[212:215], v72 offset:4672
	ds_read_b128 v[236:239], v72 offset:4704
	s_waitcnt vmcnt(13)
	ds_write_b128 v1, v[156:159] offset:18432
	ds_write_b128 v1, v[148:151] offset:23040
	ds_write_b128 v1, v[152:155] offset:27648
	s_waitcnt vmcnt(11)
	ds_write_b128 v1, v[164:167] offset:32256
	ds_write_b128 v1, v[160:163] offset:55296
	s_waitcnt vmcnt(10)
	ds_write_b128 v1, v[168:171] offset:59904
	s_waitcnt vmcnt(9)
	ds_write_b128 v1, v[172:175] offset:64512
	s_waitcnt vmcnt(8)
	ds_write_b128 v92, v[176:179] offset:32256
	global_load_dwordx4 v[148:151], v[80:81], off offset:1664
	global_load_dwordx4 v[152:155], v[82:83], off offset:1664
	global_load_dwordx4 v[156:159], v[78:79], off offset:1664
	global_load_dwordx4 v[160:163], v[76:77], off offset:1664
	global_load_dwordx4 v[164:167], v[90:91], off offset:1664
	global_load_dwordx4 v[168:171], v[84:85], off offset:1664
	global_load_dwordx4 v[172:175], v[86:87], off offset:1664
	global_load_dwordx4 v[176:179], v[88:89], off offset:1664
	s_waitcnt lgkmcnt(0)
	s_barrier
	v_mfma_f32_32x32x16_bf16 v[34:49], v[212:215], v[216:219], v[34:49]
	v_mfma_f32_32x32x16_bf16 v[50:65], v[212:215], v[228:231], v[50:65]
	v_mfma_f32_32x32x16_bf16 v[2:17], v[220:223], v[224:227], v[2:17]
	v_mfma_f32_32x32x16_bf16 v[18:33], v[220:223], v[232:235], v[18:33]
	v_mfma_f32_32x32x16_bf16 v[34:49], v[236:239], v[224:227], v[34:49]
	v_mfma_f32_32x32x16_bf16 v[50:65], v[236:239], v[232:235], v[50:65]
	ds_read_b128 v[212:215], v72 offset:18432
	ds_read_b128 v[216:219], v73 offset:55296
	ds_read_b128 v[220:223], v72 offset:18464
	ds_read_b128 v[224:227], v73 offset:55328
	ds_read_b128 v[228:231], v73 offset:59904
	ds_read_b128 v[232:235], v73 offset:59936
	s_waitcnt lgkmcnt(4)
	v_mfma_f32_32x32x16_bf16 v[2:17], v[212:215], v[216:219], v[2:17]
	s_waitcnt lgkmcnt(1)
	v_mfma_f32_32x32x16_bf16 v[18:33], v[212:215], v[228:231], v[18:33]
	ds_read_b128 v[212:215], v72 offset:23040
	ds_read_b128 v[236:239], v72 offset:23072
	s_waitcnt lgkmcnt(1)
	v_mfma_f32_32x32x16_bf16 v[34:49], v[212:215], v[216:219], v[34:49]
	v_mfma_f32_32x32x16_bf16 v[50:65], v[212:215], v[228:231], v[50:65]
	v_mfma_f32_32x32x16_bf16 v[2:17], v[220:223], v[224:227], v[2:17]
	v_mfma_f32_32x32x16_bf16 v[18:33], v[220:223], v[232:235], v[18:33]
	s_waitcnt lgkmcnt(0)
	v_mfma_f32_32x32x16_bf16 v[34:49], v[236:239], v[224:227], v[34:49]
	ds_read_b128 v[212:215], v72 offset:18496
	ds_read_b128 v[216:219], v73 offset:55360
	ds_read_b128 v[220:223], v72 offset:18528
	ds_read_b128 v[224:227], v73 offset:55392
	v_mfma_f32_32x32x16_bf16 v[50:65], v[236:239], v[232:235], v[50:65]
	ds_read_b128 v[228:231], v73 offset:59968
	ds_read_b128 v[232:235], v73 offset:60000
	s_waitcnt lgkmcnt(4)
	v_mfma_f32_32x32x16_bf16 v[2:17], v[212:215], v[216:219], v[2:17]
	s_waitcnt lgkmcnt(1)
	v_mfma_f32_32x32x16_bf16 v[18:33], v[212:215], v[228:231], v[18:33]
	ds_read_b128 v[212:215], v72 offset:23104
	ds_read_b128 v[236:239], v72 offset:23136
	s_waitcnt vmcnt(13)
	ds_write_b128 v1, v[188:191]
	ds_write_b128 v1, v[180:183] offset:4608
	ds_write_b128 v1, v[184:187] offset:9216
	s_waitcnt vmcnt(11)
	ds_write_b128 v1, v[196:199] offset:13824
	ds_write_b128 v1, v[192:195] offset:36864
	s_waitcnt vmcnt(10)
	ds_write_b128 v1, v[200:203] offset:41472
	s_waitcnt vmcnt(9)
	ds_write_b128 v1, v[204:207] offset:46080
	s_waitcnt vmcnt(8)
	ds_write_b128 v1, v[208:211] offset:50688
	global_load_dwordx4 v[180:183], v[80:81], off offset:1792
	global_load_dwordx4 v[184:187], v[82:83], off offset:1792
	global_load_dwordx4 v[188:191], v[78:79], off offset:1792
	global_load_dwordx4 v[192:195], v[76:77], off offset:1792
	global_load_dwordx4 v[196:199], v[90:91], off offset:1792
	global_load_dwordx4 v[200:203], v[84:85], off offset:1792
	global_load_dwordx4 v[204:207], v[86:87], off offset:1792
	global_load_dwordx4 v[208:211], v[88:89], off offset:1792
	s_waitcnt lgkmcnt(0)
	s_barrier
	v_mfma_f32_32x32x16_bf16 v[34:49], v[212:215], v[216:219], v[34:49]
	v_mfma_f32_32x32x16_bf16 v[50:65], v[212:215], v[228:231], v[50:65]
	v_mfma_f32_32x32x16_bf16 v[2:17], v[220:223], v[224:227], v[2:17]
	v_mfma_f32_32x32x16_bf16 v[18:33], v[220:223], v[232:235], v[18:33]
	v_mfma_f32_32x32x16_bf16 v[34:49], v[236:239], v[224:227], v[34:49]
	v_mfma_f32_32x32x16_bf16 v[50:65], v[236:239], v[232:235], v[50:65]
	ds_read_b128 v[212:215], v72
	ds_read_b128 v[216:219], v73 offset:36864
	ds_read_b128 v[220:223], v72 offset:32
	ds_read_b128 v[224:227], v73 offset:36896
	ds_read_b128 v[228:231], v73 offset:41472
	ds_read_b128 v[232:235], v73 offset:41504
	s_waitcnt lgkmcnt(4)
	v_mfma_f32_32x32x16_bf16 v[2:17], v[212:215], v[216:219], v[2:17]
	s_waitcnt lgkmcnt(1)
	v_mfma_f32_32x32x16_bf16 v[18:33], v[212:215], v[228:231], v[18:33]
	ds_read_b128 v[212:215], v72 offset:4608
	ds_read_b128 v[236:239], v72 offset:4640
	s_waitcnt lgkmcnt(1)
	v_mfma_f32_32x32x16_bf16 v[34:49], v[212:215], v[216:219], v[34:49]
	v_mfma_f32_32x32x16_bf16 v[50:65], v[212:215], v[228:231], v[50:65]
	v_mfma_f32_32x32x16_bf16 v[2:17], v[220:223], v[224:227], v[2:17]
	v_mfma_f32_32x32x16_bf16 v[18:33], v[220:223], v[232:235], v[18:33]
	s_waitcnt lgkmcnt(0)
	v_mfma_f32_32x32x16_bf16 v[34:49], v[236:239], v[224:227], v[34:49]
	ds_read_b128 v[212:215], v72 offset:64
	ds_read_b128 v[216:219], v73 offset:36928
	ds_read_b128 v[220:223], v72 offset:96
	ds_read_b128 v[224:227], v73 offset:36960
	v_mfma_f32_32x32x16_bf16 v[50:65], v[236:239], v[232:235], v[50:65]
	ds_read_b128 v[228:231], v73 offset:41536
	ds_read_b128 v[232:235], v73 offset:41568
	s_waitcnt lgkmcnt(4)
	v_mfma_f32_32x32x16_bf16 v[2:17], v[212:215], v[216:219], v[2:17]
	s_waitcnt lgkmcnt(1)
	v_mfma_f32_32x32x16_bf16 v[18:33], v[212:215], v[228:231], v[18:33]
	ds_read_b128 v[212:215], v72 offset:4672
	ds_read_b128 v[236:239], v72 offset:4704
	s_waitcnt vmcnt(13)
	ds_write_b128 v1, v[156:159] offset:18432
	ds_write_b128 v1, v[148:151] offset:23040
	ds_write_b128 v1, v[152:155] offset:27648
	s_waitcnt vmcnt(11)
	ds_write_b128 v1, v[164:167] offset:32256
	ds_write_b128 v1, v[160:163] offset:55296
	s_waitcnt vmcnt(10)
	ds_write_b128 v1, v[168:171] offset:59904
	s_waitcnt vmcnt(9)
	ds_write_b128 v1, v[172:175] offset:64512
	s_waitcnt vmcnt(8)
	ds_write_b128 v92, v[176:179] offset:32256
	s_waitcnt lgkmcnt(0)
	s_barrier
	global_load_dwordx4 v[148:151], v[80:81], off offset:1920
	s_nop 0
	global_load_dwordx4 v[80:83], v[82:83], off offset:1920
	s_nop 0
	global_load_dwordx4 v[152:155], v[78:79], off offset:1920
	s_nop 0
	global_load_dwordx4 v[76:79], v[76:77], off offset:1920
	s_nop 0
	global_load_dwordx4 v[156:159], v[90:91], off offset:1920
	global_load_dwordx4 v[160:163], v[84:85], off offset:1920
	s_nop 0
	global_load_dwordx4 v[84:87], v[86:87], off offset:1920
	s_nop 0
	global_load_dwordx4 v[88:91], v[88:89], off offset:1920
	v_mfma_f32_32x32x16_bf16 v[34:49], v[212:215], v[216:219], v[34:49]
	v_mfma_f32_32x32x16_bf16 v[50:65], v[212:215], v[228:231], v[50:65]
	v_mfma_f32_32x32x16_bf16 v[2:17], v[220:223], v[224:227], v[2:17]
	v_mfma_f32_32x32x16_bf16 v[18:33], v[220:223], v[232:235], v[18:33]
	v_mfma_f32_32x32x16_bf16 v[34:49], v[236:239], v[224:227], v[34:49]
	v_mfma_f32_32x32x16_bf16 v[50:65], v[236:239], v[232:235], v[50:65]
	ds_read_b128 v[164:167], v72 offset:18432
	ds_read_b128 v[168:171], v73 offset:55296
	ds_read_b128 v[172:175], v72 offset:18464
	ds_read_b128 v[176:179], v73 offset:55328
	ds_read_b128 v[212:215], v73 offset:59904
	ds_read_b128 v[216:219], v73 offset:59936
	s_waitcnt lgkmcnt(4)
	v_mfma_f32_32x32x16_bf16 v[2:17], v[164:167], v[168:171], v[2:17]
	s_waitcnt lgkmcnt(1)
	v_mfma_f32_32x32x16_bf16 v[18:33], v[164:167], v[212:215], v[18:33]
	ds_read_b128 v[164:167], v72 offset:23040
	ds_read_b128 v[220:223], v72 offset:23072
	s_waitcnt lgkmcnt(1)
	v_mfma_f32_32x32x16_bf16 v[34:49], v[164:167], v[168:171], v[34:49]
	v_mfma_f32_32x32x16_bf16 v[50:65], v[164:167], v[212:215], v[50:65]
	v_mfma_f32_32x32x16_bf16 v[2:17], v[172:175], v[176:179], v[2:17]
	v_mfma_f32_32x32x16_bf16 v[18:33], v[172:175], v[216:219], v[18:33]
	s_waitcnt lgkmcnt(0)
	v_mfma_f32_32x32x16_bf16 v[34:49], v[220:223], v[176:179], v[34:49]
	ds_read_b128 v[164:167], v72 offset:18496
	ds_read_b128 v[168:171], v73 offset:55360
	ds_read_b128 v[172:175], v72 offset:18528
	ds_read_b128 v[176:179], v73 offset:55392
	v_mfma_f32_32x32x16_bf16 v[50:65], v[220:223], v[216:219], v[50:65]
	ds_read_b128 v[212:215], v73 offset:59968
	ds_read_b128 v[216:219], v73 offset:60000
	s_waitcnt lgkmcnt(4)
	v_mfma_f32_32x32x16_bf16 v[2:17], v[164:167], v[168:171], v[2:17]
	s_waitcnt lgkmcnt(1)
	v_mfma_f32_32x32x16_bf16 v[18:33], v[164:167], v[212:215], v[18:33]
	ds_read_b128 v[164:167], v72 offset:23104
	ds_read_b128 v[220:223], v72 offset:23136
	s_waitcnt vmcnt(13)
	ds_write_b128 v1, v[188:191]
	ds_write_b128 v1, v[180:183] offset:4608
	ds_write_b128 v1, v[184:187] offset:9216
	s_waitcnt vmcnt(11)
	ds_write_b128 v1, v[196:199] offset:13824
	ds_write_b128 v1, v[192:195] offset:36864
	s_waitcnt vmcnt(10)
	ds_write_b128 v1, v[200:203] offset:41472
	s_waitcnt vmcnt(9)
	ds_write_b128 v1, v[204:207] offset:46080
	s_waitcnt vmcnt(8)
	ds_write_b128 v1, v[208:211] offset:50688
	s_waitcnt lgkmcnt(0)
	s_barrier
	v_mfma_f32_32x32x16_bf16 v[34:49], v[164:167], v[168:171], v[34:49]
	v_mfma_f32_32x32x16_bf16 v[50:65], v[164:167], v[212:215], v[50:65]
	v_mfma_f32_32x32x16_bf16 v[2:17], v[172:175], v[176:179], v[2:17]
	v_mfma_f32_32x32x16_bf16 v[18:33], v[172:175], v[216:219], v[18:33]
	v_mfma_f32_32x32x16_bf16 v[34:49], v[220:223], v[176:179], v[34:49]
	v_mfma_f32_32x32x16_bf16 v[50:65], v[220:223], v[216:219], v[50:65]
	ds_read_b128 v[164:167], v72
	ds_read_b128 v[168:171], v73 offset:36864
	ds_read_b128 v[172:175], v72 offset:32
	ds_read_b128 v[176:179], v73 offset:36896
	ds_read_b128 v[180:183], v73 offset:41472
	ds_read_b128 v[184:187], v73 offset:41504
	s_waitcnt lgkmcnt(4)
	v_mfma_f32_32x32x16_bf16 v[2:17], v[164:167], v[168:171], v[2:17]
	s_waitcnt lgkmcnt(1)
	v_mfma_f32_32x32x16_bf16 v[18:33], v[164:167], v[180:183], v[18:33]
	ds_read_b128 v[164:167], v72 offset:4608
	ds_read_b128 v[188:191], v72 offset:4640
	s_waitcnt lgkmcnt(1)
	v_mfma_f32_32x32x16_bf16 v[34:49], v[164:167], v[168:171], v[34:49]
	v_mfma_f32_32x32x16_bf16 v[50:65], v[164:167], v[180:183], v[50:65]
	v_mfma_f32_32x32x16_bf16 v[2:17], v[172:175], v[176:179], v[2:17]
	v_mfma_f32_32x32x16_bf16 v[18:33], v[172:175], v[184:187], v[18:33]
	s_waitcnt lgkmcnt(0)
	v_mfma_f32_32x32x16_bf16 v[34:49], v[188:191], v[176:179], v[34:49]
	ds_read_b128 v[164:167], v72 offset:64
	ds_read_b128 v[168:171], v73 offset:36928
	ds_read_b128 v[172:175], v72 offset:96
	ds_read_b128 v[176:179], v73 offset:36960
	v_mfma_f32_32x32x16_bf16 v[50:65], v[188:191], v[184:187], v[50:65]
	ds_read_b128 v[180:183], v73 offset:41536
	ds_read_b128 v[184:187], v73 offset:41568
	s_waitcnt lgkmcnt(4)
	v_mfma_f32_32x32x16_bf16 v[2:17], v[164:167], v[168:171], v[2:17]
	s_waitcnt lgkmcnt(1)
	v_mfma_f32_32x32x16_bf16 v[18:33], v[164:167], v[180:183], v[18:33]
	ds_read_b128 v[164:167], v72 offset:4672
	ds_read_b128 v[188:191], v72 offset:4704
	s_waitcnt vmcnt(5)
	ds_write_b128 v1, v[152:155] offset:18432
	ds_write_b128 v1, v[148:151] offset:23040
	ds_write_b128 v1, v[80:83] offset:27648
	s_waitcnt vmcnt(3)
	ds_write_b128 v1, v[156:159] offset:32256
	ds_write_b128 v1, v[76:79] offset:55296
	s_waitcnt vmcnt(2)
	ds_write_b128 v1, v[160:163] offset:59904
	s_waitcnt vmcnt(1)
	ds_write_b128 v1, v[84:87] offset:64512
	s_waitcnt vmcnt(0)
	ds_write_b128 v92, v[88:91] offset:32256
	s_waitcnt lgkmcnt(0)
	s_barrier
	v_mfma_f32_32x32x16_bf16 v[34:49], v[164:167], v[168:171], v[34:49]
	v_mfma_f32_32x32x16_bf16 v[50:65], v[164:167], v[180:183], v[50:65]
	v_mfma_f32_32x32x16_bf16 v[2:17], v[172:175], v[176:179], v[2:17]
	v_mfma_f32_32x32x16_bf16 v[18:33], v[172:175], v[184:187], v[18:33]
	v_mfma_f32_32x32x16_bf16 v[34:49], v[188:191], v[176:179], v[34:49]
	v_mfma_f32_32x32x16_bf16 v[50:65], v[188:191], v[184:187], v[50:65]
	ds_read_b128 v[76:79], v72 offset:18432
	ds_read_b128 v[80:83], v73 offset:55296
	ds_read_b128 v[84:87], v72 offset:18464
	ds_read_b128 v[88:91], v73 offset:55328
	ds_read_b128 v[148:151], v73 offset:59904
	ds_read_b128 v[152:155], v73 offset:59936
	v_or_b32_e32 v66, s8, v93
	s_waitcnt lgkmcnt(4)
	v_mfma_f32_32x32x16_bf16 v[2:17], v[76:79], v[80:83], v[2:17]
	s_lshl_b32 s10, s10, 1
	s_mov_b32 s11, s9
	s_add_i32 s13, s13, s12
	s_add_i32 s14, s14, s15
	s_add_i32 s16, s16, s17
	s_cmpk_lt_u32 s13, 0x400
	s_waitcnt lgkmcnt(1)
	v_mfma_f32_32x32x16_bf16 v[18:33], v[76:79], v[148:151], v[18:33]
	ds_read_b128 v[76:79], v72 offset:23040
	ds_read_b128 v[156:159], v72 offset:23072
	s_waitcnt lgkmcnt(1)
	v_mfma_f32_32x32x16_bf16 v[34:49], v[76:79], v[80:83], v[34:49]
	v_mfma_f32_32x32x16_bf16 v[50:65], v[76:79], v[148:151], v[50:65]
	v_mfma_f32_32x32x16_bf16 v[2:17], v[84:87], v[88:91], v[2:17]
	v_mfma_f32_32x32x16_bf16 v[18:33], v[84:87], v[152:155], v[18:33]
	s_waitcnt lgkmcnt(0)
	v_mfma_f32_32x32x16_bf16 v[34:49], v[156:159], v[88:91], v[34:49]
	ds_read_b128 v[76:79], v72 offset:18496
	ds_read_b128 v[80:83], v73 offset:55360
	ds_read_b128 v[84:87], v72 offset:18528
	ds_read_b128 v[88:91], v73 offset:55392
	v_mfma_f32_32x32x16_bf16 v[50:65], v[156:159], v[152:155], v[50:65]
	ds_read_b128 v[148:151], v73 offset:59968
	ds_read_b128 v[152:155], v73 offset:60000
	s_waitcnt lgkmcnt(4)
	v_mfma_f32_32x32x16_bf16 v[2:17], v[76:79], v[80:83], v[2:17]
	s_waitcnt lgkmcnt(1)
	v_mfma_f32_32x32x16_bf16 v[18:33], v[76:79], v[148:151], v[18:33]
	ds_read_b128 v[76:79], v72 offset:23104
	ds_read_b128 v[156:159], v72 offset:23136
	s_waitcnt lgkmcnt(0)
	s_barrier
	v_mfma_f32_32x32x16_bf16 v[34:49], v[76:79], v[80:83], v[34:49]
	v_mfma_f32_32x32x16_bf16 v[50:65], v[76:79], v[148:151], v[50:65]
	v_mfma_f32_32x32x16_bf16 v[2:17], v[84:87], v[88:91], v[2:17]
	v_mfma_f32_32x32x16_bf16 v[18:33], v[84:87], v[152:155], v[18:33]
	v_mfma_f32_32x32x16_bf16 v[34:49], v[156:159], v[88:91], v[34:49]
	s_nop 10
	ds_write2_b32 v101, v2, v18 offset1:32
	v_mfma_f32_32x32x16_bf16 v[50:65], v[156:159], v[152:155], v[50:65]
	s_nop 11
	ds_write2_b32 v132, v34, v50 offset0:32 offset1:64
	ds_write2_b32 v101, v3, v19 offset0:129 offset1:161
	ds_write2_b32 v132, v35, v51 offset0:161 offset1:193
	ds_write2_b32 v133, v4, v20 offset0:2 offset1:34
	ds_write2_b32 v134, v36, v52 offset0:34 offset1:66
	ds_write2_b32 v133, v5, v21 offset0:131 offset1:163
	ds_write2_b32 v134, v37, v53 offset0:163 offset1:195
	ds_write2_b32 v135, v6, v22 offset0:8 offset1:40
	ds_write2_b32 v136, v38, v54 offset0:40 offset1:72
	ds_write2_b32 v135, v7, v23 offset0:137 offset1:169
	ds_write2_b32 v136, v39, v55 offset0:169 offset1:201
	ds_write2_b32 v137, v8, v24 offset0:10 offset1:42
	ds_write2_b32 v138, v40, v56 offset0:42 offset1:74
	ds_write2_b32 v137, v9, v25 offset0:139 offset1:171
	ds_write2_b32 v138, v41, v57 offset0:171 offset1:203
	ds_write2_b32 v139, v10, v26 offset0:16 offset1:48
	ds_write2_b32 v140, v42, v58 offset0:48 offset1:80
	ds_write2_b32 v139, v11, v27 offset0:145 offset1:177
	ds_write2_b32 v140, v43, v59 offset0:177 offset1:209
	ds_write2_b32 v141, v12, v28 offset0:18 offset1:50
	ds_write2_b32 v142, v44, v60 offset0:50 offset1:82
	ds_write2_b32 v141, v13, v29 offset0:147 offset1:179
	ds_write2_b32 v142, v45, v61 offset0:179 offset1:211
	ds_write2_b32 v143, v14, v30 offset0:24 offset1:56
	ds_write2_b32 v144, v46, v62 offset0:56 offset1:88
	ds_write2_b32 v143, v15, v31 offset0:153 offset1:185
	ds_write2_b32 v144, v47, v63 offset0:185 offset1:217
	ds_write2_b32 v145, v16, v32 offset0:26 offset1:58
	ds_write2_b32 v146, v48, v64 offset0:58 offset1:90
	ds_write2_b32 v145, v17, v33 offset0:155 offset1:187
	ds_write2_b32 v146, v49, v65 offset0:187 offset1:219
	v_lshl_add_u64 v[2:3], v[66:67], 2, s[6:7]
	s_waitcnt lgkmcnt(0)
	s_barrier
	v_mov_b32_e32 v34, v66
	v_lshlrev_b32_e32 v35, 2, v34
	global_load_dword v37, v35, s[6:7]
	global_load_dword v38, v35, s[6:7] offset:64
	global_load_dword v39, v35, s[6:7] offset:128
	global_load_dword v40, v35, s[6:7] offset:192
	global_load_dword v41, v35, s[6:7] offset:256
	global_load_dword v42, v35, s[6:7] offset:320
	global_load_dword v43, v35, s[6:7] offset:384
	global_load_dword v44, v35, s[6:7] offset:448
	v_lshlrev_b32_e32 v36, 13, v34
	v_add3_u32 v36, v36, v74, s10
	s_movk_i32 s22, 0x7fff
	v_mov_b32_e32 v205, 1
	v_mov_b32_e32 v45, 0x358637bd
	s_cmpk_lt_u32 s13, 0x400
	s_cbranch_scc0 .Lxt4_last
	s_lshr_b32 s8, s13, 2
	s_and_b32 s10, s16, 56
	s_and_b32 s8, s8, 0x1ffffc0
	s_or_b32 s10, s10, s3
	s_or_b32 s8, s10, s8
	s_lshl_b32 s8, s8, 7
	s_lshl_b64 s[24:25], s[8:9], 11
	v_lshl_add_u64 v[78:79], v[68:69], 0, s[24:25]
	v_add_co_u32_e32 v80, vcc, s18, v78
	s_and_b32 s10, s14, 0xf80
	s_nop 0
	v_addc_co_u32_e32 v81, vcc, 0, v79, vcc
	s_lshl_b32 s26, s10, 11
	s_mov_b32 s27, s9
	v_add_co_u32_e32 v82, vcc, s19, v78
	v_lshl_add_u64 v[76:77], v[70:71], 0, s[26:27]
	s_nop 0
	v_addc_co_u32_e32 v83, vcc, 0, v79, vcc
	v_add_co_u32_e32 v84, vcc, s18, v76
	global_load_dwordx4 v[2:5], v[78:79], off
	global_load_dwordx4 v[6:9], v[80:81], off
	v_addc_co_u32_e32 v85, vcc, 0, v77, vcc
	v_add_co_u32_e32 v86, vcc, s19, v76
	global_load_dwordx4 v[10:13], v[82:83], off
	global_load_dwordx4 v[14:17], v[76:77], off
	v_addc_co_u32_e32 v87, vcc, 0, v77, vcc
	global_load_dwordx4 v[18:21], v[84:85], off
	global_load_dwordx4 v[22:25], v[86:87], off
	v_add_co_u32_e32 v88, vcc, s20, v76
	s_nop 1
	v_addc_co_u32_e32 v89, vcc, 0, v77, vcc
	global_load_dwordx4 v[26:29], v[88:89], off
	v_add_co_u32_e32 v90, vcc, s20, v78
	s_nop 1
	v_addc_co_u32_e32 v91, vcc, 0, v79, vcc
	global_load_dwordx4 v[30:33], v[90:91], off
	global_load_dwordx4 v[148:151], v[76:77], off offset:128
	global_load_dwordx4 v[152:155], v[84:85], off offset:128
	global_load_dwordx4 v[156:159], v[86:87], off offset:128
	global_load_dwordx4 v[160:163], v[88:89], off offset:128
	global_load_dwordx4 v[164:167], v[78:79], off offset:128
	global_load_dwordx4 v[168:171], v[80:81], off offset:128
	global_load_dwordx4 v[172:175], v[82:83], off offset:128
	global_load_dwordx4 v[176:179], v[90:91], off offset:128
	s_branch .Lxt4_go
.Lxt4_last:
	global_load_dwordx4 v[2:5], v[68:69], off
	global_load_dwordx4 v[6:9], v[68:69], off
	global_load_dwordx4 v[10:13], v[68:69], off
	global_load_dwordx4 v[14:17], v[68:69], off
	global_load_dwordx4 v[18:21], v[68:69], off
	global_load_dwordx4 v[22:25], v[68:69], off
	global_load_dwordx4 v[26:29], v[68:69], off
	global_load_dwordx4 v[30:33], v[68:69], off
	global_load_dwordx4 v[148:151], v[68:69], off
	global_load_dwordx4 v[152:155], v[68:69], off
	global_load_dwordx4 v[156:159], v[68:69], off
	global_load_dwordx4 v[160:163], v[68:69], off
	global_load_dwordx4 v[164:167], v[68:69], off
	global_load_dwordx4 v[168:171], v[68:69], off
	global_load_dwordx4 v[172:175], v[68:69], off
	global_load_dwordx4 v[176:179], v[68:69], off
.Lxt4_go:
	ds_read2_b32 v[46:47], v103 offset0:0 offset1:1
	ds_read2_b32 v[48:49], v103 offset0:2 offset1:3
	ds_read2_b32 v[50:51], v103 offset0:4 offset1:5
	ds_read2_b32 v[52:53], v103 offset0:6 offset1:7
	v_add_u32_e32 v64, 0x2040, v103
	ds_read2_b32 v[54:55], v64 offset0:0 offset1:1
	ds_read2_b32 v[56:57], v64 offset0:2 offset1:3
	ds_read2_b32 v[58:59], v64 offset0:4 offset1:5
	ds_read2_b32 v[60:61], v64 offset0:6 offset1:7
	s_waitcnt vmcnt(23) lgkmcnt(4)
	v_fmamk_f32 v62, v37, 0x3a800000, v45
	v_rsq_f32_e32 v62, v62
	s_nop 0
	v_mul_f32_e32 v46, v46, v62
	v_mul_f32_e32 v47, v47, v62
	v_mul_f32_e32 v48, v48, v62
	v_mul_f32_e32 v49, v49, v62
	v_mul_f32_e32 v50, v50, v62
	v_mul_f32_e32 v51, v51, v62
	v_mul_f32_e32 v52, v52, v62
	v_mul_f32_e32 v53, v53, v62
	v_max_f32_e32 v46, 0, v46
	v_max_f32_e32 v47, 0, v47
	v_max_f32_e32 v48, 0, v48
	v_max_f32_e32 v49, 0, v49
	v_max_f32_e32 v50, 0, v50
	v_max_f32_e32 v51, 0, v51
	v_max_f32_e32 v52, 0, v52
	v_max_f32_e32 v53, 0, v53
	v_pk_mul_f32 v[46:47], v[46:47], v[46:47]
	v_pk_mul_f32 v[48:49], v[48:49], v[48:49]
	v_pk_mul_f32 v[50:51], v[50:51], v[50:51]
	v_pk_mul_f32 v[52:53], v[52:53], v[52:53]
	v_and_b32_sdwa v196, v46, v205 dst_sel:DWORD dst_unused:UNUSED_PAD src0_sel:WORD_1 src1_sel:DWORD
	v_and_b32_sdwa v197, v47, v205 dst_sel:DWORD dst_unused:UNUSED_PAD src0_sel:WORD_1 src1_sel:DWORD
	v_and_b32_sdwa v198, v48, v205 dst_sel:DWORD dst_unused:UNUSED_PAD src0_sel:WORD_1 src1_sel:DWORD
	v_and_b32_sdwa v199, v49, v205 dst_sel:DWORD dst_unused:UNUSED_PAD src0_sel:WORD_1 src1_sel:DWORD
	v_and_b32_sdwa v200, v50, v205 dst_sel:DWORD dst_unused:UNUSED_PAD src0_sel:WORD_1 src1_sel:DWORD
	v_and_b32_sdwa v201, v51, v205 dst_sel:DWORD dst_unused:UNUSED_PAD src0_sel:WORD_1 src1_sel:DWORD
	v_and_b32_sdwa v202, v52, v205 dst_sel:DWORD dst_unused:UNUSED_PAD src0_sel:WORD_1 src1_sel:DWORD
	v_and_b32_sdwa v203, v53, v205 dst_sel:DWORD dst_unused:UNUSED_PAD src0_sel:WORD_1 src1_sel:DWORD
	v_add3_u32 v46, v46, v196, s22
	v_add3_u32 v47, v47, v197, s22
	v_add3_u32 v48, v48, v198, s22
	v_add3_u32 v49, v49, v199, s22
	v_add3_u32 v50, v50, v200, s22
	v_add3_u32 v51, v51, v201, s22
	v_add3_u32 v52, v52, v202, s22
	v_add3_u32 v53, v53, v203, s22
	v_and_b32_e32 v47, 0xffff0000, v47
	v_and_b32_e32 v49, 0xffff0000, v49
	v_and_b32_e32 v51, 0xffff0000, v51
	v_and_b32_e32 v53, 0xffff0000, v53
	v_or_b32_sdwa v208, v47, v46 dst_sel:DWORD dst_unused:UNUSED_PAD src0_sel:DWORD src1_sel:WORD_1
	v_or_b32_sdwa v209, v49, v48 dst_sel:DWORD dst_unused:UNUSED_PAD src0_sel:DWORD src1_sel:WORD_1
	v_or_b32_sdwa v210, v51, v50 dst_sel:DWORD dst_unused:UNUSED_PAD src0_sel:DWORD src1_sel:WORD_1
	v_or_b32_sdwa v211, v53, v52 dst_sel:DWORD dst_unused:UNUSED_PAD src0_sel:DWORD src1_sel:WORD_1
	global_store_dwordx4 v36, v[208:211], s[56:57]
	v_add_u32_e32 v63, 0x4080, v103
	ds_read2_b32 v[180:181], v63 offset0:0 offset1:1
	ds_read2_b32 v[182:183], v63 offset0:2 offset1:3
	ds_read2_b32 v[184:185], v63 offset0:4 offset1:5
	ds_read2_b32 v[186:187], v63 offset0:6 offset1:7
	v_add_u32_e32 v64, 0x60c0, v103
	ds_read2_b32 v[188:189], v64 offset0:0 offset1:1
	ds_read2_b32 v[190:191], v64 offset0:2 offset1:3
	ds_read2_b32 v[192:193], v64 offset0:4 offset1:5
	ds_read2_b32 v[194:195], v64 offset0:6 offset1:7
	s_waitcnt vmcnt(23) lgkmcnt(8)
	v_fmamk_f32 v62, v38, 0x3a800000, v45
	v_rsq_f32_e32 v62, v62
	v_add_u32_e32 v204, 0x20000, v36
	v_mul_f32_e32 v54, v54, v62
	v_mul_f32_e32 v55, v55, v62
	v_mul_f32_e32 v56, v56, v62
	v_mul_f32_e32 v57, v57, v62
	v_mul_f32_e32 v58, v58, v62
	v_mul_f32_e32 v59, v59, v62
	v_mul_f32_e32 v60, v60, v62
	v_mul_f32_e32 v61, v61, v62
	v_max_f32_e32 v54, 0, v54
	v_max_f32_e32 v55, 0, v55
	v_max_f32_e32 v56, 0, v56
	v_max_f32_e32 v57, 0, v57
	v_max_f32_e32 v58, 0, v58
	v_max_f32_e32 v59, 0, v59
	v_max_f32_e32 v60, 0, v60
	v_max_f32_e32 v61, 0, v61
	v_pk_mul_f32 v[54:55], v[54:55], v[54:55]
	v_pk_mul_f32 v[56:57], v[56:57], v[56:57]
	v_pk_mul_f32 v[58:59], v[58:59], v[58:59]
	v_pk_mul_f32 v[60:61], v[60:61], v[60:61]
	v_and_b32_sdwa v196, v54, v205 dst_sel:DWORD dst_unused:UNUSED_PAD src0_sel:WORD_1 src1_sel:DWORD
	v_and_b32_sdwa v197, v55, v205 dst_sel:DWORD dst_unused:UNUSED_PAD src0_sel:WORD_1 src1_sel:DWORD
	v_and_b32_sdwa v198, v56, v205 dst_sel:DWORD dst_unused:UNUSED_PAD src0_sel:WORD_1 src1_sel:DWORD
	v_and_b32_sdwa v199, v57, v205 dst_sel:DWORD dst_unused:UNUSED_PAD src0_sel:WORD_1 src1_sel:DWORD
	v_and_b32_sdwa v200, v58, v205 dst_sel:DWORD dst_unused:UNUSED_PAD src0_sel:WORD_1 src1_sel:DWORD
	v_and_b32_sdwa v201, v59, v205 dst_sel:DWORD dst_unused:UNUSED_PAD src0_sel:WORD_1 src1_sel:DWORD
	v_and_b32_sdwa v202, v60, v205 dst_sel:DWORD dst_unused:UNUSED_PAD src0_sel:WORD_1 src1_sel:DWORD
	v_and_b32_sdwa v203, v61, v205 dst_sel:DWORD dst_unused:UNUSED_PAD src0_sel:WORD_1 src1_sel:DWORD
	v_add3_u32 v54, v54, v196, s22
	v_add3_u32 v55, v55, v197, s22
	v_add3_u32 v56, v56, v198, s22
	v_add3_u32 v57, v57, v199, s22
	v_add3_u32 v58, v58, v200, s22
	v_add3_u32 v59, v59, v201, s22
	v_add3_u32 v60, v60, v202, s22
	v_add3_u32 v61, v61, v203, s22
	v_and_b32_e32 v55, 0xffff0000, v55
	v_and_b32_e32 v57, 0xffff0000, v57
	v_and_b32_e32 v59, 0xffff0000, v59
	v_and_b32_e32 v61, 0xffff0000, v61
	v_or_b32_sdwa v212, v55, v54 dst_sel:DWORD dst_unused:UNUSED_PAD src0_sel:DWORD src1_sel:WORD_1
	v_or_b32_sdwa v213, v57, v56 dst_sel:DWORD dst_unused:UNUSED_PAD src0_sel:DWORD src1_sel:WORD_1
	v_or_b32_sdwa v214, v59, v58 dst_sel:DWORD dst_unused:UNUSED_PAD src0_sel:DWORD src1_sel:WORD_1
	v_or_b32_sdwa v215, v61, v60 dst_sel:DWORD dst_unused:UNUSED_PAD src0_sel:DWORD src1_sel:WORD_1
	global_store_dwordx4 v204, v[212:215], s[56:57]
	s_waitcnt vmcnt(23) lgkmcnt(4)
	v_fmamk_f32 v62, v39, 0x3a800000, v45
	v_rsq_f32_e32 v62, v62
	v_add_u32_e32 v65, 0x40000, v36
	v_mul_f32_e32 v180, v180, v62
	v_mul_f32_e32 v181, v181, v62
	v_mul_f32_e32 v182, v182, v62
	v_mul_f32_e32 v183, v183, v62
	v_mul_f32_e32 v184, v184, v62
	v_mul_f32_e32 v185, v185, v62
	v_mul_f32_e32 v186, v186, v62
	v_mul_f32_e32 v187, v187, v62
	v_max_f32_e32 v180, 0, v180
	v_max_f32_e32 v181, 0, v181
	v_max_f32_e32 v182, 0, v182
	v_max_f32_e32 v183, 0, v183
	v_max_f32_e32 v184, 0, v184
	v_max_f32_e32 v185, 0, v185
	v_max_f32_e32 v186, 0, v186
	v_max_f32_e32 v187, 0, v187
	v_pk_mul_f32 v[180:181], v[180:181], v[180:181]
	v_pk_mul_f32 v[182:183], v[182:183], v[182:183]
	v_pk_mul_f32 v[184:185], v[184:185], v[184:185]
	v_pk_mul_f32 v[186:187], v[186:187], v[186:187]
	v_and_b32_sdwa v196, v180, v205 dst_sel:DWORD dst_unused:UNUSED_PAD src0_sel:WORD_1 src1_sel:DWORD
	v_and_b32_sdwa v197, v181, v205 dst_sel:DWORD dst_unused:UNUSED_PAD src0_sel:WORD_1 src1_sel:DWORD
	v_and_b32_sdwa v198, v182, v205 dst_sel:DWORD dst_unused:UNUSED_PAD src0_sel:WORD_1 src1_sel:DWORD
	v_and_b32_sdwa v199, v183, v205 dst_sel:DWORD dst_unused:UNUSED_PAD src0_sel:WORD_1 src1_sel:DWORD
	v_and_b32_sdwa v200, v184, v205 dst_sel:DWORD dst_unused:UNUSED_PAD src0_sel:WORD_1 src1_sel:DWORD
	v_and_b32_sdwa v201, v185, v205 dst_sel:DWORD dst_unused:UNUSED_PAD src0_sel:WORD_1 src1_sel:DWORD
	v_and_b32_sdwa v202, v186, v205 dst_sel:DWORD dst_unused:UNUSED_PAD src0_sel:WORD_1 src1_sel:DWORD
	v_and_b32_sdwa v203, v187, v205 dst_sel:DWORD dst_unused:UNUSED_PAD src0_sel:WORD_1 src1_sel:DWORD
	v_add3_u32 v180, v180, v196, s22
	v_add3_u32 v181, v181, v197, s22
	v_add3_u32 v182, v182, v198, s22
	v_add3_u32 v183, v183, v199, s22
	v_add3_u32 v184, v184, v200, s22
	v_add3_u32 v185, v185, v201, s22
	v_add3_u32 v186, v186, v202, s22
	v_add3_u32 v187, v187, v203, s22
	v_and_b32_e32 v181, 0xffff0000, v181
	v_and_b32_e32 v183, 0xffff0000, v183
	v_and_b32_e32 v185, 0xffff0000, v185
	v_and_b32_e32 v187, 0xffff0000, v187
	v_or_b32_sdwa v208, v181, v180 dst_sel:DWORD dst_unused:UNUSED_PAD src0_sel:DWORD src1_sel:WORD_1
	v_or_b32_sdwa v209, v183, v182 dst_sel:DWORD dst_unused:UNUSED_PAD src0_sel:DWORD src1_sel:WORD_1
	v_or_b32_sdwa v210, v185, v184 dst_sel:DWORD dst_unused:UNUSED_PAD src0_sel:DWORD src1_sel:WORD_1
	v_or_b32_sdwa v211, v187, v186 dst_sel:DWORD dst_unused:UNUSED_PAD src0_sel:DWORD src1_sel:WORD_1
	global_store_dwordx4 v65, v[208:211], s[56:57]
	v_add_u32_e32 v63, 0x8100, v103
	ds_read2_b32 v[46:47], v63 offset0:0 offset1:1
	ds_read2_b32 v[48:49], v63 offset0:2 offset1:3
	ds_read2_b32 v[50:51], v63 offset0:4 offset1:5
	ds_read2_b32 v[52:53], v63 offset0:6 offset1:7
	v_add_u32_e32 v64, 0xa140, v103
	ds_read2_b32 v[54:55], v64 offset0:0 offset1:1
	ds_read2_b32 v[56:57], v64 offset0:2 offset1:3
	ds_read2_b32 v[58:59], v64 offset0:4 offset1:5
	ds_read2_b32 v[60:61], v64 offset0:6 offset1:7
	s_waitcnt vmcnt(23) lgkmcnt(8)
	v_fmamk_f32 v62, v40, 0x3a800000, v45
	v_rsq_f32_e32 v62, v62
	v_add_u32_e32 v204, 0x60000, v36
	v_mul_f32_e32 v188, v188, v62
	v_mul_f32_e32 v189, v189, v62
	v_mul_f32_e32 v190, v190, v62
	v_mul_f32_e32 v191, v191, v62
	v_mul_f32_e32 v192, v192, v62
	v_mul_f32_e32 v193, v193, v62
	v_mul_f32_e32 v194, v194, v62
	v_mul_f32_e32 v195, v195, v62
	v_max_f32_e32 v188, 0, v188
	v_max_f32_e32 v189, 0, v189
	v_max_f32_e32 v190, 0, v190
	v_max_f32_e32 v191, 0, v191
	v_max_f32_e32 v192, 0, v192
	v_max_f32_e32 v193, 0, v193
	v_max_f32_e32 v194, 0, v194
	v_max_f32_e32 v195, 0, v195
	v_pk_mul_f32 v[188:189], v[188:189], v[188:189]
	v_pk_mul_f32 v[190:191], v[190:191], v[190:191]
	v_pk_mul_f32 v[192:193], v[192:193], v[192:193]
	v_pk_mul_f32 v[194:195], v[194:195], v[194:195]
	v_and_b32_sdwa v196, v188, v205 dst_sel:DWORD dst_unused:UNUSED_PAD src0_sel:WORD_1 src1_sel:DWORD
	v_and_b32_sdwa v197, v189, v205 dst_sel:DWORD dst_unused:UNUSED_PAD src0_sel:WORD_1 src1_sel:DWORD
	v_and_b32_sdwa v198, v190, v205 dst_sel:DWORD dst_unused:UNUSED_PAD src0_sel:WORD_1 src1_sel:DWORD
	v_and_b32_sdwa v199, v191, v205 dst_sel:DWORD dst_unused:UNUSED_PAD src0_sel:WORD_1 src1_sel:DWORD
	v_and_b32_sdwa v200, v192, v205 dst_sel:DWORD dst_unused:UNUSED_PAD src0_sel:WORD_1 src1_sel:DWORD
	v_and_b32_sdwa v201, v193, v205 dst_sel:DWORD dst_unused:UNUSED_PAD src0_sel:WORD_1 src1_sel:DWORD
	v_and_b32_sdwa v202, v194, v205 dst_sel:DWORD dst_unused:UNUSED_PAD src0_sel:WORD_1 src1_sel:DWORD
	v_and_b32_sdwa v203, v195, v205 dst_sel:DWORD dst_unused:UNUSED_PAD src0_sel:WORD_1 src1_sel:DWORD
	v_add3_u32 v188, v188, v196, s22
	v_add3_u32 v189, v189, v197, s22
	v_add3_u32 v190, v190, v198, s22
	v_add3_u32 v191, v191, v199, s22
	v_add3_u32 v192, v192, v200, s22
	v_add3_u32 v193, v193, v201, s22
	v_add3_u32 v194, v194, v202, s22
	v_add3_u32 v195, v195, v203, s22
	v_and_b32_e32 v189, 0xffff0000, v189
	v_and_b32_e32 v191, 0xffff0000, v191
	v_and_b32_e32 v193, 0xffff0000, v193
	v_and_b32_e32 v195, 0xffff0000, v195
	v_or_b32_sdwa v212, v189, v188 dst_sel:DWORD dst_unused:UNUSED_PAD src0_sel:DWORD src1_sel:WORD_1
	v_or_b32_sdwa v213, v191, v190 dst_sel:DWORD dst_unused:UNUSED_PAD src0_sel:DWORD src1_sel:WORD_1
	v_or_b32_sdwa v214, v193, v192 dst_sel:DWORD dst_unused:UNUSED_PAD src0_sel:DWORD src1_sel:WORD_1
	v_or_b32_sdwa v215, v195, v194 dst_sel:DWORD dst_unused:UNUSED_PAD src0_sel:DWORD src1_sel:WORD_1
	global_store_dwordx4 v204, v[212:215], s[56:57]
	s_waitcnt vmcnt(23) lgkmcnt(4)
	v_fmamk_f32 v62, v41, 0x3a800000, v45
	v_rsq_f32_e32 v62, v62
	v_add_u32_e32 v65, 0x80000, v36
	v_mul_f32_e32 v46, v46, v62
	v_mul_f32_e32 v47, v47, v62
	v_mul_f32_e32 v48, v48, v62
	v_mul_f32_e32 v49, v49, v62
	v_mul_f32_e32 v50, v50, v62
	v_mul_f32_e32 v51, v51, v62
	v_mul_f32_e32 v52, v52, v62
	v_mul_f32_e32 v53, v53, v62
	v_max_f32_e32 v46, 0, v46
	v_max_f32_e32 v47, 0, v47
	v_max_f32_e32 v48, 0, v48
	v_max_f32_e32 v49, 0, v49
	v_max_f32_e32 v50, 0, v50
	v_max_f32_e32 v51, 0, v51
	v_max_f32_e32 v52, 0, v52
	v_max_f32_e32 v53, 0, v53
	v_pk_mul_f32 v[46:47], v[46:47], v[46:47]
	v_pk_mul_f32 v[48:49], v[48:49], v[48:49]
	v_pk_mul_f32 v[50:51], v[50:51], v[50:51]
	v_pk_mul_f32 v[52:53], v[52:53], v[52:53]
	v_and_b32_sdwa v196, v46, v205 dst_sel:DWORD dst_unused:UNUSED_PAD src0_sel:WORD_1 src1_sel:DWORD
	v_and_b32_sdwa v197, v47, v205 dst_sel:DWORD dst_unused:UNUSED_PAD src0_sel:WORD_1 src1_sel:DWORD
	v_and_b32_sdwa v198, v48, v205 dst_sel:DWORD dst_unused:UNUSED_PAD src0_sel:WORD_1 src1_sel:DWORD
	v_and_b32_sdwa v199, v49, v205 dst_sel:DWORD dst_unused:UNUSED_PAD src0_sel:WORD_1 src1_sel:DWORD
	v_and_b32_sdwa v200, v50, v205 dst_sel:DWORD dst_unused:UNUSED_PAD src0_sel:WORD_1 src1_sel:DWORD
	v_and_b32_sdwa v201, v51, v205 dst_sel:DWORD dst_unused:UNUSED_PAD src0_sel:WORD_1 src1_sel:DWORD
	v_and_b32_sdwa v202, v52, v205 dst_sel:DWORD dst_unused:UNUSED_PAD src0_sel:WORD_1 src1_sel:DWORD
	v_and_b32_sdwa v203, v53, v205 dst_sel:DWORD dst_unused:UNUSED_PAD src0_sel:WORD_1 src1_sel:DWORD
	v_add3_u32 v46, v46, v196, s22
	v_add3_u32 v47, v47, v197, s22
	v_add3_u32 v48, v48, v198, s22
	v_add3_u32 v49, v49, v199, s22
	v_add3_u32 v50, v50, v200, s22
	v_add3_u32 v51, v51, v201, s22
	v_add3_u32 v52, v52, v202, s22
	v_add3_u32 v53, v53, v203, s22
	v_and_b32_e32 v47, 0xffff0000, v47
	v_and_b32_e32 v49, 0xffff0000, v49
	v_and_b32_e32 v51, 0xffff0000, v51
	v_and_b32_e32 v53, 0xffff0000, v53
	v_or_b32_sdwa v208, v47, v46 dst_sel:DWORD dst_unused:UNUSED_PAD src0_sel:DWORD src1_sel:WORD_1
	v_or_b32_sdwa v209, v49, v48 dst_sel:DWORD dst_unused:UNUSED_PAD src0_sel:DWORD src1_sel:WORD_1
	v_or_b32_sdwa v210, v51, v50 dst_sel:DWORD dst_unused:UNUSED_PAD src0_sel:DWORD src1_sel:WORD_1
	v_or_b32_sdwa v211, v53, v52 dst_sel:DWORD dst_unused:UNUSED_PAD src0_sel:DWORD src1_sel:WORD_1
	global_store_dwordx4 v65, v[208:211], s[56:57]
	v_add_u32_e32 v63, 0xc180, v103
	ds_read2_b32 v[180:181], v63 offset0:0 offset1:1
	ds_read2_b32 v[182:183], v63 offset0:2 offset1:3
	ds_read2_b32 v[184:185], v63 offset0:4 offset1:5
	ds_read2_b32 v[186:187], v63 offset0:6 offset1:7
	v_add_u32_e32 v64, 0xe1c0, v103
	ds_read2_b32 v[188:189], v64 offset0:0 offset1:1
	ds_read2_b32 v[190:191], v64 offset0:2 offset1:3
	ds_read2_b32 v[192:193], v64 offset0:4 offset1:5
	ds_read2_b32 v[194:195], v64 offset0:6 offset1:7
	s_waitcnt vmcnt(23) lgkmcnt(8)
	v_fmamk_f32 v62, v42, 0x3a800000, v45
	v_rsq_f32_e32 v62, v62
	v_add_u32_e32 v204, 0xa0000, v36
	v_mul_f32_e32 v54, v54, v62
	v_mul_f32_e32 v55, v55, v62
	v_mul_f32_e32 v56, v56, v62
	v_mul_f32_e32 v57, v57, v62
	v_mul_f32_e32 v58, v58, v62
	v_mul_f32_e32 v59, v59, v62
	v_mul_f32_e32 v60, v60, v62
	v_mul_f32_e32 v61, v61, v62
	v_max_f32_e32 v54, 0, v54
	v_max_f32_e32 v55, 0, v55
	v_max_f32_e32 v56, 0, v56
	v_max_f32_e32 v57, 0, v57
	v_max_f32_e32 v58, 0, v58
	v_max_f32_e32 v59, 0, v59
	v_max_f32_e32 v60, 0, v60
	v_max_f32_e32 v61, 0, v61
	v_pk_mul_f32 v[54:55], v[54:55], v[54:55]
	v_pk_mul_f32 v[56:57], v[56:57], v[56:57]
	v_pk_mul_f32 v[58:59], v[58:59], v[58:59]
	v_pk_mul_f32 v[60:61], v[60:61], v[60:61]
	v_and_b32_sdwa v196, v54, v205 dst_sel:DWORD dst_unused:UNUSED_PAD src0_sel:WORD_1 src1_sel:DWORD
	v_and_b32_sdwa v197, v55, v205 dst_sel:DWORD dst_unused:UNUSED_PAD src0_sel:WORD_1 src1_sel:DWORD
	v_and_b32_sdwa v198, v56, v205 dst_sel:DWORD dst_unused:UNUSED_PAD src0_sel:WORD_1 src1_sel:DWORD
	v_and_b32_sdwa v199, v57, v205 dst_sel:DWORD dst_unused:UNUSED_PAD src0_sel:WORD_1 src1_sel:DWORD
	v_and_b32_sdwa v200, v58, v205 dst_sel:DWORD dst_unused:UNUSED_PAD src0_sel:WORD_1 src1_sel:DWORD
	v_and_b32_sdwa v201, v59, v205 dst_sel:DWORD dst_unused:UNUSED_PAD src0_sel:WORD_1 src1_sel:DWORD
	v_and_b32_sdwa v202, v60, v205 dst_sel:DWORD dst_unused:UNUSED_PAD src0_sel:WORD_1 src1_sel:DWORD
	v_and_b32_sdwa v203, v61, v205 dst_sel:DWORD dst_unused:UNUSED_PAD src0_sel:WORD_1 src1_sel:DWORD
	v_add3_u32 v54, v54, v196, s22
	v_add3_u32 v55, v55, v197, s22
	v_add3_u32 v56, v56, v198, s22
	v_add3_u32 v57, v57, v199, s22
	v_add3_u32 v58, v58, v200, s22
	v_add3_u32 v59, v59, v201, s22
	v_add3_u32 v60, v60, v202, s22
	v_add3_u32 v61, v61, v203, s22
	v_and_b32_e32 v55, 0xffff0000, v55
	v_and_b32_e32 v57, 0xffff0000, v57
	v_and_b32_e32 v59, 0xffff0000, v59
	v_and_b32_e32 v61, 0xffff0000, v61
	v_or_b32_sdwa v212, v55, v54 dst_sel:DWORD dst_unused:UNUSED_PAD src0_sel:DWORD src1_sel:WORD_1
	v_or_b32_sdwa v213, v57, v56 dst_sel:DWORD dst_unused:UNUSED_PAD src0_sel:DWORD src1_sel:WORD_1
	v_or_b32_sdwa v214, v59, v58 dst_sel:DWORD dst_unused:UNUSED_PAD src0_sel:DWORD src1_sel:WORD_1
	v_or_b32_sdwa v215, v61, v60 dst_sel:DWORD dst_unused:UNUSED_PAD src0_sel:DWORD src1_sel:WORD_1
	global_store_dwordx4 v204, v[212:215], s[56:57]
	s_waitcnt vmcnt(23) lgkmcnt(4)
	v_fmamk_f32 v62, v43, 0x3a800000, v45
	v_rsq_f32_e32 v62, v62
	v_add_u32_e32 v65, 0xc0000, v36
	v_mul_f32_e32 v180, v180, v62
	v_mul_f32_e32 v181, v181, v62
	v_mul_f32_e32 v182, v182, v62
	v_mul_f32_e32 v183, v183, v62
	v_mul_f32_e32 v184, v184, v62
	v_mul_f32_e32 v185, v185, v62
	v_mul_f32_e32 v186, v186, v62
	v_mul_f32_e32 v187, v187, v62
	v_max_f32_e32 v180, 0, v180
	v_max_f32_e32 v181, 0, v181
	v_max_f32_e32 v182, 0, v182
	v_max_f32_e32 v183, 0, v183
	v_max_f32_e32 v184, 0, v184
	v_max_f32_e32 v185, 0, v185
	v_max_f32_e32 v186, 0, v186
	v_max_f32_e32 v187, 0, v187
	v_pk_mul_f32 v[180:181], v[180:181], v[180:181]
	v_pk_mul_f32 v[182:183], v[182:183], v[182:183]
	v_pk_mul_f32 v[184:185], v[184:185], v[184:185]
	v_pk_mul_f32 v[186:187], v[186:187], v[186:187]
	v_and_b32_sdwa v196, v180, v205 dst_sel:DWORD dst_unused:UNUSED_PAD src0_sel:WORD_1 src1_sel:DWORD
	v_and_b32_sdwa v197, v181, v205 dst_sel:DWORD dst_unused:UNUSED_PAD src0_sel:WORD_1 src1_sel:DWORD
	v_and_b32_sdwa v198, v182, v205 dst_sel:DWORD dst_unused:UNUSED_PAD src0_sel:WORD_1 src1_sel:DWORD
	v_and_b32_sdwa v199, v183, v205 dst_sel:DWORD dst_unused:UNUSED_PAD src0_sel:WORD_1 src1_sel:DWORD
	v_and_b32_sdwa v200, v184, v205 dst_sel:DWORD dst_unused:UNUSED_PAD src0_sel:WORD_1 src1_sel:DWORD
	v_and_b32_sdwa v201, v185, v205 dst_sel:DWORD dst_unused:UNUSED_PAD src0_sel:WORD_1 src1_sel:DWORD
	v_and_b32_sdwa v202, v186, v205 dst_sel:DWORD dst_unused:UNUSED_PAD src0_sel:WORD_1 src1_sel:DWORD
	v_and_b32_sdwa v203, v187, v205 dst_sel:DWORD dst_unused:UNUSED_PAD src0_sel:WORD_1 src1_sel:DWORD
	v_add3_u32 v180, v180, v196, s22
	v_add3_u32 v181, v181, v197, s22
	v_add3_u32 v182, v182, v198, s22
	v_add3_u32 v183, v183, v199, s22
	v_add3_u32 v184, v184, v200, s22
	v_add3_u32 v185, v185, v201, s22
	v_add3_u32 v186, v186, v202, s22
	v_add3_u32 v187, v187, v203, s22
	v_and_b32_e32 v181, 0xffff0000, v181
	v_and_b32_e32 v183, 0xffff0000, v183
	v_and_b32_e32 v185, 0xffff0000, v185
	v_and_b32_e32 v187, 0xffff0000, v187
	v_or_b32_sdwa v208, v181, v180 dst_sel:DWORD dst_unused:UNUSED_PAD src0_sel:DWORD src1_sel:WORD_1
	v_or_b32_sdwa v209, v183, v182 dst_sel:DWORD dst_unused:UNUSED_PAD src0_sel:DWORD src1_sel:WORD_1
	v_or_b32_sdwa v210, v185, v184 dst_sel:DWORD dst_unused:UNUSED_PAD src0_sel:DWORD src1_sel:WORD_1
	v_or_b32_sdwa v211, v187, v186 dst_sel:DWORD dst_unused:UNUSED_PAD src0_sel:DWORD src1_sel:WORD_1
	global_store_dwordx4 v65, v[208:211], s[56:57]
	s_waitcnt vmcnt(23) lgkmcnt(0)
	v_fmamk_f32 v62, v44, 0x3a800000, v45
	v_rsq_f32_e32 v62, v62
	v_add_u32_e32 v204, 0xe0000, v36
	v_mul_f32_e32 v188, v188, v62
	v_mul_f32_e32 v189, v189, v62
	v_mul_f32_e32 v190, v190, v62
	v_mul_f32_e32 v191, v191, v62
	v_mul_f32_e32 v192, v192, v62
	v_mul_f32_e32 v193, v193, v62
	v_mul_f32_e32 v194, v194, v62
	v_mul_f32_e32 v195, v195, v62
	v_max_f32_e32 v188, 0, v188
	v_max_f32_e32 v189, 0, v189
	v_max_f32_e32 v190, 0, v190
	v_max_f32_e32 v191, 0, v191
	v_max_f32_e32 v192, 0, v192
	v_max_f32_e32 v193, 0, v193
	v_max_f32_e32 v194, 0, v194
	v_max_f32_e32 v195, 0, v195
	v_pk_mul_f32 v[188:189], v[188:189], v[188:189]
	v_pk_mul_f32 v[190:191], v[190:191], v[190:191]
	v_pk_mul_f32 v[192:193], v[192:193], v[192:193]
	v_pk_mul_f32 v[194:195], v[194:195], v[194:195]
	v_and_b32_sdwa v196, v188, v205 dst_sel:DWORD dst_unused:UNUSED_PAD src0_sel:WORD_1 src1_sel:DWORD
	v_and_b32_sdwa v197, v189, v205 dst_sel:DWORD dst_unused:UNUSED_PAD src0_sel:WORD_1 src1_sel:DWORD
	v_and_b32_sdwa v198, v190, v205 dst_sel:DWORD dst_unused:UNUSED_PAD src0_sel:WORD_1 src1_sel:DWORD
	v_and_b32_sdwa v199, v191, v205 dst_sel:DWORD dst_unused:UNUSED_PAD src0_sel:WORD_1 src1_sel:DWORD
	v_and_b32_sdwa v200, v192, v205 dst_sel:DWORD dst_unused:UNUSED_PAD src0_sel:WORD_1 src1_sel:DWORD
	v_and_b32_sdwa v201, v193, v205 dst_sel:DWORD dst_unused:UNUSED_PAD src0_sel:WORD_1 src1_sel:DWORD
	v_and_b32_sdwa v202, v194, v205 dst_sel:DWORD dst_unused:UNUSED_PAD src0_sel:WORD_1 src1_sel:DWORD
	v_and_b32_sdwa v203, v195, v205 dst_sel:DWORD dst_unused:UNUSED_PAD src0_sel:WORD_1 src1_sel:DWORD
	v_add3_u32 v188, v188, v196, s22
	v_add3_u32 v189, v189, v197, s22
	v_add3_u32 v190, v190, v198, s22
	v_add3_u32 v191, v191, v199, s22
	v_add3_u32 v192, v192, v200, s22
	v_add3_u32 v193, v193, v201, s22
	v_add3_u32 v194, v194, v202, s22
	v_add3_u32 v195, v195, v203, s22
	v_and_b32_e32 v189, 0xffff0000, v189
	v_and_b32_e32 v191, 0xffff0000, v191
	v_and_b32_e32 v193, 0xffff0000, v193
	v_and_b32_e32 v195, 0xffff0000, v195
	v_or_b32_sdwa v212, v189, v188 dst_sel:DWORD dst_unused:UNUSED_PAD src0_sel:DWORD src1_sel:WORD_1
	v_or_b32_sdwa v213, v191, v190 dst_sel:DWORD dst_unused:UNUSED_PAD src0_sel:DWORD src1_sel:WORD_1
	v_or_b32_sdwa v214, v193, v192 dst_sel:DWORD dst_unused:UNUSED_PAD src0_sel:DWORD src1_sel:WORD_1
	v_or_b32_sdwa v215, v195, v194 dst_sel:DWORD dst_unused:UNUSED_PAD src0_sel:DWORD src1_sel:WORD_1
	global_store_dwordx4 v204, v[212:215], s[56:57]
	s_cmpk_lt_u32 s13, 0x400
	s_barrier
	s_cbranch_scc1 .LBB0_338
	s_waitcnt vmcnt(0)

.LBB0_588:
	s_cmpk_gt_u32 s2, 0x1fff
	v_readfirstlane_b32 s8, v2
	s_cbranch_scc1 .LBB0_591
	s_add_u32 s6, s82, 0xaea0000
	s_addc_u32 s7, s83, 0
	s_bfe_u32 s11, s8, 0x10006
	s_lshr_b32 s8, s8, 1
	v_bfe_u32 v3, v2, 5, 1
	v_and_b32_e32 v5, 31, v2
	s_and_b32 s14, s8, 0x7fffffc0
	v_lshrrev_b32_e32 v7, 3, v2
	v_or_b32_e32 v9, s14, v5
	v_lshlrev_b32_e32 v6, 4, v3
	s_movk_i32 s15, 0x90
	s_load_dword s10, s[0:1], 0x1b8
	v_mad_u64_u32 v[66:67], s[8:9], v9, s15, v[6:7]
	v_lshl_or_b32 v3, v3, 2, s14
	s_movk_i32 s8, 0x204
	v_lshlrev_b32_e32 v8, 3, v2
	v_lshl_or_b32 v9, s11, 6, v5
	v_mul_lo_u32 v3, v3, s8
	s_lshl_b32 s8, s11, 8
	v_lshlrev_b32_e32 v5, 2, v5
	v_lshlrev_b32_e32 v4, 4, v2
	v_add3_u32 v93, s8, v3, v5
	v_lshrrev_b32_e32 v94, 4, v2
	v_and_b32_e32 v2, 0x78, v8
	v_mov_b32_e32 v69, 0
	v_lshlrev_b32_e32 v68, 11, v7
	v_readlane_b32 s8, v252, 6
	v_mul_u32_u24_e32 v1, 0x48, v7
	v_and_b32_e32 v4, 0x70, v4
	v_mad_u32_u24 v67, v9, s15, v6
	v_lshlrev_b32_e32 v3, 2, v2
	v_mul_u32_u24_e32 v8, 0x204, v94
	v_lshl_add_u64 v[6:7], s[92:93], 0, v[68:69]
	v_mov_b32_e32 v5, v69
	v_readlane_b32 s9, v252, 7
	s_lshr_b32 s12, s2, 3
	s_waitcnt lgkmcnt(0)
	s_lshr_b32 s13, s10, 3
	v_lshl_add_u32 v1, v1, 1, v4
	v_lshl_add_u64 v[70:71], v[6:7], 0, v[4:5]
	v_lshl_add_u64 v[6:7], s[8:9], 0, v[68:69]
	v_add_u32_e32 v103, v3, v8
	s_and_b32 s3, s2, 7
	v_add_u32_e32 v92, 0x9000, v1
	v_add_u32_e32 v95, 16, v94
	v_add_u32_e32 v96, 32, v94
	v_add_u32_e32 v97, 48, v94
	v_or_b32_e32 v98, 64, v94
	v_add_u32_e32 v99, 0x50, v94
	v_add_u32_e32 v100, 0x60, v94
	v_add_u32_e32 v101, 0x70, v94
	v_lshl_add_u64 v[72:73], v[6:7], 0, v[4:5]
	s_lshl_b32 s14, s12, 4
	s_lshl_b32 s15, s13, 4
	s_and_b32 s16, s2, -8
	s_and_b32 s17, s10, -8
	s_mov_b32 s9, 0
	s_mov_b32 s18, 0x10000
	s_mov_b32 s19, 0x20000
	s_mov_b32 s20, 0x30000
	v_mov_b32_e32 v102, 0x358637bd
	s_mov_b32 s21, 0x800000
	v_lshlrev_b32_e32 v74, 1, v2
	v_mov_b32_e32 v75, v69
	s_movk_i32 s22, 0x7fff
	v_add_u32_e32 v104, 0x2040, v103
	v_add_u32_e32 v105, 0x2048, v103
	v_add_u32_e32 v106, 0x2050, v103
	v_add_u32_e32 v107, 0x2058, v103
	v_add_u32_e32 v108, 0x4080, v103
	v_add_u32_e32 v109, 0x4088, v103
	v_add_u32_e32 v110, 0x4090, v103
	v_add_u32_e32 v111, 0x4098, v103
	v_add_u32_e32 v112, 0x60c0, v103
	v_add_u32_e32 v113, 0x60c8, v103
	v_add_u32_e32 v114, 0x60d0, v103
	v_add_u32_e32 v115, 0x60d8, v103
	v_add_u32_e32 v116, 0x8100, v103
	v_add_u32_e32 v117, 0x8108, v103
	v_add_u32_e32 v118, 0x8110, v103
	v_add_u32_e32 v119, 0x8118, v103
	v_add_u32_e32 v120, 0xa140, v103
	v_add_u32_e32 v121, 0xa148, v103
	v_add_u32_e32 v122, 0xa150, v103
	v_add_u32_e32 v123, 0xa158, v103
	v_add_u32_e32 v124, 0xc180, v103
	v_add_u32_e32 v125, 0xc188, v103
	v_add_u32_e32 v126, 0xc190, v103
	v_add_u32_e32 v127, 0xc198, v103
	v_add_u32_e32 v128, 0xe1c0, v103
	v_add_u32_e32 v129, 0xe1c8, v103
	v_add_u32_e32 v130, 0xe1d0, v103
	v_add_u32_e32 v131, 0xe1d8, v103
	v_add_u32_e32 v132, 0x4000, v93
	v_add_u32_e32 v133, 0x400, v93
	v_add_u32_e32 v134, 0x4400, v93
	v_add_u32_e32 v135, 0x1000, v93
	v_add_u32_e32 v136, 0x5000, v93
	v_add_u32_e32 v137, 0x1400, v93
	v_add_u32_e32 v138, 0x5400, v93
	v_add_u32_e32 v139, 0x2000, v93
	v_add_u32_e32 v140, 0x6000, v93
	v_add_u32_e32 v141, 0x2400, v93
	v_add_u32_e32 v142, 0x6400, v93
	v_add_u32_e32 v143, 0x3000, v93
	v_add_u32_e32 v144, 0x7000, v93
	v_add_u32_e32 v145, 0x3400, v93
	v_add_u32_e32 v146, 0x7400, v93
	v_mov_b32_e32 v147, 1
	s_lshr_b32 s8, s12, 2
	s_and_b32 s10, s16, 56
	s_and_b32 s8, s8, 0x1ffffc0
	s_or_b32 s10, s10, s3
	s_or_b32 s8, s10, s8
	s_lshl_b32 s8, s8, 7
	s_lshl_b64 s[24:25], s[8:9], 11
	v_lshl_add_u64 v[78:79], v[70:71], 0, s[24:25]
	v_add_co_u32_e32 v80, vcc, s18, v78
	s_and_b32 s10, s14, 0xf80
	s_nop 0
	v_addc_co_u32_e32 v81, vcc, 0, v79, vcc
	s_lshl_b32 s26, s10, 11
	s_mov_b32 s27, s9
	v_add_co_u32_e32 v82, vcc, s19, v78
	v_lshl_add_u64 v[76:77], v[72:73], 0, s[26:27]
	s_nop 0
	v_addc_co_u32_e32 v83, vcc, 0, v79, vcc
	v_add_co_u32_e32 v84, vcc, s18, v76
	global_load_dwordx4 v[2:5], v[78:79], off
	global_load_dwordx4 v[6:9], v[80:81], off
	v_addc_co_u32_e32 v85, vcc, 0, v77, vcc
	v_add_co_u32_e32 v86, vcc, s19, v76
	global_load_dwordx4 v[10:13], v[82:83], off
	global_load_dwordx4 v[14:17], v[76:77], off
	v_addc_co_u32_e32 v87, vcc, 0, v77, vcc
	global_load_dwordx4 v[18:21], v[84:85], off
	global_load_dwordx4 v[22:25], v[86:87], off
	v_add_co_u32_e32 v88, vcc, s20, v76
	s_nop 1
	v_addc_co_u32_e32 v89, vcc, 0, v77, vcc
	global_load_dwordx4 v[26:29], v[88:89], off
	v_add_co_u32_e32 v90, vcc, s20, v78
	s_nop 1
	v_addc_co_u32_e32 v91, vcc, 0, v79, vcc
	global_load_dwordx4 v[30:33], v[90:91], off
	global_load_dwordx4 v[148:151], v[76:77], off offset:128
	global_load_dwordx4 v[152:155], v[84:85], off offset:128
	global_load_dwordx4 v[156:159], v[86:87], off offset:128
	global_load_dwordx4 v[160:163], v[88:89], off offset:128
	global_load_dwordx4 v[164:167], v[78:79], off offset:128
	global_load_dwordx4 v[168:171], v[80:81], off offset:128
	global_load_dwordx4 v[172:175], v[82:83], off offset:128
	global_load_dwordx4 v[176:179], v[90:91], off offset:128
.LBB0_590:
	s_waitcnt vmcnt(12)
	ds_write_b128 v1, v[14:17] offset:36864
	s_waitcnt vmcnt(11)
	ds_write_b128 v1, v[18:21] offset:41472
	s_waitcnt vmcnt(10)
	ds_write_b128 v1, v[22:25] offset:46080
	s_waitcnt vmcnt(9)
	ds_write_b128 v1, v[26:29] offset:50688
	ds_write_b128 v1, v[2:5]
	ds_write_b128 v1, v[6:9] offset:4608
	ds_write_b128 v1, v[10:13] offset:9216
	s_waitcnt vmcnt(8)
	ds_write_b128 v1, v[30:33] offset:13824
	s_waitcnt lgkmcnt(0)
	s_barrier
	global_load_dwordx4 v[180:183], v[80:81], off offset:256
	global_load_dwordx4 v[184:187], v[82:83], off offset:256
	global_load_dwordx4 v[188:191], v[78:79], off offset:256
	global_load_dwordx4 v[192:195], v[76:77], off offset:256
	global_load_dwordx4 v[196:199], v[90:91], off offset:256
	global_load_dwordx4 v[200:203], v[84:85], off offset:256
	global_load_dwordx4 v[204:207], v[86:87], off offset:256
	global_load_dwordx4 v[208:211], v[88:89], off offset:256
	ds_read_b128 v[18:21], v66
	ds_read_b128 v[34:37], v67 offset:36864
	ds_read_b128 v[212:215], v66 offset:32
	ds_read_b128 v[216:219], v67 offset:36896
	ds_read_b128 v[50:53], v67 offset:41472
	ds_read_b128 v[220:223], v67 offset:41504
	ds_read_b128 v[54:57], v66 offset:4608
	ds_read_b128 v[224:227], v66 offset:4640
	s_waitcnt lgkmcnt(6)
	v_mfma_f32_32x32x16_bf16 v[2:17], v[18:21], v[34:37], 0
	s_waitcnt lgkmcnt(3)
	v_mfma_f32_32x32x16_bf16 v[18:33], v[18:21], v[50:53], 0
	s_waitcnt lgkmcnt(1)
	v_mfma_f32_32x32x16_bf16 v[34:49], v[54:57], v[34:37], 0
	v_mfma_f32_32x32x16_bf16 v[50:65], v[54:57], v[50:53], 0
	v_mfma_f32_32x32x16_bf16 v[2:17], v[212:215], v[216:219], v[2:17]
	v_mfma_f32_32x32x16_bf16 v[18:33], v[212:215], v[220:223], v[18:33]
	s_waitcnt lgkmcnt(0)
	v_mfma_f32_32x32x16_bf16 v[34:49], v[224:227], v[216:219], v[34:49]
	v_mfma_f32_32x32x16_bf16 v[50:65], v[224:227], v[220:223], v[50:65]
	ds_read_b128 v[212:215], v66 offset:64
	ds_read_b128 v[216:219], v67 offset:36928
	ds_read_b128 v[220:223], v66 offset:96
	ds_read_b128 v[224:227], v67 offset:36960
	ds_read_b128 v[228:231], v67 offset:41536
	ds_read_b128 v[232:235], v67 offset:41568
	s_waitcnt lgkmcnt(4)
	v_mfma_f32_32x32x16_bf16 v[2:17], v[212:215], v[216:219], v[2:17]
	s_waitcnt lgkmcnt(1)
	v_mfma_f32_32x32x16_bf16 v[18:33], v[212:215], v[228:231], v[18:33]
	ds_read_b128 v[212:215], v66 offset:4672
	ds_read_b128 v[236:239], v66 offset:4704
	s_waitcnt vmcnt(11)
	ds_write_b128 v1, v[164:167] offset:18432
	s_waitcnt vmcnt(10)
	ds_write_b128 v1, v[168:171] offset:23040
	s_waitcnt vmcnt(9)
	ds_write_b128 v1, v[172:175] offset:27648
	s_waitcnt vmcnt(8)
	ds_write_b128 v1, v[176:179] offset:32256
	ds_write_b128 v1, v[148:151] offset:55296
	ds_write_b128 v1, v[152:155] offset:59904
	ds_write_b128 v1, v[156:159] offset:64512
	ds_write_b128 v92, v[160:163] offset:32256
	global_load_dwordx4 v[148:151], v[80:81], off offset:384
	global_load_dwordx4 v[152:155], v[82:83], off offset:384
	global_load_dwordx4 v[156:159], v[78:79], off offset:384
	global_load_dwordx4 v[160:163], v[76:77], off offset:384
	global_load_dwordx4 v[164:167], v[90:91], off offset:384
	global_load_dwordx4 v[168:171], v[84:85], off offset:384
	global_load_dwordx4 v[172:175], v[86:87], off offset:384
	global_load_dwordx4 v[176:179], v[88:89], off offset:384
	s_waitcnt lgkmcnt(0)
	s_barrier
	v_mfma_f32_32x32x16_bf16 v[34:49], v[212:215], v[216:219], v[34:49]
	v_mfma_f32_32x32x16_bf16 v[50:65], v[212:215], v[228:231], v[50:65]
	v_mfma_f32_32x32x16_bf16 v[2:17], v[220:223], v[224:227], v[2:17]
	v_mfma_f32_32x32x16_bf16 v[18:33], v[220:223], v[232:235], v[18:33]
	v_mfma_f32_32x32x16_bf16 v[34:49], v[236:239], v[224:227], v[34:49]
	v_mfma_f32_32x32x16_bf16 v[50:65], v[236:239], v[232:235], v[50:65]
	ds_read_b128 v[212:215], v66 offset:18432
	ds_read_b128 v[216:219], v67 offset:55296
	ds_read_b128 v[220:223], v66 offset:18464
	ds_read_b128 v[224:227], v67 offset:55328
	ds_read_b128 v[228:231], v67 offset:59904
	ds_read_b128 v[232:235], v67 offset:59936
	s_waitcnt lgkmcnt(4)
	v_mfma_f32_32x32x16_bf16 v[2:17], v[212:215], v[216:219], v[2:17]
	s_waitcnt lgkmcnt(1)
	v_mfma_f32_32x32x16_bf16 v[18:33], v[212:215], v[228:231], v[18:33]
	ds_read_b128 v[212:215], v66 offset:23040
	ds_read_b128 v[236:239], v66 offset:23072
	s_waitcnt lgkmcnt(1)
	v_mfma_f32_32x32x16_bf16 v[34:49], v[212:215], v[216:219], v[34:49]
	v_mfma_f32_32x32x16_bf16 v[50:65], v[212:215], v[228:231], v[50:65]
	v_mfma_f32_32x32x16_bf16 v[2:17], v[220:223], v[224:227], v[2:17]
	v_mfma_f32_32x32x16_bf16 v[18:33], v[220:223], v[232:235], v[18:33]
	s_waitcnt lgkmcnt(0)
	v_mfma_f32_32x32x16_bf16 v[34:49], v[236:239], v[224:227], v[34:49]
	ds_read_b128 v[212:215], v66 offset:18496
	ds_read_b128 v[216:219], v67 offset:55360
	ds_read_b128 v[220:223], v66 offset:18528
	ds_read_b128 v[224:227], v67 offset:55392
	v_mfma_f32_32x32x16_bf16 v[50:65], v[236:239], v[232:235], v[50:65]
	ds_read_b128 v[228:231], v67 offset:59968
	ds_read_b128 v[232:235], v67 offset:60000
	s_waitcnt lgkmcnt(4)
	v_mfma_f32_32x32x16_bf16 v[2:17], v[212:215], v[216:219], v[2:17]
	s_waitcnt lgkmcnt(1)
	v_mfma_f32_32x32x16_bf16 v[18:33], v[212:215], v[228:231], v[18:33]
	ds_read_b128 v[212:215], v66 offset:23104
	ds_read_b128 v[236:239], v66 offset:23136
	s_waitcnt vmcnt(13)
	ds_write_b128 v1, v[188:191]
	ds_write_b128 v1, v[180:183] offset:4608
	ds_write_b128 v1, v[184:187] offset:9216
	s_waitcnt vmcnt(11)
	ds_write_b128 v1, v[196:199] offset:13824
	ds_write_b128 v1, v[192:195] offset:36864
	s_waitcnt vmcnt(10)
	ds_write_b128 v1, v[200:203] offset:41472
	s_waitcnt vmcnt(9)
	ds_write_b128 v1, v[204:207] offset:46080
	s_waitcnt vmcnt(8)
	ds_write_b128 v1, v[208:211] offset:50688
	global_load_dwordx4 v[180:183], v[80:81], off offset:512
	global_load_dwordx4 v[184:187], v[82:83], off offset:512
	global_load_dwordx4 v[188:191], v[78:79], off offset:512
	global_load_dwordx4 v[192:195], v[76:77], off offset:512
	global_load_dwordx4 v[196:199], v[90:91], off offset:512
	global_load_dwordx4 v[200:203], v[84:85], off offset:512
	global_load_dwordx4 v[204:207], v[86:87], off offset:512
	global_load_dwordx4 v[208:211], v[88:89], off offset:512
	s_waitcnt lgkmcnt(0)
	s_barrier
	v_mfma_f32_32x32x16_bf16 v[34:49], v[212:215], v[216:219], v[34:49]
	v_mfma_f32_32x32x16_bf16 v[50:65], v[212:215], v[228:231], v[50:65]
	v_mfma_f32_32x32x16_bf16 v[2:17], v[220:223], v[224:227], v[2:17]
	v_mfma_f32_32x32x16_bf16 v[18:33], v[220:223], v[232:235], v[18:33]
	v_mfma_f32_32x32x16_bf16 v[34:49], v[236:239], v[224:227], v[34:49]
	v_mfma_f32_32x32x16_bf16 v[50:65], v[236:239], v[232:235], v[50:65]
	ds_read_b128 v[212:215], v66
	ds_read_b128 v[216:219], v67 offset:36864
	ds_read_b128 v[220:223], v66 offset:32
	ds_read_b128 v[224:227], v67 offset:36896
	ds_read_b128 v[228:231], v67 offset:41472
	ds_read_b128 v[232:235], v67 offset:41504
	s_waitcnt lgkmcnt(4)
	v_mfma_f32_32x32x16_bf16 v[2:17], v[212:215], v[216:219], v[2:17]
	s_waitcnt lgkmcnt(1)
	v_mfma_f32_32x32x16_bf16 v[18:33], v[212:215], v[228:231], v[18:33]
	ds_read_b128 v[212:215], v66 offset:4608
	ds_read_b128 v[236:239], v66 offset:4640
	s_waitcnt lgkmcnt(1)
	v_mfma_f32_32x32x16_bf16 v[34:49], v[212:215], v[216:219], v[34:49]
	v_mfma_f32_32x32x16_bf16 v[50:65], v[212:215], v[228:231], v[50:65]
	v_mfma_f32_32x32x16_bf16 v[2:17], v[220:223], v[224:227], v[2:17]
	v_mfma_f32_32x32x16_bf16 v[18:33], v[220:223], v[232:235], v[18:33]
	s_waitcnt lgkmcnt(0)
	v_mfma_f32_32x32x16_bf16 v[34:49], v[236:239], v[224:227], v[34:49]
	ds_read_b128 v[212:215], v66 offset:64
	ds_read_b128 v[216:219], v67 offset:36928
	ds_read_b128 v[220:223], v66 offset:96
	ds_read_b128 v[224:227], v67 offset:36960
	v_mfma_f32_32x32x16_bf16 v[50:65], v[236:239], v[232:235], v[50:65]
	ds_read_b128 v[228:231], v67 offset:41536
	ds_read_b128 v[232:235], v67 offset:41568
	s_waitcnt lgkmcnt(4)
	v_mfma_f32_32x32x16_bf16 v[2:17], v[212:215], v[216:219], v[2:17]
	s_waitcnt lgkmcnt(1)
	v_mfma_f32_32x32x16_bf16 v[18:33], v[212:215], v[228:231], v[18:33]
	ds_read_b128 v[212:215], v66 offset:4672
	ds_read_b128 v[236:239], v66 offset:4704
	s_waitcnt vmcnt(13)
	ds_write_b128 v1, v[156:159] offset:18432
	ds_write_b128 v1, v[148:151] offset:23040
	ds_write_b128 v1, v[152:155] offset:27648
	s_waitcnt vmcnt(11)
	ds_write_b128 v1, v[164:167] offset:32256
	ds_write_b128 v1, v[160:163] offset:55296
	s_waitcnt vmcnt(10)
	ds_write_b128 v1, v[168:171] offset:59904
	s_waitcnt vmcnt(9)
	ds_write_b128 v1, v[172:175] offset:64512
	s_waitcnt vmcnt(8)
	ds_write_b128 v92, v[176:179] offset:32256
	global_load_dwordx4 v[148:151], v[80:81], off offset:640
	global_load_dwordx4 v[152:155], v[82:83], off offset:640
	global_load_dwordx4 v[156:159], v[78:79], off offset:640
	global_load_dwordx4 v[160:163], v[76:77], off offset:640
	global_load_dwordx4 v[164:167], v[90:91], off offset:640
	global_load_dwordx4 v[168:171], v[84:85], off offset:640
	global_load_dwordx4 v[172:175], v[86:87], off offset:640
	global_load_dwordx4 v[176:179], v[88:89], off offset:640
	s_waitcnt lgkmcnt(0)
	s_barrier
	v_mfma_f32_32x32x16_bf16 v[34:49], v[212:215], v[216:219], v[34:49]
	v_mfma_f32_32x32x16_bf16 v[50:65], v[212:215], v[228:231], v[50:65]
	v_mfma_f32_32x32x16_bf16 v[2:17], v[220:223], v[224:227], v[2:17]
	v_mfma_f32_32x32x16_bf16 v[18:33], v[220:223], v[232:235], v[18:33]
	v_mfma_f32_32x32x16_bf16 v[34:49], v[236:239], v[224:227], v[34:49]
	v_mfma_f32_32x32x16_bf16 v[50:65], v[236:239], v[232:235], v[50:65]
	ds_read_b128 v[212:215], v66 offset:18432
	ds_read_b128 v[216:219], v67 offset:55296
	ds_read_b128 v[220:223], v66 offset:18464
	ds_read_b128 v[224:227], v67 offset:55328
	ds_read_b128 v[228:231], v67 offset:59904
	ds_read_b128 v[232:235], v67 offset:59936
	s_waitcnt lgkmcnt(4)
	v_mfma_f32_32x32x16_bf16 v[2:17], v[212:215], v[216:219], v[2:17]
	s_waitcnt lgkmcnt(1)
	v_mfma_f32_32x32x16_bf16 v[18:33], v[212:215], v[228:231], v[18:33]
	ds_read_b128 v[212:215], v66 offset:23040
	ds_read_b128 v[236:239], v66 offset:23072
	s_waitcnt lgkmcnt(1)
	v_mfma_f32_32x32x16_bf16 v[34:49], v[212:215], v[216:219], v[34:49]
	v_mfma_f32_32x32x16_bf16 v[50:65], v[212:215], v[228:231], v[50:65]
	v_mfma_f32_32x32x16_bf16 v[2:17], v[220:223], v[224:227], v[2:17]
	v_mfma_f32_32x32x16_bf16 v[18:33], v[220:223], v[232:235], v[18:33]
	s_waitcnt lgkmcnt(0)
	v_mfma_f32_32x32x16_bf16 v[34:49], v[236:239], v[224:227], v[34:49]
	ds_read_b128 v[212:215], v66 offset:18496
	ds_read_b128 v[216:219], v67 offset:55360
	ds_read_b128 v[220:223], v66 offset:18528
	ds_read_b128 v[224:227], v67 offset:55392
	v_mfma_f32_32x32x16_bf16 v[50:65], v[236:239], v[232:235], v[50:65]
	ds_read_b128 v[228:231], v67 offset:59968
	ds_read_b128 v[232:235], v67 offset:60000
	s_waitcnt lgkmcnt(4)
	v_mfma_f32_32x32x16_bf16 v[2:17], v[212:215], v[216:219], v[2:17]
	s_waitcnt lgkmcnt(1)
	v_mfma_f32_32x32x16_bf16 v[18:33], v[212:215], v[228:231], v[18:33]
	ds_read_b128 v[212:215], v66 offset:23104
	ds_read_b128 v[236:239], v66 offset:23136
	s_waitcnt vmcnt(13)
	ds_write_b128 v1, v[188:191]
	ds_write_b128 v1, v[180:183] offset:4608
	ds_write_b128 v1, v[184:187] offset:9216
	s_waitcnt vmcnt(11)
	ds_write_b128 v1, v[196:199] offset:13824
	ds_write_b128 v1, v[192:195] offset:36864
	s_waitcnt vmcnt(10)
	ds_write_b128 v1, v[200:203] offset:41472
	s_waitcnt vmcnt(9)
	ds_write_b128 v1, v[204:207] offset:46080
	s_waitcnt vmcnt(8)
	ds_write_b128 v1, v[208:211] offset:50688
	global_load_dwordx4 v[180:183], v[80:81], off offset:768
	global_load_dwordx4 v[184:187], v[82:83], off offset:768
	global_load_dwordx4 v[188:191], v[78:79], off offset:768
	global_load_dwordx4 v[192:195], v[76:77], off offset:768
	global_load_dwordx4 v[196:199], v[90:91], off offset:768
	global_load_dwordx4 v[200:203], v[84:85], off offset:768
	global_load_dwordx4 v[204:207], v[86:87], off offset:768
	global_load_dwordx4 v[208:211], v[88:89], off offset:768
	s_waitcnt lgkmcnt(0)
	s_barrier
	v_mfma_f32_32x32x16_bf16 v[34:49], v[212:215], v[216:219], v[34:49]
	v_mfma_f32_32x32x16_bf16 v[50:65], v[212:215], v[228:231], v[50:65]
	v_mfma_f32_32x32x16_bf16 v[2:17], v[220:223], v[224:227], v[2:17]
	v_mfma_f32_32x32x16_bf16 v[18:33], v[220:223], v[232:235], v[18:33]
	v_mfma_f32_32x32x16_bf16 v[34:49], v[236:239], v[224:227], v[34:49]
	v_mfma_f32_32x32x16_bf16 v[50:65], v[236:239], v[232:235], v[50:65]
	ds_read_b128 v[212:215], v66
	ds_read_b128 v[216:219], v67 offset:36864
	ds_read_b128 v[220:223], v66 offset:32
	ds_read_b128 v[224:227], v67 offset:36896
	ds_read_b128 v[228:231], v67 offset:41472
	ds_read_b128 v[232:235], v67 offset:41504
	s_waitcnt lgkmcnt(4)
	v_mfma_f32_32x32x16_bf16 v[2:17], v[212:215], v[216:219], v[2:17]
	s_waitcnt lgkmcnt(1)
	v_mfma_f32_32x32x16_bf16 v[18:33], v[212:215], v[228:231], v[18:33]
	ds_read_b128 v[212:215], v66 offset:4608
	ds_read_b128 v[236:239], v66 offset:4640
	s_waitcnt lgkmcnt(1)
	v_mfma_f32_32x32x16_bf16 v[34:49], v[212:215], v[216:219], v[34:49]
	v_mfma_f32_32x32x16_bf16 v[50:65], v[212:215], v[228:231], v[50:65]
	v_mfma_f32_32x32x16_bf16 v[2:17], v[220:223], v[224:227], v[2:17]
	v_mfma_f32_32x32x16_bf16 v[18:33], v[220:223], v[232:235], v[18:33]
	s_waitcnt lgkmcnt(0)
	v_mfma_f32_32x32x16_bf16 v[34:49], v[236:239], v[224:227], v[34:49]
	ds_read_b128 v[212:215], v66 offset:64
	ds_read_b128 v[216:219], v67 offset:36928
	ds_read_b128 v[220:223], v66 offset:96
	ds_read_b128 v[224:227], v67 offset:36960
	v_mfma_f32_32x32x16_bf16 v[50:65], v[236:239], v[232:235], v[50:65]
	ds_read_b128 v[228:231], v67 offset:41536
	ds_read_b128 v[232:235], v67 offset:41568
	s_waitcnt lgkmcnt(4)
	v_mfma_f32_32x32x16_bf16 v[2:17], v[212:215], v[216:219], v[2:17]
	s_waitcnt lgkmcnt(1)
	v_mfma_f32_32x32x16_bf16 v[18:33], v[212:215], v[228:231], v[18:33]
	ds_read_b128 v[212:215], v66 offset:4672
	ds_read_b128 v[236:239], v66 offset:4704
	s_waitcnt vmcnt(13)
	ds_write_b128 v1, v[156:159] offset:18432
	ds_write_b128 v1, v[148:151] offset:23040
	ds_write_b128 v1, v[152:155] offset:27648
	s_waitcnt vmcnt(11)
	ds_write_b128 v1, v[164:167] offset:32256
	ds_write_b128 v1, v[160:163] offset:55296
	s_waitcnt vmcnt(10)
	ds_write_b128 v1, v[168:171] offset:59904
	s_waitcnt vmcnt(9)
	ds_write_b128 v1, v[172:175] offset:64512
	s_waitcnt vmcnt(8)
	ds_write_b128 v92, v[176:179] offset:32256
	global_load_dwordx4 v[148:151], v[80:81], off offset:896
	global_load_dwordx4 v[152:155], v[82:83], off offset:896
	global_load_dwordx4 v[156:159], v[78:79], off offset:896
	global_load_dwordx4 v[160:163], v[76:77], off offset:896
	global_load_dwordx4 v[164:167], v[90:91], off offset:896
	global_load_dwordx4 v[168:171], v[84:85], off offset:896
	global_load_dwordx4 v[172:175], v[86:87], off offset:896
	global_load_dwordx4 v[176:179], v[88:89], off offset:896
	s_waitcnt lgkmcnt(0)
	s_barrier
	v_mfma_f32_32x32x16_bf16 v[34:49], v[212:215], v[216:219], v[34:49]
	v_mfma_f32_32x32x16_bf16 v[50:65], v[212:215], v[228:231], v[50:65]
	v_mfma_f32_32x32x16_bf16 v[2:17], v[220:223], v[224:227], v[2:17]
	v_mfma_f32_32x32x16_bf16 v[18:33], v[220:223], v[232:235], v[18:33]
	v_mfma_f32_32x32x16_bf16 v[34:49], v[236:239], v[224:227], v[34:49]
	v_mfma_f32_32x32x16_bf16 v[50:65], v[236:239], v[232:235], v[50:65]
	ds_read_b128 v[212:215], v66 offset:18432
	ds_read_b128 v[216:219], v67 offset:55296
	ds_read_b128 v[220:223], v66 offset:18464
	ds_read_b128 v[224:227], v67 offset:55328
	ds_read_b128 v[228:231], v67 offset:59904
	ds_read_b128 v[232:235], v67 offset:59936
	s_waitcnt lgkmcnt(4)
	v_mfma_f32_32x32x16_bf16 v[2:17], v[212:215], v[216:219], v[2:17]
	s_waitcnt lgkmcnt(1)
	v_mfma_f32_32x32x16_bf16 v[18:33], v[212:215], v[228:231], v[18:33]
	ds_read_b128 v[212:215], v66 offset:23040
	ds_read_b128 v[236:239], v66 offset:23072
	s_waitcnt lgkmcnt(1)
	v_mfma_f32_32x32x16_bf16 v[34:49], v[212:215], v[216:219], v[34:49]
	v_mfma_f32_32x32x16_bf16 v[50:65], v[212:215], v[228:231], v[50:65]
	v_mfma_f32_32x32x16_bf16 v[2:17], v[220:223], v[224:227], v[2:17]
	v_mfma_f32_32x32x16_bf16 v[18:33], v[220:223], v[232:235], v[18:33]
	s_waitcnt lgkmcnt(0)
	v_mfma_f32_32x32x16_bf16 v[34:49], v[236:239], v[224:227], v[34:49]
	ds_read_b128 v[212:215], v66 offset:18496
	ds_read_b128 v[216:219], v67 offset:55360
	ds_read_b128 v[220:223], v66 offset:18528
	ds_read_b128 v[224:227], v67 offset:55392
	v_mfma_f32_32x32x16_bf16 v[50:65], v[236:239], v[232:235], v[50:65]
	ds_read_b128 v[228:231], v67 offset:59968
	ds_read_b128 v[232:235], v67 offset:60000
	s_waitcnt lgkmcnt(4)
	v_mfma_f32_32x32x16_bf16 v[2:17], v[212:215], v[216:219], v[2:17]
	s_waitcnt lgkmcnt(1)
	v_mfma_f32_32x32x16_bf16 v[18:33], v[212:215], v[228:231], v[18:33]
	ds_read_b128 v[212:215], v66 offset:23104
	ds_read_b128 v[236:239], v66 offset:23136
	s_waitcnt vmcnt(13)
	ds_write_b128 v1, v[188:191]
	ds_write_b128 v1, v[180:183] offset:4608
	ds_write_b128 v1, v[184:187] offset:9216
	s_waitcnt vmcnt(11)
	ds_write_b128 v1, v[196:199] offset:13824
	ds_write_b128 v1, v[192:195] offset:36864
	s_waitcnt vmcnt(10)
	ds_write_b128 v1, v[200:203] offset:41472
	s_waitcnt vmcnt(9)
	ds_write_b128 v1, v[204:207] offset:46080
	s_waitcnt vmcnt(8)
	ds_write_b128 v1, v[208:211] offset:50688
	global_load_dwordx4 v[180:183], v[80:81], off offset:1024
	global_load_dwordx4 v[184:187], v[82:83], off offset:1024
	global_load_dwordx4 v[188:191], v[78:79], off offset:1024
	global_load_dwordx4 v[192:195], v[76:77], off offset:1024
	global_load_dwordx4 v[196:199], v[90:91], off offset:1024
	global_load_dwordx4 v[200:203], v[84:85], off offset:1024
	global_load_dwordx4 v[204:207], v[86:87], off offset:1024
	global_load_dwordx4 v[208:211], v[88:89], off offset:1024
	s_waitcnt lgkmcnt(0)
	s_barrier
	v_mfma_f32_32x32x16_bf16 v[34:49], v[212:215], v[216:219], v[34:49]
	v_mfma_f32_32x32x16_bf16 v[50:65], v[212:215], v[228:231], v[50:65]
	v_mfma_f32_32x32x16_bf16 v[2:17], v[220:223], v[224:227], v[2:17]
	v_mfma_f32_32x32x16_bf16 v[18:33], v[220:223], v[232:235], v[18:33]
	v_mfma_f32_32x32x16_bf16 v[34:49], v[236:239], v[224:227], v[34:49]
	v_mfma_f32_32x32x16_bf16 v[50:65], v[236:239], v[232:235], v[50:65]
	ds_read_b128 v[212:215], v66
	ds_read_b128 v[216:219], v67 offset:36864
	ds_read_b128 v[220:223], v66 offset:32
	ds_read_b128 v[224:227], v67 offset:36896
	ds_read_b128 v[228:231], v67 offset:41472
	ds_read_b128 v[232:235], v67 offset:41504
	s_waitcnt lgkmcnt(4)
	v_mfma_f32_32x32x16_bf16 v[2:17], v[212:215], v[216:219], v[2:17]
	s_waitcnt lgkmcnt(1)
	v_mfma_f32_32x32x16_bf16 v[18:33], v[212:215], v[228:231], v[18:33]
	ds_read_b128 v[212:215], v66 offset:4608
	ds_read_b128 v[236:239], v66 offset:4640
	s_waitcnt lgkmcnt(1)
	v_mfma_f32_32x32x16_bf16 v[34:49], v[212:215], v[216:219], v[34:49]
	v_mfma_f32_32x32x16_bf16 v[50:65], v[212:215], v[228:231], v[50:65]
	v_mfma_f32_32x32x16_bf16 v[2:17], v[220:223], v[224:227], v[2:17]
	v_mfma_f32_32x32x16_bf16 v[18:33], v[220:223], v[232:235], v[18:33]
	s_waitcnt lgkmcnt(0)
	v_mfma_f32_32x32x16_bf16 v[34:49], v[236:239], v[224:227], v[34:49]
	ds_read_b128 v[212:215], v66 offset:64
	ds_read_b128 v[216:219], v67 offset:36928
	ds_read_b128 v[220:223], v66 offset:96
	ds_read_b128 v[224:227], v67 offset:36960
	v_mfma_f32_32x32x16_bf16 v[50:65], v[236:239], v[232:235], v[50:65]
	ds_read_b128 v[228:231], v67 offset:41536
	ds_read_b128 v[232:235], v67 offset:41568
	s_waitcnt lgkmcnt(4)
	v_mfma_f32_32x32x16_bf16 v[2:17], v[212:215], v[216:219], v[2:17]
	s_waitcnt lgkmcnt(1)
	v_mfma_f32_32x32x16_bf16 v[18:33], v[212:215], v[228:231], v[18:33]
	ds_read_b128 v[212:215], v66 offset:4672
	ds_read_b128 v[236:239], v66 offset:4704
	s_waitcnt vmcnt(13)
	ds_write_b128 v1, v[156:159] offset:18432
	ds_write_b128 v1, v[148:151] offset:23040
	ds_write_b128 v1, v[152:155] offset:27648
	s_waitcnt vmcnt(11)
	ds_write_b128 v1, v[164:167] offset:32256
	ds_write_b128 v1, v[160:163] offset:55296
	s_waitcnt vmcnt(10)
	ds_write_b128 v1, v[168:171] offset:59904
	s_waitcnt vmcnt(9)
	ds_write_b128 v1, v[172:175] offset:64512
	s_waitcnt vmcnt(8)
	ds_write_b128 v92, v[176:179] offset:32256
	global_load_dwordx4 v[148:151], v[80:81], off offset:1152
	global_load_dwordx4 v[152:155], v[82:83], off offset:1152
	global_load_dwordx4 v[156:159], v[78:79], off offset:1152
	global_load_dwordx4 v[160:163], v[76:77], off offset:1152
	global_load_dwordx4 v[164:167], v[90:91], off offset:1152
	global_load_dwordx4 v[168:171], v[84:85], off offset:1152
	global_load_dwordx4 v[172:175], v[86:87], off offset:1152
	global_load_dwordx4 v[176:179], v[88:89], off offset:1152
	s_waitcnt lgkmcnt(0)
	s_barrier
	v_mfma_f32_32x32x16_bf16 v[34:49], v[212:215], v[216:219], v[34:49]
	v_mfma_f32_32x32x16_bf16 v[50:65], v[212:215], v[228:231], v[50:65]
	v_mfma_f32_32x32x16_bf16 v[2:17], v[220:223], v[224:227], v[2:17]
	v_mfma_f32_32x32x16_bf16 v[18:33], v[220:223], v[232:235], v[18:33]
	v_mfma_f32_32x32x16_bf16 v[34:49], v[236:239], v[224:227], v[34:49]
	v_mfma_f32_32x32x16_bf16 v[50:65], v[236:239], v[232:235], v[50:65]
	ds_read_b128 v[212:215], v66 offset:18432
	ds_read_b128 v[216:219], v67 offset:55296
	ds_read_b128 v[220:223], v66 offset:18464
	ds_read_b128 v[224:227], v67 offset:55328
	ds_read_b128 v[228:231], v67 offset:59904
	ds_read_b128 v[232:235], v67 offset:59936
	s_waitcnt lgkmcnt(4)
	v_mfma_f32_32x32x16_bf16 v[2:17], v[212:215], v[216:219], v[2:17]
	s_waitcnt lgkmcnt(1)
	v_mfma_f32_32x32x16_bf16 v[18:33], v[212:215], v[228:231], v[18:33]
	ds_read_b128 v[212:215], v66 offset:23040
	ds_read_b128 v[236:239], v66 offset:23072
	s_waitcnt lgkmcnt(1)
	v_mfma_f32_32x32x16_bf16 v[34:49], v[212:215], v[216:219], v[34:49]
	v_mfma_f32_32x32x16_bf16 v[50:65], v[212:215], v[228:231], v[50:65]
	v_mfma_f32_32x32x16_bf16 v[2:17], v[220:223], v[224:227], v[2:17]
	v_mfma_f32_32x32x16_bf16 v[18:33], v[220:223], v[232:235], v[18:33]
	s_waitcnt lgkmcnt(0)
	v_mfma_f32_32x32x16_bf16 v[34:49], v[236:239], v[224:227], v[34:49]
	ds_read_b128 v[212:215], v66 offset:18496
	ds_read_b128 v[216:219], v67 offset:55360
	ds_read_b128 v[220:223], v66 offset:18528
	ds_read_b128 v[224:227], v67 offset:55392
	v_mfma_f32_32x32x16_bf16 v[50:65], v[236:239], v[232:235], v[50:65]
	ds_read_b128 v[228:231], v67 offset:59968
	ds_read_b128 v[232:235], v67 offset:60000
	s_waitcnt lgkmcnt(4)
	v_mfma_f32_32x32x16_bf16 v[2:17], v[212:215], v[216:219], v[2:17]
	s_waitcnt lgkmcnt(1)
	v_mfma_f32_32x32x16_bf16 v[18:33], v[212:215], v[228:231], v[18:33]
	ds_read_b128 v[212:215], v66 offset:23104
	ds_read_b128 v[236:239], v66 offset:23136
	s_waitcnt vmcnt(13)
	ds_write_b128 v1, v[188:191]
	ds_write_b128 v1, v[180:183] offset:4608
	ds_write_b128 v1, v[184:187] offset:9216
	s_waitcnt vmcnt(11)
	ds_write_b128 v1, v[196:199] offset:13824
	ds_write_b128 v1, v[192:195] offset:36864
	s_waitcnt vmcnt(10)
	ds_write_b128 v1, v[200:203] offset:41472
	s_waitcnt vmcnt(9)
	ds_write_b128 v1, v[204:207] offset:46080
	s_waitcnt vmcnt(8)
	ds_write_b128 v1, v[208:211] offset:50688
	global_load_dwordx4 v[180:183], v[80:81], off offset:1280
	global_load_dwordx4 v[184:187], v[82:83], off offset:1280
	global_load_dwordx4 v[188:191], v[78:79], off offset:1280
	global_load_dwordx4 v[192:195], v[76:77], off offset:1280
	global_load_dwordx4 v[196:199], v[90:91], off offset:1280
	global_load_dwordx4 v[200:203], v[84:85], off offset:1280
	global_load_dwordx4 v[204:207], v[86:87], off offset:1280
	global_load_dwordx4 v[208:211], v[88:89], off offset:1280
	s_waitcnt lgkmcnt(0)
	s_barrier
	v_mfma_f32_32x32x16_bf16 v[34:49], v[212:215], v[216:219], v[34:49]
	v_mfma_f32_32x32x16_bf16 v[50:65], v[212:215], v[228:231], v[50:65]
	v_mfma_f32_32x32x16_bf16 v[2:17], v[220:223], v[224:227], v[2:17]
	v_mfma_f32_32x32x16_bf16 v[18:33], v[220:223], v[232:235], v[18:33]
	v_mfma_f32_32x32x16_bf16 v[34:49], v[236:239], v[224:227], v[34:49]
	v_mfma_f32_32x32x16_bf16 v[50:65], v[236:239], v[232:235], v[50:65]
	ds_read_b128 v[212:215], v66
	ds_read_b128 v[216:219], v67 offset:36864
	ds_read_b128 v[220:223], v66 offset:32
	ds_read_b128 v[224:227], v67 offset:36896
	ds_read_b128 v[228:231], v67 offset:41472
	ds_read_b128 v[232:235], v67 offset:41504
	s_waitcnt lgkmcnt(4)
	v_mfma_f32_32x32x16_bf16 v[2:17], v[212:215], v[216:219], v[2:17]
	s_waitcnt lgkmcnt(1)
	v_mfma_f32_32x32x16_bf16 v[18:33], v[212:215], v[228:231], v[18:33]
	ds_read_b128 v[212:215], v66 offset:4608
	ds_read_b128 v[236:239], v66 offset:4640
	s_waitcnt lgkmcnt(1)
	v_mfma_f32_32x32x16_bf16 v[34:49], v[212:215], v[216:219], v[34:49]
	v_mfma_f32_32x32x16_bf16 v[50:65], v[212:215], v[228:231], v[50:65]
	v_mfma_f32_32x32x16_bf16 v[2:17], v[220:223], v[224:227], v[2:17]
	v_mfma_f32_32x32x16_bf16 v[18:33], v[220:223], v[232:235], v[18:33]
	s_waitcnt lgkmcnt(0)
	v_mfma_f32_32x32x16_bf16 v[34:49], v[236:239], v[224:227], v[34:49]
	ds_read_b128 v[212:215], v66 offset:64
	ds_read_b128 v[216:219], v67 offset:36928
	ds_read_b128 v[220:223], v66 offset:96
	ds_read_b128 v[224:227], v67 offset:36960
	v_mfma_f32_32x32x16_bf16 v[50:65], v[236:239], v[232:235], v[50:65]
	ds_read_b128 v[228:231], v67 offset:41536
	ds_read_b128 v[232:235], v67 offset:41568
	s_waitcnt lgkmcnt(4)
	v_mfma_f32_32x32x16_bf16 v[2:17], v[212:215], v[216:219], v[2:17]
	s_waitcnt lgkmcnt(1)
	v_mfma_f32_32x32x16_bf16 v[18:33], v[212:215], v[228:231], v[18:33]
	ds_read_b128 v[212:215], v66 offset:4672
	ds_read_b128 v[236:239], v66 offset:4704
	s_waitcnt vmcnt(13)
	ds_write_b128 v1, v[156:159] offset:18432
	ds_write_b128 v1, v[148:151] offset:23040
	ds_write_b128 v1, v[152:155] offset:27648
	s_waitcnt vmcnt(11)
	ds_write_b128 v1, v[164:167] offset:32256
	ds_write_b128 v1, v[160:163] offset:55296
	s_waitcnt vmcnt(10)
	ds_write_b128 v1, v[168:171] offset:59904
	s_waitcnt vmcnt(9)
	ds_write_b128 v1, v[172:175] offset:64512
	s_waitcnt vmcnt(8)
	ds_write_b128 v92, v[176:179] offset:32256
	global_load_dwordx4 v[148:151], v[80:81], off offset:1408
	global_load_dwordx4 v[152:155], v[82:83], off offset:1408
	global_load_dwordx4 v[156:159], v[78:79], off offset:1408
	global_load_dwordx4 v[160:163], v[76:77], off offset:1408
	global_load_dwordx4 v[164:167], v[90:91], off offset:1408
	global_load_dwordx4 v[168:171], v[84:85], off offset:1408
	global_load_dwordx4 v[172:175], v[86:87], off offset:1408
	global_load_dwordx4 v[176:179], v[88:89], off offset:1408
	s_waitcnt lgkmcnt(0)
	s_barrier
	v_mfma_f32_32x32x16_bf16 v[34:49], v[212:215], v[216:219], v[34:49]
	v_mfma_f32_32x32x16_bf16 v[50:65], v[212:215], v[228:231], v[50:65]
	v_mfma_f32_32x32x16_bf16 v[2:17], v[220:223], v[224:227], v[2:17]
	v_mfma_f32_32x32x16_bf16 v[18:33], v[220:223], v[232:235], v[18:33]
	v_mfma_f32_32x32x16_bf16 v[34:49], v[236:239], v[224:227], v[34:49]
	v_mfma_f32_32x32x16_bf16 v[50:65], v[236:239], v[232:235], v[50:65]
	ds_read_b128 v[212:215], v66 offset:18432
	ds_read_b128 v[216:219], v67 offset:55296
	ds_read_b128 v[220:223], v66 offset:18464
	ds_read_b128 v[224:227], v67 offset:55328
	ds_read_b128 v[228:231], v67 offset:59904
	ds_read_b128 v[232:235], v67 offset:59936
	s_waitcnt lgkmcnt(4)
	v_mfma_f32_32x32x16_bf16 v[2:17], v[212:215], v[216:219], v[2:17]
	s_waitcnt lgkmcnt(1)
	v_mfma_f32_32x32x16_bf16 v[18:33], v[212:215], v[228:231], v[18:33]
	ds_read_b128 v[212:215], v66 offset:23040
	ds_read_b128 v[236:239], v66 offset:23072
	s_waitcnt lgkmcnt(1)
	v_mfma_f32_32x32x16_bf16 v[34:49], v[212:215], v[216:219], v[34:49]
	v_mfma_f32_32x32x16_bf16 v[50:65], v[212:215], v[228:231], v[50:65]
	v_mfma_f32_32x32x16_bf16 v[2:17], v[220:223], v[224:227], v[2:17]
	v_mfma_f32_32x32x16_bf16 v[18:33], v[220:223], v[232:235], v[18:33]
	s_waitcnt lgkmcnt(0)
	v_mfma_f32_32x32x16_bf16 v[34:49], v[236:239], v[224:227], v[34:49]
	ds_read_b128 v[212:215], v66 offset:18496
	ds_read_b128 v[216:219], v67 offset:55360
	ds_read_b128 v[220:223], v66 offset:18528
	ds_read_b128 v[224:227], v67 offset:55392
	v_mfma_f32_32x32x16_bf16 v[50:65], v[236:239], v[232:235], v[50:65]
	ds_read_b128 v[228:231], v67 offset:59968
	ds_read_b128 v[232:235], v67 offset:60000
	s_waitcnt lgkmcnt(4)
	v_mfma_f32_32x32x16_bf16 v[2:17], v[212:215], v[216:219], v[2:17]
	s_waitcnt lgkmcnt(1)
	v_mfma_f32_32x32x16_bf16 v[18:33], v[212:215], v[228:231], v[18:33]
	ds_read_b128 v[212:215], v66 offset:23104
	ds_read_b128 v[236:239], v66 offset:23136
	s_waitcnt vmcnt(13)
	ds_write_b128 v1, v[188:191]
	ds_write_b128 v1, v[180:183] offset:4608
	ds_write_b128 v1, v[184:187] offset:9216
	s_waitcnt vmcnt(11)
	ds_write_b128 v1, v[196:199] offset:13824
	ds_write_b128 v1, v[192:195] offset:36864
	s_waitcnt vmcnt(10)
	ds_write_b128 v1, v[200:203] offset:41472
	s_waitcnt vmcnt(9)
	ds_write_b128 v1, v[204:207] offset:46080
	s_waitcnt vmcnt(8)
	ds_write_b128 v1, v[208:211] offset:50688
	global_load_dwordx4 v[180:183], v[80:81], off offset:1536
	global_load_dwordx4 v[184:187], v[82:83], off offset:1536
	global_load_dwordx4 v[188:191], v[78:79], off offset:1536
	global_load_dwordx4 v[192:195], v[76:77], off offset:1536
	global_load_dwordx4 v[196:199], v[90:91], off offset:1536
	global_load_dwordx4 v[200:203], v[84:85], off offset:1536
	global_load_dwordx4 v[204:207], v[86:87], off offset:1536
	global_load_dwordx4 v[208:211], v[88:89], off offset:1536
	s_waitcnt lgkmcnt(0)
	s_barrier
	v_mfma_f32_32x32x16_bf16 v[34:49], v[212:215], v[216:219], v[34:49]
	v_mfma_f32_32x32x16_bf16 v[50:65], v[212:215], v[228:231], v[50:65]
	v_mfma_f32_32x32x16_bf16 v[2:17], v[220:223], v[224:227], v[2:17]
	v_mfma_f32_32x32x16_bf16 v[18:33], v[220:223], v[232:235], v[18:33]
	v_mfma_f32_32x32x16_bf16 v[34:49], v[236:239], v[224:227], v[34:49]
	v_mfma_f32_32x32x16_bf16 v[50:65], v[236:239], v[232:235], v[50:65]
	ds_read_b128 v[212:215], v66
	ds_read_b128 v[216:219], v67 offset:36864
	ds_read_b128 v[220:223], v66 offset:32
	ds_read_b128 v[224:227], v67 offset:36896
	ds_read_b128 v[228:231], v67 offset:41472
	ds_read_b128 v[232:235], v67 offset:41504
	s_waitcnt lgkmcnt(4)
	v_mfma_f32_32x32x16_bf16 v[2:17], v[212:215], v[216:219], v[2:17]
	s_waitcnt lgkmcnt(1)
	v_mfma_f32_32x32x16_bf16 v[18:33], v[212:215], v[228:231], v[18:33]
	ds_read_b128 v[212:215], v66 offset:4608
	ds_read_b128 v[236:239], v66 offset:4640
	s_waitcnt lgkmcnt(1)
	v_mfma_f32_32x32x16_bf16 v[34:49], v[212:215], v[216:219], v[34:49]
	v_mfma_f32_32x32x16_bf16 v[50:65], v[212:215], v[228:231], v[50:65]
	v_mfma_f32_32x32x16_bf16 v[2:17], v[220:223], v[224:227], v[2:17]
	v_mfma_f32_32x32x16_bf16 v[18:33], v[220:223], v[232:235], v[18:33]
	s_waitcnt lgkmcnt(0)
	v_mfma_f32_32x32x16_bf16 v[34:49], v[236:239], v[224:227], v[34:49]
	ds_read_b128 v[212:215], v66 offset:64
	ds_read_b128 v[216:219], v67 offset:36928
	ds_read_b128 v[220:223], v66 offset:96
	ds_read_b128 v[224:227], v67 offset:36960
	v_mfma_f32_32x32x16_bf16 v[50:65], v[236:239], v[232:235], v[50:65]
	ds_read_b128 v[228:231], v67 offset:41536
	ds_read_b128 v[232:235], v67 offset:41568
	s_waitcnt lgkmcnt(4)
	v_mfma_f32_32x32x16_bf16 v[2:17], v[212:215], v[216:219], v[2:17]
	s_waitcnt lgkmcnt(1)
	v_mfma_f32_32x32x16_bf16 v[18:33], v[212:215], v[228:231], v[18:33]
	ds_read_b128 v[212:215], v66 offset:4672
	ds_read_b128 v[236:239], v66 offset:4704
	s_waitcnt vmcnt(13)
	ds_write_b128 v1, v[156:159] offset:18432
	ds_write_b128 v1, v[148:151] offset:23040
	ds_write_b128 v1, v[152:155] offset:27648
	s_waitcnt vmcnt(11)
	ds_write_b128 v1, v[164:167] offset:32256
	ds_write_b128 v1, v[160:163] offset:55296
	s_waitcnt vmcnt(10)
	ds_write_b128 v1, v[168:171] offset:59904
	s_waitcnt vmcnt(9)
	ds_write_b128 v1, v[172:175] offset:64512
	s_waitcnt vmcnt(8)
	ds_write_b128 v92, v[176:179] offset:32256
	global_load_dwordx4 v[148:151], v[80:81], off offset:1664
	global_load_dwordx4 v[152:155], v[82:83], off offset:1664
	global_load_dwordx4 v[156:159], v[78:79], off offset:1664
	global_load_dwordx4 v[160:163], v[76:77], off offset:1664
	global_load_dwordx4 v[164:167], v[90:91], off offset:1664
	global_load_dwordx4 v[168:171], v[84:85], off offset:1664
	global_load_dwordx4 v[172:175], v[86:87], off offset:1664
	global_load_dwordx4 v[176:179], v[88:89], off offset:1664
	s_waitcnt lgkmcnt(0)
	s_barrier
	v_mfma_f32_32x32x16_bf16 v[34:49], v[212:215], v[216:219], v[34:49]
	v_mfma_f32_32x32x16_bf16 v[50:65], v[212:215], v[228:231], v[50:65]
	v_mfma_f32_32x32x16_bf16 v[2:17], v[220:223], v[224:227], v[2:17]
	v_mfma_f32_32x32x16_bf16 v[18:33], v[220:223], v[232:235], v[18:33]
	v_mfma_f32_32x32x16_bf16 v[34:49], v[236:239], v[224:227], v[34:49]
	v_mfma_f32_32x32x16_bf16 v[50:65], v[236:239], v[232:235], v[50:65]
	ds_read_b128 v[212:215], v66 offset:18432
	ds_read_b128 v[216:219], v67 offset:55296
	ds_read_b128 v[220:223], v66 offset:18464
	ds_read_b128 v[224:227], v67 offset:55328
	ds_read_b128 v[228:231], v67 offset:59904
	ds_read_b128 v[232:235], v67 offset:59936
	s_waitcnt lgkmcnt(4)
	v_mfma_f32_32x32x16_bf16 v[2:17], v[212:215], v[216:219], v[2:17]
	s_waitcnt lgkmcnt(1)
	v_mfma_f32_32x32x16_bf16 v[18:33], v[212:215], v[228:231], v[18:33]
	ds_read_b128 v[212:215], v66 offset:23040
	ds_read_b128 v[236:239], v66 offset:23072
	s_waitcnt lgkmcnt(1)
	v_mfma_f32_32x32x16_bf16 v[34:49], v[212:215], v[216:219], v[34:49]
	v_mfma_f32_32x32x16_bf16 v[50:65], v[212:215], v[228:231], v[50:65]
	v_mfma_f32_32x32x16_bf16 v[2:17], v[220:223], v[224:227], v[2:17]
	v_mfma_f32_32x32x16_bf16 v[18:33], v[220:223], v[232:235], v[18:33]
	s_waitcnt lgkmcnt(0)
	v_mfma_f32_32x32x16_bf16 v[34:49], v[236:239], v[224:227], v[34:49]
	ds_read_b128 v[212:215], v66 offset:18496
	ds_read_b128 v[216:219], v67 offset:55360
	ds_read_b128 v[220:223], v66 offset:18528
	ds_read_b128 v[224:227], v67 offset:55392
	v_mfma_f32_32x32x16_bf16 v[50:65], v[236:239], v[232:235], v[50:65]
	ds_read_b128 v[228:231], v67 offset:59968
	ds_read_b128 v[232:235], v67 offset:60000
	s_waitcnt lgkmcnt(4)
	v_mfma_f32_32x32x16_bf16 v[2:17], v[212:215], v[216:219], v[2:17]
	s_waitcnt lgkmcnt(1)
	v_mfma_f32_32x32x16_bf16 v[18:33], v[212:215], v[228:231], v[18:33]
	ds_read_b128 v[212:215], v66 offset:23104
	ds_read_b128 v[236:239], v66 offset:23136
	s_waitcnt vmcnt(13)
	ds_write_b128 v1, v[188:191]
	ds_write_b128 v1, v[180:183] offset:4608
	ds_write_b128 v1, v[184:187] offset:9216
	s_waitcnt vmcnt(11)
	ds_write_b128 v1, v[196:199] offset:13824
	ds_write_b128 v1, v[192:195] offset:36864
	s_waitcnt vmcnt(10)
	ds_write_b128 v1, v[200:203] offset:41472
	s_waitcnt vmcnt(9)
	ds_write_b128 v1, v[204:207] offset:46080
	s_waitcnt vmcnt(8)
	ds_write_b128 v1, v[208:211] offset:50688
	global_load_dwordx4 v[180:183], v[80:81], off offset:1792
	global_load_dwordx4 v[184:187], v[82:83], off offset:1792
	global_load_dwordx4 v[188:191], v[78:79], off offset:1792
	global_load_dwordx4 v[192:195], v[76:77], off offset:1792
	global_load_dwordx4 v[196:199], v[90:91], off offset:1792
	global_load_dwordx4 v[200:203], v[84:85], off offset:1792
	global_load_dwordx4 v[204:207], v[86:87], off offset:1792
	global_load_dwordx4 v[208:211], v[88:89], off offset:1792
	s_waitcnt lgkmcnt(0)
	s_barrier
	v_mfma_f32_32x32x16_bf16 v[34:49], v[212:215], v[216:219], v[34:49]
	v_mfma_f32_32x32x16_bf16 v[50:65], v[212:215], v[228:231], v[50:65]
	v_mfma_f32_32x32x16_bf16 v[2:17], v[220:223], v[224:227], v[2:17]
	v_mfma_f32_32x32x16_bf16 v[18:33], v[220:223], v[232:235], v[18:33]
	v_mfma_f32_32x32x16_bf16 v[34:49], v[236:239], v[224:227], v[34:49]
	v_mfma_f32_32x32x16_bf16 v[50:65], v[236:239], v[232:235], v[50:65]
	ds_read_b128 v[212:215], v66
	ds_read_b128 v[216:219], v67 offset:36864
	ds_read_b128 v[220:223], v66 offset:32
	ds_read_b128 v[224:227], v67 offset:36896
	ds_read_b128 v[228:231], v67 offset:41472
	ds_read_b128 v[232:235], v67 offset:41504
	s_waitcnt lgkmcnt(4)
	v_mfma_f32_32x32x16_bf16 v[2:17], v[212:215], v[216:219], v[2:17]
	s_waitcnt lgkmcnt(1)
	v_mfma_f32_32x32x16_bf16 v[18:33], v[212:215], v[228:231], v[18:33]
	ds_read_b128 v[212:215], v66 offset:4608
	ds_read_b128 v[236:239], v66 offset:4640
	s_waitcnt lgkmcnt(1)
	v_mfma_f32_32x32x16_bf16 v[34:49], v[212:215], v[216:219], v[34:49]
	v_mfma_f32_32x32x16_bf16 v[50:65], v[212:215], v[228:231], v[50:65]
	v_mfma_f32_32x32x16_bf16 v[2:17], v[220:223], v[224:227], v[2:17]
	v_mfma_f32_32x32x16_bf16 v[18:33], v[220:223], v[232:235], v[18:33]
	s_waitcnt lgkmcnt(0)
	v_mfma_f32_32x32x16_bf16 v[34:49], v[236:239], v[224:227], v[34:49]
	ds_read_b128 v[212:215], v66 offset:64
	ds_read_b128 v[216:219], v67 offset:36928
	ds_read_b128 v[220:223], v66 offset:96
	ds_read_b128 v[224:227], v67 offset:36960
	v_mfma_f32_32x32x16_bf16 v[50:65], v[236:239], v[232:235], v[50:65]
	ds_read_b128 v[228:231], v67 offset:41536
	ds_read_b128 v[232:235], v67 offset:41568
	s_waitcnt lgkmcnt(4)
	v_mfma_f32_32x32x16_bf16 v[2:17], v[212:215], v[216:219], v[2:17]
	s_waitcnt lgkmcnt(1)
	v_mfma_f32_32x32x16_bf16 v[18:33], v[212:215], v[228:231], v[18:33]
	ds_read_b128 v[212:215], v66 offset:4672
	ds_read_b128 v[236:239], v66 offset:4704
	s_waitcnt vmcnt(13)
	ds_write_b128 v1, v[156:159] offset:18432
	ds_write_b128 v1, v[148:151] offset:23040
	ds_write_b128 v1, v[152:155] offset:27648
	s_waitcnt vmcnt(11)
	ds_write_b128 v1, v[164:167] offset:32256
	ds_write_b128 v1, v[160:163] offset:55296
	s_waitcnt vmcnt(10)
	ds_write_b128 v1, v[168:171] offset:59904
	s_waitcnt vmcnt(9)
	ds_write_b128 v1, v[172:175] offset:64512
	s_waitcnt vmcnt(8)
	ds_write_b128 v92, v[176:179] offset:32256
	s_waitcnt lgkmcnt(0)
	s_barrier
	global_load_dwordx4 v[148:151], v[80:81], off offset:1920
	s_nop 0
	global_load_dwordx4 v[80:83], v[82:83], off offset:1920
	s_nop 0
	global_load_dwordx4 v[152:155], v[78:79], off offset:1920
	s_nop 0
	global_load_dwordx4 v[76:79], v[76:77], off offset:1920
	s_nop 0
	global_load_dwordx4 v[156:159], v[90:91], off offset:1920
	global_load_dwordx4 v[160:163], v[84:85], off offset:1920
	s_nop 0
	global_load_dwordx4 v[84:87], v[86:87], off offset:1920
	s_nop 0
	global_load_dwordx4 v[88:91], v[88:89], off offset:1920
	v_mfma_f32_32x32x16_bf16 v[34:49], v[212:215], v[216:219], v[34:49]
	v_mfma_f32_32x32x16_bf16 v[50:65], v[212:215], v[228:231], v[50:65]
	v_mfma_f32_32x32x16_bf16 v[2:17], v[220:223], v[224:227], v[2:17]
	v_mfma_f32_32x32x16_bf16 v[18:33], v[220:223], v[232:235], v[18:33]
	v_mfma_f32_32x32x16_bf16 v[34:49], v[236:239], v[224:227], v[34:49]
	v_mfma_f32_32x32x16_bf16 v[50:65], v[236:239], v[232:235], v[50:65]
	ds_read_b128 v[164:167], v66 offset:18432
	ds_read_b128 v[168:171], v67 offset:55296
	ds_read_b128 v[172:175], v66 offset:18464
	ds_read_b128 v[176:179], v67 offset:55328
	ds_read_b128 v[212:215], v67 offset:59904
	ds_read_b128 v[216:219], v67 offset:59936
	s_waitcnt lgkmcnt(4)
	v_mfma_f32_32x32x16_bf16 v[2:17], v[164:167], v[168:171], v[2:17]
	s_waitcnt lgkmcnt(1)
	v_mfma_f32_32x32x16_bf16 v[18:33], v[164:167], v[212:215], v[18:33]
	ds_read_b128 v[164:167], v66 offset:23040
	ds_read_b128 v[220:223], v66 offset:23072
	s_waitcnt lgkmcnt(1)
	v_mfma_f32_32x32x16_bf16 v[34:49], v[164:167], v[168:171], v[34:49]
	v_mfma_f32_32x32x16_bf16 v[50:65], v[164:167], v[212:215], v[50:65]
	v_mfma_f32_32x32x16_bf16 v[2:17], v[172:175], v[176:179], v[2:17]
	v_mfma_f32_32x32x16_bf16 v[18:33], v[172:175], v[216:219], v[18:33]
	s_waitcnt lgkmcnt(0)
	v_mfma_f32_32x32x16_bf16 v[34:49], v[220:223], v[176:179], v[34:49]
	ds_read_b128 v[164:167], v66 offset:18496
	ds_read_b128 v[168:171], v67 offset:55360
	ds_read_b128 v[172:175], v66 offset:18528
	ds_read_b128 v[176:179], v67 offset:55392
	v_mfma_f32_32x32x16_bf16 v[50:65], v[220:223], v[216:219], v[50:65]
	ds_read_b128 v[212:215], v67 offset:59968
	ds_read_b128 v[216:219], v67 offset:60000
	s_waitcnt lgkmcnt(4)
	v_mfma_f32_32x32x16_bf16 v[2:17], v[164:167], v[168:171], v[2:17]
	s_waitcnt lgkmcnt(1)
	v_mfma_f32_32x32x16_bf16 v[18:33], v[164:167], v[212:215], v[18:33]
	ds_read_b128 v[164:167], v66 offset:23104
	ds_read_b128 v[220:223], v66 offset:23136
	s_waitcnt vmcnt(13)
	ds_write_b128 v1, v[188:191]
	ds_write_b128 v1, v[180:183] offset:4608
	ds_write_b128 v1, v[184:187] offset:9216
	s_waitcnt vmcnt(11)
	ds_write_b128 v1, v[196:199] offset:13824
	ds_write_b128 v1, v[192:195] offset:36864
	s_waitcnt vmcnt(10)
	ds_write_b128 v1, v[200:203] offset:41472
	s_waitcnt vmcnt(9)
	ds_write_b128 v1, v[204:207] offset:46080
	s_waitcnt vmcnt(8)
	ds_write_b128 v1, v[208:211] offset:50688
	s_waitcnt lgkmcnt(0)
	s_barrier
	v_mfma_f32_32x32x16_bf16 v[34:49], v[164:167], v[168:171], v[34:49]
	v_mfma_f32_32x32x16_bf16 v[50:65], v[164:167], v[212:215], v[50:65]
	v_mfma_f32_32x32x16_bf16 v[2:17], v[172:175], v[176:179], v[2:17]
	v_mfma_f32_32x32x16_bf16 v[18:33], v[172:175], v[216:219], v[18:33]
	v_mfma_f32_32x32x16_bf16 v[34:49], v[220:223], v[176:179], v[34:49]
	v_mfma_f32_32x32x16_bf16 v[50:65], v[220:223], v[216:219], v[50:65]
	ds_read_b128 v[164:167], v66
	ds_read_b128 v[168:171], v67 offset:36864
	ds_read_b128 v[172:175], v66 offset:32
	ds_read_b128 v[176:179], v67 offset:36896
	ds_read_b128 v[180:183], v67 offset:41472
	ds_read_b128 v[184:187], v67 offset:41504
	s_waitcnt lgkmcnt(4)
	v_mfma_f32_32x32x16_bf16 v[2:17], v[164:167], v[168:171], v[2:17]
	s_waitcnt lgkmcnt(1)
	v_mfma_f32_32x32x16_bf16 v[18:33], v[164:167], v[180:183], v[18:33]
	ds_read_b128 v[164:167], v66 offset:4608
	ds_read_b128 v[188:191], v66 offset:4640
	s_waitcnt lgkmcnt(1)
	v_mfma_f32_32x32x16_bf16 v[34:49], v[164:167], v[168:171], v[34:49]
	v_mfma_f32_32x32x16_bf16 v[50:65], v[164:167], v[180:183], v[50:65]
	v_mfma_f32_32x32x16_bf16 v[2:17], v[172:175], v[176:179], v[2:17]
	v_mfma_f32_32x32x16_bf16 v[18:33], v[172:175], v[184:187], v[18:33]
	s_waitcnt lgkmcnt(0)
	v_mfma_f32_32x32x16_bf16 v[34:49], v[188:191], v[176:179], v[34:49]
	ds_read_b128 v[164:167], v66 offset:64
	ds_read_b128 v[168:171], v67 offset:36928
	ds_read_b128 v[172:175], v66 offset:96
	ds_read_b128 v[176:179], v67 offset:36960
	v_mfma_f32_32x32x16_bf16 v[50:65], v[188:191], v[184:187], v[50:65]
	ds_read_b128 v[180:183], v67 offset:41536
	ds_read_b128 v[184:187], v67 offset:41568
	s_waitcnt lgkmcnt(4)
	v_mfma_f32_32x32x16_bf16 v[2:17], v[164:167], v[168:171], v[2:17]
	s_waitcnt lgkmcnt(1)
	v_mfma_f32_32x32x16_bf16 v[18:33], v[164:167], v[180:183], v[18:33]
	ds_read_b128 v[164:167], v66 offset:4672
	ds_read_b128 v[188:191], v66 offset:4704
	s_waitcnt vmcnt(5)
	ds_write_b128 v1, v[152:155] offset:18432
	ds_write_b128 v1, v[148:151] offset:23040
	ds_write_b128 v1, v[80:83] offset:27648
	s_waitcnt vmcnt(3)
	ds_write_b128 v1, v[156:159] offset:32256
	ds_write_b128 v1, v[76:79] offset:55296
	s_waitcnt vmcnt(2)
	ds_write_b128 v1, v[160:163] offset:59904
	s_waitcnt vmcnt(1)
	ds_write_b128 v1, v[84:87] offset:64512
	s_waitcnt vmcnt(0)
	ds_write_b128 v92, v[88:91] offset:32256
	s_waitcnt lgkmcnt(0)
	s_barrier
	v_mfma_f32_32x32x16_bf16 v[34:49], v[164:167], v[168:171], v[34:49]
	v_mfma_f32_32x32x16_bf16 v[50:65], v[164:167], v[180:183], v[50:65]
	v_mfma_f32_32x32x16_bf16 v[2:17], v[172:175], v[176:179], v[2:17]
	v_mfma_f32_32x32x16_bf16 v[18:33], v[172:175], v[184:187], v[18:33]
	v_mfma_f32_32x32x16_bf16 v[34:49], v[188:191], v[176:179], v[34:49]
	v_mfma_f32_32x32x16_bf16 v[50:65], v[188:191], v[184:187], v[50:65]
	ds_read_b128 v[76:79], v66 offset:18432
	ds_read_b128 v[80:83], v67 offset:55296
	ds_read_b128 v[84:87], v66 offset:18464
	ds_read_b128 v[88:91], v67 offset:55328
	ds_read_b128 v[148:151], v67 offset:59904
	ds_read_b128 v[152:155], v67 offset:59936
	v_or_b32_e32 v68, s8, v94
	s_waitcnt lgkmcnt(4)
	v_mfma_f32_32x32x16_bf16 v[2:17], v[76:79], v[80:83], v[2:17]
	s_lshl_b32 s10, s10, 1
	s_mov_b32 s11, s9
	s_add_i32 s12, s12, s13
	s_add_i32 s14, s14, s15
	s_add_i32 s16, s16, s17
	s_cmpk_lt_u32 s12, 0x400
	s_waitcnt lgkmcnt(1)
	v_mfma_f32_32x32x16_bf16 v[18:33], v[76:79], v[148:151], v[18:33]
	ds_read_b128 v[76:79], v66 offset:23040
	ds_read_b128 v[156:159], v66 offset:23072
	s_waitcnt lgkmcnt(1)
	v_mfma_f32_32x32x16_bf16 v[34:49], v[76:79], v[80:83], v[34:49]
	v_mfma_f32_32x32x16_bf16 v[50:65], v[76:79], v[148:151], v[50:65]
	v_mfma_f32_32x32x16_bf16 v[2:17], v[84:87], v[88:91], v[2:17]
	v_mfma_f32_32x32x16_bf16 v[18:33], v[84:87], v[152:155], v[18:33]
	s_waitcnt lgkmcnt(0)
	v_mfma_f32_32x32x16_bf16 v[34:49], v[156:159], v[88:91], v[34:49]
	ds_read_b128 v[76:79], v66 offset:18496
	ds_read_b128 v[80:83], v67 offset:55360
	ds_read_b128 v[84:87], v66 offset:18528
	ds_read_b128 v[88:91], v67 offset:55392
	v_mfma_f32_32x32x16_bf16 v[50:65], v[156:159], v[152:155], v[50:65]
	ds_read_b128 v[148:151], v67 offset:59968
	ds_read_b128 v[152:155], v67 offset:60000
	s_waitcnt lgkmcnt(4)
	v_mfma_f32_32x32x16_bf16 v[2:17], v[76:79], v[80:83], v[2:17]
	s_waitcnt lgkmcnt(1)
	v_mfma_f32_32x32x16_bf16 v[18:33], v[76:79], v[148:151], v[18:33]
	ds_read_b128 v[76:79], v66 offset:23104
	ds_read_b128 v[156:159], v66 offset:23136
	s_waitcnt lgkmcnt(0)
	s_barrier
	v_mfma_f32_32x32x16_bf16 v[34:49], v[76:79], v[80:83], v[34:49]
	v_mfma_f32_32x32x16_bf16 v[50:65], v[76:79], v[148:151], v[50:65]
	v_mfma_f32_32x32x16_bf16 v[2:17], v[84:87], v[88:91], v[2:17]
	v_mfma_f32_32x32x16_bf16 v[18:33], v[84:87], v[152:155], v[18:33]
	v_mfma_f32_32x32x16_bf16 v[34:49], v[156:159], v[88:91], v[34:49]
	s_nop 10
	ds_write2_b32 v93, v2, v18 offset1:32
	v_mfma_f32_32x32x16_bf16 v[50:65], v[156:159], v[152:155], v[50:65]
	s_nop 11
	ds_write2_b32 v132, v34, v50 offset0:32 offset1:64
	ds_write2_b32 v93, v3, v19 offset0:129 offset1:161
	ds_write2_b32 v132, v35, v51 offset0:161 offset1:193
	ds_write2_b32 v133, v4, v20 offset0:2 offset1:34
	ds_write2_b32 v134, v36, v52 offset0:34 offset1:66
	ds_write2_b32 v133, v5, v21 offset0:131 offset1:163
	ds_write2_b32 v134, v37, v53 offset0:163 offset1:195
	ds_write2_b32 v135, v6, v22 offset0:8 offset1:40
	ds_write2_b32 v136, v38, v54 offset0:40 offset1:72
	ds_write2_b32 v135, v7, v23 offset0:137 offset1:169
	ds_write2_b32 v136, v39, v55 offset0:169 offset1:201
	ds_write2_b32 v137, v8, v24 offset0:10 offset1:42
	ds_write2_b32 v138, v40, v56 offset0:42 offset1:74
	ds_write2_b32 v137, v9, v25 offset0:139 offset1:171
	ds_write2_b32 v138, v41, v57 offset0:171 offset1:203
	ds_write2_b32 v139, v10, v26 offset0:16 offset1:48
	ds_write2_b32 v140, v42, v58 offset0:48 offset1:80
	ds_write2_b32 v139, v11, v27 offset0:145 offset1:177
	ds_write2_b32 v140, v43, v59 offset0:177 offset1:209
	ds_write2_b32 v141, v12, v28 offset0:18 offset1:50
	ds_write2_b32 v142, v44, v60 offset0:50 offset1:82
	ds_write2_b32 v141, v13, v29 offset0:147 offset1:179
	ds_write2_b32 v142, v45, v61 offset0:179 offset1:211
	ds_write2_b32 v143, v14, v30 offset0:24 offset1:56
	ds_write2_b32 v144, v46, v62 offset0:56 offset1:88
	ds_write2_b32 v143, v15, v31 offset0:153 offset1:185
	ds_write2_b32 v144, v47, v63 offset0:185 offset1:217
	ds_write2_b32 v145, v16, v32 offset0:26 offset1:58
	ds_write2_b32 v146, v48, v64 offset0:58 offset1:90
	ds_write2_b32 v145, v17, v33 offset0:155 offset1:187
	ds_write2_b32 v146, v49, v65 offset0:187 offset1:219
	v_lshl_add_u64 v[2:3], v[68:69], 2, s[6:7]
	s_waitcnt lgkmcnt(0)
	s_barrier
	v_mov_b32_e32 v34, v68
	v_lshlrev_b32_e32 v35, 2, v34
	global_load_dword v37, v35, s[6:7]
	global_load_dword v38, v35, s[6:7] offset:64
	global_load_dword v39, v35, s[6:7] offset:128
	global_load_dword v40, v35, s[6:7] offset:192
	global_load_dword v41, v35, s[6:7] offset:256
	global_load_dword v42, v35, s[6:7] offset:320
	global_load_dword v43, v35, s[6:7] offset:384
	global_load_dword v44, v35, s[6:7] offset:448
	v_lshlrev_b32_e32 v36, 13, v34
	v_add3_u32 v36, v36, v74, s10
	s_movk_i32 s22, 0x7fff
	v_mov_b32_e32 v205, 1
	v_mov_b32_e32 v45, 0x358637bd
	s_cmpk_lt_u32 s12, 0x400
	s_cbranch_scc0 .Lxt9_last
	s_lshr_b32 s8, s12, 2
	s_and_b32 s10, s16, 56
	s_and_b32 s8, s8, 0x1ffffc0
	s_or_b32 s10, s10, s3
	s_or_b32 s8, s10, s8
	s_lshl_b32 s8, s8, 7
	s_lshl_b64 s[24:25], s[8:9], 11
	v_lshl_add_u64 v[78:79], v[70:71], 0, s[24:25]
	v_add_co_u32_e32 v80, vcc, s18, v78
	s_and_b32 s10, s14, 0xf80
	s_nop 0
	v_addc_co_u32_e32 v81, vcc, 0, v79, vcc
	s_lshl_b32 s26, s10, 11
	s_mov_b32 s27, s9
	v_add_co_u32_e32 v82, vcc, s19, v78
	v_lshl_add_u64 v[76:77], v[72:73], 0, s[26:27]
	s_nop 0
	v_addc_co_u32_e32 v83, vcc, 0, v79, vcc
	v_add_co_u32_e32 v84, vcc, s18, v76
	global_load_dwordx4 v[2:5], v[78:79], off
	global_load_dwordx4 v[6:9], v[80:81], off
	v_addc_co_u32_e32 v85, vcc, 0, v77, vcc
	v_add_co_u32_e32 v86, vcc, s19, v76
	global_load_dwordx4 v[10:13], v[82:83], off
	global_load_dwordx4 v[14:17], v[76:77], off
	v_addc_co_u32_e32 v87, vcc, 0, v77, vcc
	global_load_dwordx4 v[18:21], v[84:85], off
	global_load_dwordx4 v[22:25], v[86:87], off
	v_add_co_u32_e32 v88, vcc, s20, v76
	s_nop 1
	v_addc_co_u32_e32 v89, vcc, 0, v77, vcc
	global_load_dwordx4 v[26:29], v[88:89], off
	v_add_co_u32_e32 v90, vcc, s20, v78
	s_nop 1
	v_addc_co_u32_e32 v91, vcc, 0, v79, vcc
	global_load_dwordx4 v[30:33], v[90:91], off
	global_load_dwordx4 v[148:151], v[76:77], off offset:128
	global_load_dwordx4 v[152:155], v[84:85], off offset:128
	global_load_dwordx4 v[156:159], v[86:87], off offset:128
	global_load_dwordx4 v[160:163], v[88:89], off offset:128
	global_load_dwordx4 v[164:167], v[78:79], off offset:128
	global_load_dwordx4 v[168:171], v[80:81], off offset:128
	global_load_dwordx4 v[172:175], v[82:83], off offset:128
	global_load_dwordx4 v[176:179], v[90:91], off offset:128
	s_branch .Lxt9_go
.Lxt9_last:
	global_load_dwordx4 v[2:5], v[70:71], off
	global_load_dwordx4 v[6:9], v[70:71], off
	global_load_dwordx4 v[10:13], v[70:71], off
	global_load_dwordx4 v[14:17], v[70:71], off
	global_load_dwordx4 v[18:21], v[70:71], off
	global_load_dwordx4 v[22:25], v[70:71], off
	global_load_dwordx4 v[26:29], v[70:71], off
	global_load_dwordx4 v[30:33], v[70:71], off
	global_load_dwordx4 v[148:151], v[70:71], off
	global_load_dwordx4 v[152:155], v[70:71], off
	global_load_dwordx4 v[156:159], v[70:71], off
	global_load_dwordx4 v[160:163], v[70:71], off
	global_load_dwordx4 v[164:167], v[70:71], off
	global_load_dwordx4 v[168:171], v[70:71], off
	global_load_dwordx4 v[172:175], v[70:71], off
	global_load_dwordx4 v[176:179], v[70:71], off
.Lxt9_go:
	ds_read2_b32 v[46:47], v103 offset0:0 offset1:1
	ds_read2_b32 v[48:49], v103 offset0:2 offset1:3
	ds_read2_b32 v[50:51], v103 offset0:4 offset1:5
	ds_read2_b32 v[52:53], v103 offset0:6 offset1:7
	v_add_u32_e32 v64, 0x2040, v103
	ds_read2_b32 v[54:55], v64 offset0:0 offset1:1
	ds_read2_b32 v[56:57], v64 offset0:2 offset1:3
	ds_read2_b32 v[58:59], v64 offset0:4 offset1:5
	ds_read2_b32 v[60:61], v64 offset0:6 offset1:7
	s_waitcnt vmcnt(23) lgkmcnt(4)
	v_fmamk_f32 v62, v37, 0x3a800000, v45
	v_rsq_f32_e32 v62, v62
	s_nop 0
	v_mul_f32_e32 v46, v46, v62
	v_mul_f32_e32 v47, v47, v62
	v_mul_f32_e32 v48, v48, v62
	v_mul_f32_e32 v49, v49, v62
	v_mul_f32_e32 v50, v50, v62
	v_mul_f32_e32 v51, v51, v62
	v_mul_f32_e32 v52, v52, v62
	v_mul_f32_e32 v53, v53, v62
	v_max_f32_e32 v46, 0, v46
	v_max_f32_e32 v47, 0, v47
	v_max_f32_e32 v48, 0, v48
	v_max_f32_e32 v49, 0, v49
	v_max_f32_e32 v50, 0, v50
	v_max_f32_e32 v51, 0, v51
	v_max_f32_e32 v52, 0, v52
	v_max_f32_e32 v53, 0, v53
	v_pk_mul_f32 v[46:47], v[46:47], v[46:47]
	v_pk_mul_f32 v[48:49], v[48:49], v[48:49]
	v_pk_mul_f32 v[50:51], v[50:51], v[50:51]
	v_pk_mul_f32 v[52:53], v[52:53], v[52:53]
	v_and_b32_sdwa v196, v46, v205 dst_sel:DWORD dst_unused:UNUSED_PAD src0_sel:WORD_1 src1_sel:DWORD
	v_and_b32_sdwa v197, v47, v205 dst_sel:DWORD dst_unused:UNUSED_PAD src0_sel:WORD_1 src1_sel:DWORD
	v_and_b32_sdwa v198, v48, v205 dst_sel:DWORD dst_unused:UNUSED_PAD src0_sel:WORD_1 src1_sel:DWORD
	v_and_b32_sdwa v199, v49, v205 dst_sel:DWORD dst_unused:UNUSED_PAD src0_sel:WORD_1 src1_sel:DWORD
	v_and_b32_sdwa v200, v50, v205 dst_sel:DWORD dst_unused:UNUSED_PAD src0_sel:WORD_1 src1_sel:DWORD
	v_and_b32_sdwa v201, v51, v205 dst_sel:DWORD dst_unused:UNUSED_PAD src0_sel:WORD_1 src1_sel:DWORD
	v_and_b32_sdwa v202, v52, v205 dst_sel:DWORD dst_unused:UNUSED_PAD src0_sel:WORD_1 src1_sel:DWORD
	v_and_b32_sdwa v203, v53, v205 dst_sel:DWORD dst_unused:UNUSED_PAD src0_sel:WORD_1 src1_sel:DWORD
	v_add3_u32 v46, v46, v196, s22
	v_add3_u32 v47, v47, v197, s22
	v_add3_u32 v48, v48, v198, s22
	v_add3_u32 v49, v49, v199, s22
	v_add3_u32 v50, v50, v200, s22
	v_add3_u32 v51, v51, v201, s22
	v_add3_u32 v52, v52, v202, s22
	v_add3_u32 v53, v53, v203, s22
	v_and_b32_e32 v47, 0xffff0000, v47
	v_and_b32_e32 v49, 0xffff0000, v49
	v_and_b32_e32 v51, 0xffff0000, v51
	v_and_b32_e32 v53, 0xffff0000, v53
	v_or_b32_sdwa v208, v47, v46 dst_sel:DWORD dst_unused:UNUSED_PAD src0_sel:DWORD src1_sel:WORD_1
	v_or_b32_sdwa v209, v49, v48 dst_sel:DWORD dst_unused:UNUSED_PAD src0_sel:DWORD src1_sel:WORD_1
	v_or_b32_sdwa v210, v51, v50 dst_sel:DWORD dst_unused:UNUSED_PAD src0_sel:DWORD src1_sel:WORD_1
	v_or_b32_sdwa v211, v53, v52 dst_sel:DWORD dst_unused:UNUSED_PAD src0_sel:DWORD src1_sel:WORD_1
	global_store_dwordx4 v36, v[208:211], s[56:57]
	v_add_u32_e32 v63, 0x4080, v103
	ds_read2_b32 v[180:181], v63 offset0:0 offset1:1
	ds_read2_b32 v[182:183], v63 offset0:2 offset1:3
	ds_read2_b32 v[184:185], v63 offset0:4 offset1:5
	ds_read2_b32 v[186:187], v63 offset0:6 offset1:7
	v_add_u32_e32 v64, 0x60c0, v103
	ds_read2_b32 v[188:189], v64 offset0:0 offset1:1
	ds_read2_b32 v[190:191], v64 offset0:2 offset1:3
	ds_read2_b32 v[192:193], v64 offset0:4 offset1:5
	ds_read2_b32 v[194:195], v64 offset0:6 offset1:7
	s_waitcnt vmcnt(23) lgkmcnt(8)
	v_fmamk_f32 v62, v38, 0x3a800000, v45
	v_rsq_f32_e32 v62, v62
	v_add_u32_e32 v204, 0x20000, v36
	v_mul_f32_e32 v54, v54, v62
	v_mul_f32_e32 v55, v55, v62
	v_mul_f32_e32 v56, v56, v62
	v_mul_f32_e32 v57, v57, v62
	v_mul_f32_e32 v58, v58, v62
	v_mul_f32_e32 v59, v59, v62
	v_mul_f32_e32 v60, v60, v62
	v_mul_f32_e32 v61, v61, v62
	v_max_f32_e32 v54, 0, v54
	v_max_f32_e32 v55, 0, v55
	v_max_f32_e32 v56, 0, v56
	v_max_f32_e32 v57, 0, v57
	v_max_f32_e32 v58, 0, v58
	v_max_f32_e32 v59, 0, v59
	v_max_f32_e32 v60, 0, v60
	v_max_f32_e32 v61, 0, v61
	v_pk_mul_f32 v[54:55], v[54:55], v[54:55]
	v_pk_mul_f32 v[56:57], v[56:57], v[56:57]
	v_pk_mul_f32 v[58:59], v[58:59], v[58:59]
	v_pk_mul_f32 v[60:61], v[60:61], v[60:61]
	v_and_b32_sdwa v196, v54, v205 dst_sel:DWORD dst_unused:UNUSED_PAD src0_sel:WORD_1 src1_sel:DWORD
	v_and_b32_sdwa v197, v55, v205 dst_sel:DWORD dst_unused:UNUSED_PAD src0_sel:WORD_1 src1_sel:DWORD
	v_and_b32_sdwa v198, v56, v205 dst_sel:DWORD dst_unused:UNUSED_PAD src0_sel:WORD_1 src1_sel:DWORD
	v_and_b32_sdwa v199, v57, v205 dst_sel:DWORD dst_unused:UNUSED_PAD src0_sel:WORD_1 src1_sel:DWORD
	v_and_b32_sdwa v200, v58, v205 dst_sel:DWORD dst_unused:UNUSED_PAD src0_sel:WORD_1 src1_sel:DWORD
	v_and_b32_sdwa v201, v59, v205 dst_sel:DWORD dst_unused:UNUSED_PAD src0_sel:WORD_1 src1_sel:DWORD
	v_and_b32_sdwa v202, v60, v205 dst_sel:DWORD dst_unused:UNUSED_PAD src0_sel:WORD_1 src1_sel:DWORD
	v_and_b32_sdwa v203, v61, v205 dst_sel:DWORD dst_unused:UNUSED_PAD src0_sel:WORD_1 src1_sel:DWORD
	v_add3_u32 v54, v54, v196, s22
	v_add3_u32 v55, v55, v197, s22
	v_add3_u32 v56, v56, v198, s22
	v_add3_u32 v57, v57, v199, s22
	v_add3_u32 v58, v58, v200, s22
	v_add3_u32 v59, v59, v201, s22
	v_add3_u32 v60, v60, v202, s22
	v_add3_u32 v61, v61, v203, s22
	v_and_b32_e32 v55, 0xffff0000, v55
	v_and_b32_e32 v57, 0xffff0000, v57
	v_and_b32_e32 v59, 0xffff0000, v59
	v_and_b32_e32 v61, 0xffff0000, v61
	v_or_b32_sdwa v212, v55, v54 dst_sel:DWORD dst_unused:UNUSED_PAD src0_sel:DWORD src1_sel:WORD_1
	v_or_b32_sdwa v213, v57, v56 dst_sel:DWORD dst_unused:UNUSED_PAD src0_sel:DWORD src1_sel:WORD_1
	v_or_b32_sdwa v214, v59, v58 dst_sel:DWORD dst_unused:UNUSED_PAD src0_sel:DWORD src1_sel:WORD_1
	v_or_b32_sdwa v215, v61, v60 dst_sel:DWORD dst_unused:UNUSED_PAD src0_sel:DWORD src1_sel:WORD_1
	global_store_dwordx4 v204, v[212:215], s[56:57]
	s_waitcnt vmcnt(23) lgkmcnt(4)
	v_fmamk_f32 v62, v39, 0x3a800000, v45
	v_rsq_f32_e32 v62, v62
	v_add_u32_e32 v65, 0x40000, v36
	v_mul_f32_e32 v180, v180, v62
	v_mul_f32_e32 v181, v181, v62
	v_mul_f32_e32 v182, v182, v62
	v_mul_f32_e32 v183, v183, v62
	v_mul_f32_e32 v184, v184, v62
	v_mul_f32_e32 v185, v185, v62
	v_mul_f32_e32 v186, v186, v62
	v_mul_f32_e32 v187, v187, v62
	v_max_f32_e32 v180, 0, v180
	v_max_f32_e32 v181, 0, v181
	v_max_f32_e32 v182, 0, v182
	v_max_f32_e32 v183, 0, v183
	v_max_f32_e32 v184, 0, v184
	v_max_f32_e32 v185, 0, v185
	v_max_f32_e32 v186, 0, v186
	v_max_f32_e32 v187, 0, v187
	v_pk_mul_f32 v[180:181], v[180:181], v[180:181]
	v_pk_mul_f32 v[182:183], v[182:183], v[182:183]
	v_pk_mul_f32 v[184:185], v[184:185], v[184:185]
	v_pk_mul_f32 v[186:187], v[186:187], v[186:187]
	v_and_b32_sdwa v196, v180, v205 dst_sel:DWORD dst_unused:UNUSED_PAD src0_sel:WORD_1 src1_sel:DWORD
	v_and_b32_sdwa v197, v181, v205 dst_sel:DWORD dst_unused:UNUSED_PAD src0_sel:WORD_1 src1_sel:DWORD
	v_and_b32_sdwa v198, v182, v205 dst_sel:DWORD dst_unused:UNUSED_PAD src0_sel:WORD_1 src1_sel:DWORD
	v_and_b32_sdwa v199, v183, v205 dst_sel:DWORD dst_unused:UNUSED_PAD src0_sel:WORD_1 src1_sel:DWORD
	v_and_b32_sdwa v200, v184, v205 dst_sel:DWORD dst_unused:UNUSED_PAD src0_sel:WORD_1 src1_sel:DWORD
	v_and_b32_sdwa v201, v185, v205 dst_sel:DWORD dst_unused:UNUSED_PAD src0_sel:WORD_1 src1_sel:DWORD
	v_and_b32_sdwa v202, v186, v205 dst_sel:DWORD dst_unused:UNUSED_PAD src0_sel:WORD_1 src1_sel:DWORD
	v_and_b32_sdwa v203, v187, v205 dst_sel:DWORD dst_unused:UNUSED_PAD src0_sel:WORD_1 src1_sel:DWORD
	v_add3_u32 v180, v180, v196, s22
	v_add3_u32 v181, v181, v197, s22
	v_add3_u32 v182, v182, v198, s22
	v_add3_u32 v183, v183, v199, s22
	v_add3_u32 v184, v184, v200, s22
	v_add3_u32 v185, v185, v201, s22
	v_add3_u32 v186, v186, v202, s22
	v_add3_u32 v187, v187, v203, s22
	v_and_b32_e32 v181, 0xffff0000, v181
	v_and_b32_e32 v183, 0xffff0000, v183
	v_and_b32_e32 v185, 0xffff0000, v185
	v_and_b32_e32 v187, 0xffff0000, v187
	v_or_b32_sdwa v208, v181, v180 dst_sel:DWORD dst_unused:UNUSED_PAD src0_sel:DWORD src1_sel:WORD_1
	v_or_b32_sdwa v209, v183, v182 dst_sel:DWORD dst_unused:UNUSED_PAD src0_sel:DWORD src1_sel:WORD_1
	v_or_b32_sdwa v210, v185, v184 dst_sel:DWORD dst_unused:UNUSED_PAD src0_sel:DWORD src1_sel:WORD_1
	v_or_b32_sdwa v211, v187, v186 dst_sel:DWORD dst_unused:UNUSED_PAD src0_sel:DWORD src1_sel:WORD_1
	global_store_dwordx4 v65, v[208:211], s[56:57]
	v_add_u32_e32 v63, 0x8100, v103
	ds_read2_b32 v[46:47], v63 offset0:0 offset1:1
	ds_read2_b32 v[48:49], v63 offset0:2 offset1:3
	ds_read2_b32 v[50:51], v63 offset0:4 offset1:5
	ds_read2_b32 v[52:53], v63 offset0:6 offset1:7
	v_add_u32_e32 v64, 0xa140, v103
	ds_read2_b32 v[54:55], v64 offset0:0 offset1:1
	ds_read2_b32 v[56:57], v64 offset0:2 offset1:3
	ds_read2_b32 v[58:59], v64 offset0:4 offset1:5
	ds_read2_b32 v[60:61], v64 offset0:6 offset1:7
	s_waitcnt vmcnt(23) lgkmcnt(8)
	v_fmamk_f32 v62, v40, 0x3a800000, v45
	v_rsq_f32_e32 v62, v62
	v_add_u32_e32 v204, 0x60000, v36
	v_mul_f32_e32 v188, v188, v62
	v_mul_f32_e32 v189, v189, v62
	v_mul_f32_e32 v190, v190, v62
	v_mul_f32_e32 v191, v191, v62
	v_mul_f32_e32 v192, v192, v62
	v_mul_f32_e32 v193, v193, v62
	v_mul_f32_e32 v194, v194, v62
	v_mul_f32_e32 v195, v195, v62
	v_max_f32_e32 v188, 0, v188
	v_max_f32_e32 v189, 0, v189
	v_max_f32_e32 v190, 0, v190
	v_max_f32_e32 v191, 0, v191
	v_max_f32_e32 v192, 0, v192
	v_max_f32_e32 v193, 0, v193
	v_max_f32_e32 v194, 0, v194
	v_max_f32_e32 v195, 0, v195
	v_pk_mul_f32 v[188:189], v[188:189], v[188:189]
	v_pk_mul_f32 v[190:191], v[190:191], v[190:191]
	v_pk_mul_f32 v[192:193], v[192:193], v[192:193]
	v_pk_mul_f32 v[194:195], v[194:195], v[194:195]
	v_and_b32_sdwa v196, v188, v205 dst_sel:DWORD dst_unused:UNUSED_PAD src0_sel:WORD_1 src1_sel:DWORD
	v_and_b32_sdwa v197, v189, v205 dst_sel:DWORD dst_unused:UNUSED_PAD src0_sel:WORD_1 src1_sel:DWORD
	v_and_b32_sdwa v198, v190, v205 dst_sel:DWORD dst_unused:UNUSED_PAD src0_sel:WORD_1 src1_sel:DWORD
	v_and_b32_sdwa v199, v191, v205 dst_sel:DWORD dst_unused:UNUSED_PAD src0_sel:WORD_1 src1_sel:DWORD
	v_and_b32_sdwa v200, v192, v205 dst_sel:DWORD dst_unused:UNUSED_PAD src0_sel:WORD_1 src1_sel:DWORD
	v_and_b32_sdwa v201, v193, v205 dst_sel:DWORD dst_unused:UNUSED_PAD src0_sel:WORD_1 src1_sel:DWORD
	v_and_b32_sdwa v202, v194, v205 dst_sel:DWORD dst_unused:UNUSED_PAD src0_sel:WORD_1 src1_sel:DWORD
	v_and_b32_sdwa v203, v195, v205 dst_sel:DWORD dst_unused:UNUSED_PAD src0_sel:WORD_1 src1_sel:DWORD
	v_add3_u32 v188, v188, v196, s22
	v_add3_u32 v189, v189, v197, s22
	v_add3_u32 v190, v190, v198, s22
	v_add3_u32 v191, v191, v199, s22
	v_add3_u32 v192, v192, v200, s22
	v_add3_u32 v193, v193, v201, s22
	v_add3_u32 v194, v194, v202, s22
	v_add3_u32 v195, v195, v203, s22
	v_and_b32_e32 v189, 0xffff0000, v189
	v_and_b32_e32 v191, 0xffff0000, v191
	v_and_b32_e32 v193, 0xffff0000, v193
	v_and_b32_e32 v195, 0xffff0000, v195
	v_or_b32_sdwa v212, v189, v188 dst_sel:DWORD dst_unused:UNUSED_PAD src0_sel:DWORD src1_sel:WORD_1
	v_or_b32_sdwa v213, v191, v190 dst_sel:DWORD dst_unused:UNUSED_PAD src0_sel:DWORD src1_sel:WORD_1
	v_or_b32_sdwa v214, v193, v192 dst_sel:DWORD dst_unused:UNUSED_PAD src0_sel:DWORD src1_sel:WORD_1
	v_or_b32_sdwa v215, v195, v194 dst_sel:DWORD dst_unused:UNUSED_PAD src0_sel:DWORD src1_sel:WORD_1
	global_store_dwordx4 v204, v[212:215], s[56:57]
	s_waitcnt vmcnt(23) lgkmcnt(4)
	v_fmamk_f32 v62, v41, 0x3a800000, v45
	v_rsq_f32_e32 v62, v62
	v_add_u32_e32 v65, 0x80000, v36
	v_mul_f32_e32 v46, v46, v62
	v_mul_f32_e32 v47, v47, v62
	v_mul_f32_e32 v48, v48, v62
	v_mul_f32_e32 v49, v49, v62
	v_mul_f32_e32 v50, v50, v62
	v_mul_f32_e32 v51, v51, v62
	v_mul_f32_e32 v52, v52, v62
	v_mul_f32_e32 v53, v53, v62
	v_max_f32_e32 v46, 0, v46
	v_max_f32_e32 v47, 0, v47
	v_max_f32_e32 v48, 0, v48
	v_max_f32_e32 v49, 0, v49
	v_max_f32_e32 v50, 0, v50
	v_max_f32_e32 v51, 0, v51
	v_max_f32_e32 v52, 0, v52
	v_max_f32_e32 v53, 0, v53
	v_pk_mul_f32 v[46:47], v[46:47], v[46:47]
	v_pk_mul_f32 v[48:49], v[48:49], v[48:49]
	v_pk_mul_f32 v[50:51], v[50:51], v[50:51]
	v_pk_mul_f32 v[52:53], v[52:53], v[52:53]
	v_and_b32_sdwa v196, v46, v205 dst_sel:DWORD dst_unused:UNUSED_PAD src0_sel:WORD_1 src1_sel:DWORD
	v_and_b32_sdwa v197, v47, v205 dst_sel:DWORD dst_unused:UNUSED_PAD src0_sel:WORD_1 src1_sel:DWORD
	v_and_b32_sdwa v198, v48, v205 dst_sel:DWORD dst_unused:UNUSED_PAD src0_sel:WORD_1 src1_sel:DWORD
	v_and_b32_sdwa v199, v49, v205 dst_sel:DWORD dst_unused:UNUSED_PAD src0_sel:WORD_1 src1_sel:DWORD
	v_and_b32_sdwa v200, v50, v205 dst_sel:DWORD dst_unused:UNUSED_PAD src0_sel:WORD_1 src1_sel:DWORD
	v_and_b32_sdwa v201, v51, v205 dst_sel:DWORD dst_unused:UNUSED_PAD src0_sel:WORD_1 src1_sel:DWORD
	v_and_b32_sdwa v202, v52, v205 dst_sel:DWORD dst_unused:UNUSED_PAD src0_sel:WORD_1 src1_sel:DWORD
	v_and_b32_sdwa v203, v53, v205 dst_sel:DWORD dst_unused:UNUSED_PAD src0_sel:WORD_1 src1_sel:DWORD
	v_add3_u32 v46, v46, v196, s22
	v_add3_u32 v47, v47, v197, s22
	v_add3_u32 v48, v48, v198, s22
	v_add3_u32 v49, v49, v199, s22
	v_add3_u32 v50, v50, v200, s22
	v_add3_u32 v51, v51, v201, s22
	v_add3_u32 v52, v52, v202, s22
	v_add3_u32 v53, v53, v203, s22
	v_and_b32_e32 v47, 0xffff0000, v47
	v_and_b32_e32 v49, 0xffff0000, v49
	v_and_b32_e32 v51, 0xffff0000, v51
	v_and_b32_e32 v53, 0xffff0000, v53
	v_or_b32_sdwa v208, v47, v46 dst_sel:DWORD dst_unused:UNUSED_PAD src0_sel:DWORD src1_sel:WORD_1
	v_or_b32_sdwa v209, v49, v48 dst_sel:DWORD dst_unused:UNUSED_PAD src0_sel:DWORD src1_sel:WORD_1
	v_or_b32_sdwa v210, v51, v50 dst_sel:DWORD dst_unused:UNUSED_PAD src0_sel:DWORD src1_sel:WORD_1
	v_or_b32_sdwa v211, v53, v52 dst_sel:DWORD dst_unused:UNUSED_PAD src0_sel:DWORD src1_sel:WORD_1
	global_store_dwordx4 v65, v[208:211], s[56:57]
	v_add_u32_e32 v63, 0xc180, v103
	ds_read2_b32 v[180:181], v63 offset0:0 offset1:1
	ds_read2_b32 v[182:183], v63 offset0:2 offset1:3
	ds_read2_b32 v[184:185], v63 offset0:4 offset1:5
	ds_read2_b32 v[186:187], v63 offset0:6 offset1:7
	v_add_u32_e32 v64, 0xe1c0, v103
	ds_read2_b32 v[188:189], v64 offset0:0 offset1:1
	ds_read2_b32 v[190:191], v64 offset0:2 offset1:3
	ds_read2_b32 v[192:193], v64 offset0:4 offset1:5
	ds_read2_b32 v[194:195], v64 offset0:6 offset1:7
	s_waitcnt vmcnt(23) lgkmcnt(8)
	v_fmamk_f32 v62, v42, 0x3a800000, v45
	v_rsq_f32_e32 v62, v62
	v_add_u32_e32 v204, 0xa0000, v36
	v_mul_f32_e32 v54, v54, v62
	v_mul_f32_e32 v55, v55, v62
	v_mul_f32_e32 v56, v56, v62
	v_mul_f32_e32 v57, v57, v62
	v_mul_f32_e32 v58, v58, v62
	v_mul_f32_e32 v59, v59, v62
	v_mul_f32_e32 v60, v60, v62
	v_mul_f32_e32 v61, v61, v62
	v_max_f32_e32 v54, 0, v54
	v_max_f32_e32 v55, 0, v55
	v_max_f32_e32 v56, 0, v56
	v_max_f32_e32 v57, 0, v57
	v_max_f32_e32 v58, 0, v58
	v_max_f32_e32 v59, 0, v59
	v_max_f32_e32 v60, 0, v60
	v_max_f32_e32 v61, 0, v61
	v_pk_mul_f32 v[54:55], v[54:55], v[54:55]
	v_pk_mul_f32 v[56:57], v[56:57], v[56:57]
	v_pk_mul_f32 v[58:59], v[58:59], v[58:59]
	v_pk_mul_f32 v[60:61], v[60:61], v[60:61]
	v_and_b32_sdwa v196, v54, v205 dst_sel:DWORD dst_unused:UNUSED_PAD src0_sel:WORD_1 src1_sel:DWORD
	v_and_b32_sdwa v197, v55, v205 dst_sel:DWORD dst_unused:UNUSED_PAD src0_sel:WORD_1 src1_sel:DWORD
	v_and_b32_sdwa v198, v56, v205 dst_sel:DWORD dst_unused:UNUSED_PAD src0_sel:WORD_1 src1_sel:DWORD
	v_and_b32_sdwa v199, v57, v205 dst_sel:DWORD dst_unused:UNUSED_PAD src0_sel:WORD_1 src1_sel:DWORD
	v_and_b32_sdwa v200, v58, v205 dst_sel:DWORD dst_unused:UNUSED_PAD src0_sel:WORD_1 src1_sel:DWORD
	v_and_b32_sdwa v201, v59, v205 dst_sel:DWORD dst_unused:UNUSED_PAD src0_sel:WORD_1 src1_sel:DWORD
	v_and_b32_sdwa v202, v60, v205 dst_sel:DWORD dst_unused:UNUSED_PAD src0_sel:WORD_1 src1_sel:DWORD
	v_and_b32_sdwa v203, v61, v205 dst_sel:DWORD dst_unused:UNUSED_PAD src0_sel:WORD_1 src1_sel:DWORD
	v_add3_u32 v54, v54, v196, s22
	v_add3_u32 v55, v55, v197, s22
	v_add3_u32 v56, v56, v198, s22
	v_add3_u32 v57, v57, v199, s22
	v_add3_u32 v58, v58, v200, s22
	v_add3_u32 v59, v59, v201, s22
	v_add3_u32 v60, v60, v202, s22
	v_add3_u32 v61, v61, v203, s22
	v_and_b32_e32 v55, 0xffff0000, v55
	v_and_b32_e32 v57, 0xffff0000, v57
	v_and_b32_e32 v59, 0xffff0000, v59
	v_and_b32_e32 v61, 0xffff0000, v61
	v_or_b32_sdwa v212, v55, v54 dst_sel:DWORD dst_unused:UNUSED_PAD src0_sel:DWORD src1_sel:WORD_1
	v_or_b32_sdwa v213, v57, v56 dst_sel:DWORD dst_unused:UNUSED_PAD src0_sel:DWORD src1_sel:WORD_1
	v_or_b32_sdwa v214, v59, v58 dst_sel:DWORD dst_unused:UNUSED_PAD src0_sel:DWORD src1_sel:WORD_1
	v_or_b32_sdwa v215, v61, v60 dst_sel:DWORD dst_unused:UNUSED_PAD src0_sel:DWORD src1_sel:WORD_1
	global_store_dwordx4 v204, v[212:215], s[56:57]
	s_waitcnt vmcnt(23) lgkmcnt(4)
	v_fmamk_f32 v62, v43, 0x3a800000, v45
	v_rsq_f32_e32 v62, v62
	v_add_u32_e32 v65, 0xc0000, v36
	v_mul_f32_e32 v180, v180, v62
	v_mul_f32_e32 v181, v181, v62
	v_mul_f32_e32 v182, v182, v62
	v_mul_f32_e32 v183, v183, v62
	v_mul_f32_e32 v184, v184, v62
	v_mul_f32_e32 v185, v185, v62
	v_mul_f32_e32 v186, v186, v62
	v_mul_f32_e32 v187, v187, v62
	v_max_f32_e32 v180, 0, v180
	v_max_f32_e32 v181, 0, v181
	v_max_f32_e32 v182, 0, v182
	v_max_f32_e32 v183, 0, v183
	v_max_f32_e32 v184, 0, v184
	v_max_f32_e32 v185, 0, v185
	v_max_f32_e32 v186, 0, v186
	v_max_f32_e32 v187, 0, v187
	v_pk_mul_f32 v[180:181], v[180:181], v[180:181]
	v_pk_mul_f32 v[182:183], v[182:183], v[182:183]
	v_pk_mul_f32 v[184:185], v[184:185], v[184:185]
	v_pk_mul_f32 v[186:187], v[186:187], v[186:187]
	v_and_b32_sdwa v196, v180, v205 dst_sel:DWORD dst_unused:UNUSED_PAD src0_sel:WORD_1 src1_sel:DWORD
	v_and_b32_sdwa v197, v181, v205 dst_sel:DWORD dst_unused:UNUSED_PAD src0_sel:WORD_1 src1_sel:DWORD
	v_and_b32_sdwa v198, v182, v205 dst_sel:DWORD dst_unused:UNUSED_PAD src0_sel:WORD_1 src1_sel:DWORD
	v_and_b32_sdwa v199, v183, v205 dst_sel:DWORD dst_unused:UNUSED_PAD src0_sel:WORD_1 src1_sel:DWORD
	v_and_b32_sdwa v200, v184, v205 dst_sel:DWORD dst_unused:UNUSED_PAD src0_sel:WORD_1 src1_sel:DWORD
	v_and_b32_sdwa v201, v185, v205 dst_sel:DWORD dst_unused:UNUSED_PAD src0_sel:WORD_1 src1_sel:DWORD
	v_and_b32_sdwa v202, v186, v205 dst_sel:DWORD dst_unused:UNUSED_PAD src0_sel:WORD_1 src1_sel:DWORD
	v_and_b32_sdwa v203, v187, v205 dst_sel:DWORD dst_unused:UNUSED_PAD src0_sel:WORD_1 src1_sel:DWORD
	v_add3_u32 v180, v180, v196, s22
	v_add3_u32 v181, v181, v197, s22
	v_add3_u32 v182, v182, v198, s22
	v_add3_u32 v183, v183, v199, s22
	v_add3_u32 v184, v184, v200, s22
	v_add3_u32 v185, v185, v201, s22
	v_add3_u32 v186, v186, v202, s22
	v_add3_u32 v187, v187, v203, s22
	v_and_b32_e32 v181, 0xffff0000, v181
	v_and_b32_e32 v183, 0xffff0000, v183
	v_and_b32_e32 v185, 0xffff0000, v185
	v_and_b32_e32 v187, 0xffff0000, v187
	v_or_b32_sdwa v208, v181, v180 dst_sel:DWORD dst_unused:UNUSED_PAD src0_sel:DWORD src1_sel:WORD_1
	v_or_b32_sdwa v209, v183, v182 dst_sel:DWORD dst_unused:UNUSED_PAD src0_sel:DWORD src1_sel:WORD_1
	v_or_b32_sdwa v210, v185, v184 dst_sel:DWORD dst_unused:UNUSED_PAD src0_sel:DWORD src1_sel:WORD_1
	v_or_b32_sdwa v211, v187, v186 dst_sel:DWORD dst_unused:UNUSED_PAD src0_sel:DWORD src1_sel:WORD_1
	global_store_dwordx4 v65, v[208:211], s[56:57]
	s_waitcnt vmcnt(23) lgkmcnt(0)
	v_fmamk_f32 v62, v44, 0x3a800000, v45
	v_rsq_f32_e32 v62, v62
	v_add_u32_e32 v204, 0xe0000, v36
	v_mul_f32_e32 v188, v188, v62
	v_mul_f32_e32 v189, v189, v62
	v_mul_f32_e32 v190, v190, v62
	v_mul_f32_e32 v191, v191, v62
	v_mul_f32_e32 v192, v192, v62
	v_mul_f32_e32 v193, v193, v62
	v_mul_f32_e32 v194, v194, v62
	v_mul_f32_e32 v195, v195, v62
	v_max_f32_e32 v188, 0, v188
	v_max_f32_e32 v189, 0, v189
	v_max_f32_e32 v190, 0, v190
	v_max_f32_e32 v191, 0, v191
	v_max_f32_e32 v192, 0, v192
	v_max_f32_e32 v193, 0, v193
	v_max_f32_e32 v194, 0, v194
	v_max_f32_e32 v195, 0, v195
	v_pk_mul_f32 v[188:189], v[188:189], v[188:189]
	v_pk_mul_f32 v[190:191], v[190:191], v[190:191]
	v_pk_mul_f32 v[192:193], v[192:193], v[192:193]
	v_pk_mul_f32 v[194:195], v[194:195], v[194:195]
	v_and_b32_sdwa v196, v188, v205 dst_sel:DWORD dst_unused:UNUSED_PAD src0_sel:WORD_1 src1_sel:DWORD
	v_and_b32_sdwa v197, v189, v205 dst_sel:DWORD dst_unused:UNUSED_PAD src0_sel:WORD_1 src1_sel:DWORD
	v_and_b32_sdwa v198, v190, v205 dst_sel:DWORD dst_unused:UNUSED_PAD src0_sel:WORD_1 src1_sel:DWORD
	v_and_b32_sdwa v199, v191, v205 dst_sel:DWORD dst_unused:UNUSED_PAD src0_sel:WORD_1 src1_sel:DWORD
	v_and_b32_sdwa v200, v192, v205 dst_sel:DWORD dst_unused:UNUSED_PAD src0_sel:WORD_1 src1_sel:DWORD
	v_and_b32_sdwa v201, v193, v205 dst_sel:DWORD dst_unused:UNUSED_PAD src0_sel:WORD_1 src1_sel:DWORD
	v_and_b32_sdwa v202, v194, v205 dst_sel:DWORD dst_unused:UNUSED_PAD src0_sel:WORD_1 src1_sel:DWORD
	v_and_b32_sdwa v203, v195, v205 dst_sel:DWORD dst_unused:UNUSED_PAD src0_sel:WORD_1 src1_sel:DWORD
	v_add3_u32 v188, v188, v196, s22
	v_add3_u32 v189, v189, v197, s22
	v_add3_u32 v190, v190, v198, s22
	v_add3_u32 v191, v191, v199, s22
	v_add3_u32 v192, v192, v200, s22
	v_add3_u32 v193, v193, v201, s22
	v_add3_u32 v194, v194, v202, s22
	v_add3_u32 v195, v195, v203, s22
	v_and_b32_e32 v189, 0xffff0000, v189
	v_and_b32_e32 v191, 0xffff0000, v191
	v_and_b32_e32 v193, 0xffff0000, v193
	v_and_b32_e32 v195, 0xffff0000, v195
	v_or_b32_sdwa v212, v189, v188 dst_sel:DWORD dst_unused:UNUSED_PAD src0_sel:DWORD src1_sel:WORD_1
	v_or_b32_sdwa v213, v191, v190 dst_sel:DWORD dst_unused:UNUSED_PAD src0_sel:DWORD src1_sel:WORD_1
	v_or_b32_sdwa v214, v193, v192 dst_sel:DWORD dst_unused:UNUSED_PAD src0_sel:DWORD src1_sel:WORD_1
	v_or_b32_sdwa v215, v195, v194 dst_sel:DWORD dst_unused:UNUSED_PAD src0_sel:DWORD src1_sel:WORD_1
	global_store_dwordx4 v204, v[212:215], s[56:57]
	s_cmpk_lt_u32 s12, 0x400
	s_barrier
	s_cbranch_scc1 .LBB0_590
	s_waitcnt vmcnt(0)
